# remove s_setprio in 5 GEMM K-loops; hand-scheduled prefetched G2 scan
# speedup vs baseline: 1.0047x; 1.0047x over previous
; #define PG8_STAGE(bufoff, gbase, voff) do { _Pragma("unroll") for (int _i = 0; _i < 2; ++_i) \
;         __builtin_amdgcn_global_load_lds((const unsigned*)((const char*)(gbase) + (voff)[_i]), (PG8_LAS unsigned*)(lds + (bufoff) + ldsw + _i * 8192), 16, 0, 0); } while (0)
; #define PG8_LDA(dst, b, h) do { _Pragma("unroll") for (int m = 0; m < 4; ++m) _Pragma("unroll") for (int k = 0; k < 2; ++k) dst[m][k] = *(const PG8_LAS bf16x8*)(lds + PG8_SA(b, h) + aoff + m * 2048 + k * 1024); } while (0)
; #define PG8_LDB(dst, b, h) do { _Pragma("unroll") for (int n = 0; n < 2; ++n) _Pragma("unroll") for (int k = 0; k < 2; ++k) dst[n][k] = *(const PG8_LAS bf16x8*)(lds + PG8_SB(b, h) + boff + n * 2048 + k * 1024); } while (0)
; #define PG8_MMA(ai, bj, At, Bt) do { __builtin_amdgcn_s_setprio(1); _Pragma("unroll") for (int m = 0; m < 4; ++m) _Pragma("unroll") for (int n = 0; n < 2; ++n) _Pragma("unroll") for (int k = 0; k < 2; ++k) \
;         acc[ai][bj][m][n] = __builtin_amdgcn_mfma_f32_16x16x32_bf16(Bt[n][k], At[m][k], acc[ai][bj][m][n], 0, 0, 0); __builtin_amdgcn_s_setprio(0); } while (0)
; #define PG8_WAIT_V(n) asm volatile("s_waitcnt vmcnt(" #n ")" ::: "memory")
; #define PG8_WAIT_L(n) asm volatile("s_waitcnt lgkmcnt(" #n ")" ::: "memory")
; #define PG8_BAR __builtin_amdgcn_s_barrier()
; template <class Epi, class Sched, bool ALIGN_EPI = true>
; __device__ __forceinline__ void gemm_phase(PG8_LAS unsigned char* lds, const Gemm g, const Sched& S, const Epi& E, const int tid) {
;     ...
;             const bool last = (t == nt - 2);
;             const char* a1 = cA + (size_t)(t + 1) * kstep;
;             const char* a2 = last ? nA : cA + (size_t)(t + 2) * kstep; const char* b2 = last ? nB : cB + (size_t)(t + 2) * kstep;
;             const char* a3 = a2 + kstep; const char* b3 = b2 + kstep;
;             if (last && has_next) S.a_ready(nxt);
;             PG8_LDB(B0, 0, 0); PG8_LDB(B1, 0, 1); PG8_SCHED; PG8_LDA(At, 0, 0); PG8_STAGE(PG8_SA(1, 1), a1 + hstepA, voffA);
;             PG8_WAIT_V(8); PG8_WAIT_L(0); PG8_BAR; PG8_MMA(0, 0, At, B0); PG8_MMA(0, 1, At, B1); PG8_BAR; PG8_SCHED;
;             PG8_LDA(At, 0, 1); PG8_STAGE(PG8_SB(0, 0), b2, voffB); PG8_STAGE(PG8_SB(0, 1), b2 + hstepB, voffB); PG8_STAGE(PG8_SA(0, 0), a2, voffA);
;             PG8_WAIT_V(8); PG8_WAIT_L(0); PG8_BAR; PG8_MMA(1, 0, At, B0); PG8_MMA(1, 1, At, B1); PG8_BAR; PG8_SCHED;
.LBB0_426:
	s_add_u32 s15, s12, 0xfff80080
	s_addc_u32 s16, s13, -1
	s_add_i32 s17, 0, 0x10000
	s_cmp_eq_u32 s53, 4
	s_cselect_b32 s63, s1, s16
	s_cselect_b32 s62, s5, s15
	s_cselect_b32 s23, s8, s21
	s_cselect_b32 s22, s9, s20
	s_add_i32 s15, 0, 0x14000
	v_add_u32_e32 v72, s17, v251
	v_add_u32_e32 v136, s15, v251
	ds_read_b128 v[60:63], v72
	ds_read_b128 v[64:67], v72 offset:1024
	ds_read_b128 v[68:71], v72 offset:2048
	ds_read_b128 v[72:75], v72 offset:3072
	ds_read_b128 v[100:103], v136
	ds_read_b128 v[112:115], v136 offset:1024
	ds_read_b128 v[116:119], v136 offset:2048
	ds_read_b128 v[136:139], v136 offset:3072
	v_lshl_add_u64 v[196:197], s[12:13], 0, v[216:217]
	s_add_i32 m0, s11, 0xc000
	ds_read_b128 v[140:143], v252
	ds_read_b128 v[152:155], v252 offset:1024
	ds_read_b128 v[156:159], v252 offset:2048
	ds_read_b128 v[168:171], v252 offset:3072
	ds_read_b128 v[172:175], v252 offset:4096
	ds_read_b128 v[184:187], v252 offset:5120
	ds_read_b128 v[188:191], v252 offset:6144
	ds_read_b128 v[192:195], v252 offset:7168
	global_load_lds_dwordx4 v[196:197], off
	v_lshl_add_u64 v[196:197], s[12:13], 0, v[218:219]
	s_add_i32 m0, s11, 0xe000
	s_nop 0
	global_load_lds_dwordx4 v[196:197], off
	s_waitcnt vmcnt(8)
	s_waitcnt lgkmcnt(0)
	s_barrier
	s_waitcnt lgkmcnt(0)
	v_mfma_f32_16x16x32_bf16 v[180:183], v[60:63], v[140:143], v[180:183]
	v_mfma_f32_16x16x32_bf16 v[176:179], v[68:71], v[140:143], v[176:179]
	v_mfma_f32_16x16x32_bf16 v[148:151], v[60:63], v[156:159], v[148:151]
	v_mfma_f32_16x16x32_bf16 v[144:147], v[68:71], v[156:159], v[144:147]
	v_mfma_f32_16x16x32_bf16 v[124:127], v[60:63], v[172:175], v[124:127]
	v_mfma_f32_16x16x32_bf16 v[120:123], v[68:71], v[172:175], v[120:123]
	v_mfma_f32_16x16x32_bf16 v[96:99], v[60:63], v[188:191], v[96:99]
	v_mfma_f32_16x16x32_bf16 v[92:95], v[68:71], v[188:191], v[92:95]
	v_mfma_f32_16x16x32_bf16 v[180:183], v[64:67], v[152:155], v[180:183]
	v_mfma_f32_16x16x32_bf16 v[176:179], v[72:75], v[152:155], v[176:179]
	v_mfma_f32_16x16x32_bf16 v[148:151], v[64:67], v[168:171], v[148:151]
	v_mfma_f32_16x16x32_bf16 v[144:147], v[72:75], v[168:171], v[144:147]
	v_mfma_f32_16x16x32_bf16 v[124:127], v[64:67], v[184:187], v[124:127]
	v_mfma_f32_16x16x32_bf16 v[120:123], v[72:75], v[184:187], v[120:123]
	v_mfma_f32_16x16x32_bf16 v[96:99], v[64:67], v[192:195], v[96:99]
	v_mfma_f32_16x16x32_bf16 v[92:95], v[72:75], v[192:195], v[92:95]
	v_mfma_f32_16x16x32_bf16 v[164:167], v[100:103], v[140:143], v[164:167]
	v_mfma_f32_16x16x32_bf16 v[132:135], v[100:103], v[156:159], v[132:135]
	v_mfma_f32_16x16x32_bf16 v[128:131], v[116:119], v[156:159], v[128:131]
	v_mfma_f32_16x16x32_bf16 v[108:111], v[100:103], v[172:175], v[108:111]
	v_mfma_f32_16x16x32_bf16 v[104:107], v[116:119], v[172:175], v[104:107]
	v_mfma_f32_16x16x32_bf16 v[88:91], v[100:103], v[188:191], v[88:91]
	v_mfma_f32_16x16x32_bf16 v[84:87], v[116:119], v[188:191], v[84:87]
	v_mfma_f32_16x16x32_bf16 v[164:167], v[112:115], v[152:155], v[164:167]
	v_mfma_f32_16x16x32_bf16 v[140:143], v[116:119], v[140:143], v[160:163]
	v_mfma_f32_16x16x32_bf16 v[132:135], v[112:115], v[168:171], v[132:135]
	v_mfma_f32_16x16x32_bf16 v[128:131], v[136:139], v[168:171], v[128:131]
	v_mfma_f32_16x16x32_bf16 v[108:111], v[112:115], v[184:187], v[108:111]
	v_mfma_f32_16x16x32_bf16 v[104:107], v[136:139], v[184:187], v[104:107]
	v_mfma_f32_16x16x32_bf16 v[88:91], v[112:115], v[192:195], v[88:91]
	v_mfma_f32_16x16x32_bf16 v[84:87], v[136:139], v[192:195], v[84:87]
	v_mfma_f32_16x16x32_bf16 v[140:143], v[136:139], v[152:155], v[140:143]
	s_barrier
	s_add_i32 s16, s17, s67
	v_lshl_add_u64 v[200:201], s[22:23], 0, v[2:3]
	s_mov_b32 m0, s16
	ds_read_b128 v[152:155], v252 offset:16384
	ds_read_b128 v[156:159], v252 offset:17408
	ds_read_b128 v[160:163], v252 offset:18432
	ds_read_b128 v[168:171], v252 offset:19456
	ds_read_b128 v[172:175], v252 offset:20480
	ds_read_b128 v[184:187], v252 offset:21504
	ds_read_b128 v[188:191], v252 offset:22528
	ds_read_b128 v[192:195], v252 offset:23552
	global_load_lds_dwordx4 v[200:201], off
	s_add_i32 m0, s16, 0x2000
	s_add_u32 s78, s22, 0x20000
	v_lshl_add_u64 v[202:203], s[22:23], 0, v[210:211]
	s_addc_u32 s79, s23, 0
	s_add_i32 s15, s15, s67
	global_load_lds_dwordx4 v[202:203], off
	v_lshl_add_u64 v[196:197], s[78:79], 0, v[2:3]
	s_mov_b32 m0, s15
	v_lshl_add_u64 v[204:205], s[62:63], 0, v[214:215]
	global_load_lds_dwordx4 v[196:197], off
	v_lshl_add_u64 v[196:197], s[78:79], 0, v[210:211]
	s_add_i32 m0, s15, 0x2000
	v_lshl_add_u64 v[206:207], s[62:63], 0, v[212:213]
	global_load_lds_dwordx4 v[196:197], off
	s_mov_b32 m0, s11
	s_nop 0
	global_load_lds_dwordx4 v[204:205], off
	s_mov_b32 m0, s68
	s_nop 0
	global_load_lds_dwordx4 v[206:207], off
	s_waitcnt vmcnt(8)
	s_waitcnt lgkmcnt(0)
	s_barrier
; #define PG8_STAGE(bufoff, gbase, voff) do { _Pragma("unroll") for (int _i = 0; _i < 2; ++_i) \
;         __builtin_amdgcn_global_load_lds((const unsigned*)((const char*)(gbase) + (voff)[_i]), (PG8_LAS unsigned*)(lds + (bufoff) + ldsw + _i * 8192), 16, 0, 0); } while (0)
; #define PG8_LDA(dst, b, h) do { _Pragma("unroll") for (int m = 0; m < 4; ++m) _Pragma("unroll") for (int k = 0; k < 2; ++k) dst[m][k] = *(const PG8_LAS bf16x8*)(lds + PG8_SA(b, h) + aoff + m * 2048 + k * 1024); } while (0)
; #define PG8_LDB(dst, b, h) do { _Pragma("unroll") for (int n = 0; n < 2; ++n) _Pragma("unroll") for (int k = 0; k < 2; ++k) dst[n][k] = *(const PG8_LAS bf16x8*)(lds + PG8_SB(b, h) + boff + n * 2048 + k * 1024); } while (0)
; #define PG8_MMA(ai, bj, At, Bt) do { __builtin_amdgcn_s_setprio(1); _Pragma("unroll") for (int m = 0; m < 4; ++m) _Pragma("unroll") for (int n = 0; n < 2; ++n) _Pragma("unroll") for (int k = 0; k < 2; ++k) \
;         acc[ai][bj][m][n] = __builtin_amdgcn_mfma_f32_16x16x32_bf16(Bt[n][k], At[m][k], acc[ai][bj][m][n], 0, 0, 0); __builtin_amdgcn_s_setprio(0); } while (0)
; #define PG8_WAIT_V(n) asm volatile("s_waitcnt vmcnt(" #n ")" ::: "memory")
; #define PG8_WAIT_L(n) asm volatile("s_waitcnt lgkmcnt(" #n ")" ::: "memory")
; #define PG8_BAR __builtin_amdgcn_s_barrier()
; #define PG8_SCHED __builtin_amdgcn_sched_barrier(0)
; template <class Epi, class Sched, bool ALIGN_EPI = true>
; __device__ __forceinline__ void gemm_phase(PG8_LAS unsigned char* lds, const Gemm g, const Sched& S, const Epi& E, const int tid) {
;     ...
;             PG8_WAIT_V(8); PG8_WAIT_L(0); PG8_BAR; PG8_MMA(1, 0, At, B0); PG8_MMA(1, 1, At, B1); PG8_BAR; PG8_SCHED;
;             PG8_LDB(B0, 1, 0); PG8_LDB(B1, 1, 1); PG8_SCHED; PG8_LDA(At, 1, 0); PG8_STAGE(PG8_SA(0, 1), a2 + hstepA, voffA);
;             PG8_WAIT_V(8); PG8_WAIT_L(0); PG8_BAR; PG8_MMA(0, 0, At, B0); PG8_MMA(0, 1, At, B1); PG8_BAR; PG8_SCHED;
;             PG8_LDA(At, 1, 1); PG8_STAGE(PG8_SB(1, 0), b3, voffB); PG8_STAGE(PG8_SB(1, 1), b3 + hstepB, voffB); PG8_STAGE(PG8_SA(1, 0), a3, voffA);
;             PG8_WAIT_V(8); PG8_WAIT_L(0); PG8_BAR; PG8_MMA(1, 0, At, B0); PG8_MMA(1, 1, At, B1); PG8_BAR; PG8_SCHED;
	s_waitcnt lgkmcnt(0)
	v_mfma_f32_16x16x32_bf16 v[80:83], v[60:63], v[152:155], v[80:83]
	v_mfma_f32_16x16x32_bf16 v[76:79], v[68:71], v[152:155], v[76:79]
	v_mfma_f32_16x16x32_bf16 v[48:51], v[60:63], v[160:163], v[48:51]
	v_mfma_f32_16x16x32_bf16 v[44:47], v[68:71], v[160:163], v[44:47]
	v_mfma_f32_16x16x32_bf16 v[32:35], v[60:63], v[172:175], v[32:35]
	v_mfma_f32_16x16x32_bf16 v[28:31], v[68:71], v[172:175], v[28:31]
	v_mfma_f32_16x16x32_bf16 v[16:19], v[60:63], v[188:191], v[16:19]
	v_mfma_f32_16x16x32_bf16 v[12:15], v[68:71], v[188:191], v[12:15]
	v_mfma_f32_16x16x32_bf16 v[80:83], v[64:67], v[156:159], v[80:83]
	v_mfma_f32_16x16x32_bf16 v[76:79], v[72:75], v[156:159], v[76:79]
	v_mfma_f32_16x16x32_bf16 v[48:51], v[64:67], v[168:171], v[48:51]
	v_mfma_f32_16x16x32_bf16 v[44:47], v[72:75], v[168:171], v[44:47]
	v_mfma_f32_16x16x32_bf16 v[32:35], v[64:67], v[184:187], v[32:35]
	v_mfma_f32_16x16x32_bf16 v[28:31], v[72:75], v[184:187], v[28:31]
	v_mfma_f32_16x16x32_bf16 v[16:19], v[64:67], v[192:195], v[16:19]
	v_mfma_f32_16x16x32_bf16 v[12:15], v[72:75], v[192:195], v[12:15]
	v_mfma_f32_16x16x32_bf16 v[56:59], v[100:103], v[152:155], v[56:59]
	v_mfma_f32_16x16x32_bf16 v[52:55], v[116:119], v[152:155], v[52:55]
	v_mfma_f32_16x16x32_bf16 v[40:43], v[100:103], v[160:163], v[40:43]
	v_mfma_f32_16x16x32_bf16 v[36:39], v[116:119], v[160:163], v[36:39]
	v_mfma_f32_16x16x32_bf16 v[24:27], v[100:103], v[172:175], v[24:27]
	v_mfma_f32_16x16x32_bf16 v[20:23], v[116:119], v[172:175], v[20:23]
	v_mfma_f32_16x16x32_bf16 v[8:11], v[100:103], v[188:191], v[8:11]
	v_mfma_f32_16x16x32_bf16 v[4:7], v[116:119], v[188:191], v[4:7]
	v_mfma_f32_16x16x32_bf16 v[56:59], v[112:115], v[156:159], v[56:59]
	v_mfma_f32_16x16x32_bf16 v[52:55], v[136:139], v[156:159], v[52:55]
	v_mfma_f32_16x16x32_bf16 v[40:43], v[112:115], v[168:171], v[40:43]
	v_mfma_f32_16x16x32_bf16 v[36:39], v[136:139], v[168:171], v[36:39]
	v_mfma_f32_16x16x32_bf16 v[24:27], v[112:115], v[184:187], v[24:27]
	v_mfma_f32_16x16x32_bf16 v[20:23], v[136:139], v[184:187], v[20:23]
	v_mfma_f32_16x16x32_bf16 v[8:11], v[112:115], v[192:195], v[8:11]
	v_mfma_f32_16x16x32_bf16 v[4:7], v[136:139], v[192:195], v[4:7]
	s_barrier
	s_add_i32 s15, 0, 0x18000
	s_add_i32 s16, 0, 0x1c000
	v_add_u32_e32 v72, s15, v251
	v_add_u32_e32 v136, s16, v251
	ds_read_b128 v[60:63], v72
	ds_read_b128 v[64:67], v72 offset:1024
	ds_read_b128 v[68:71], v72 offset:2048
	ds_read_b128 v[72:75], v72 offset:3072
	ds_read_b128 v[100:103], v136
	ds_read_b128 v[112:115], v136 offset:1024
	ds_read_b128 v[116:119], v136 offset:2048
	ds_read_b128 v[136:139], v136 offset:3072
	s_add_u32 s62, s62, 0x80000
	s_addc_u32 s63, s63, 0
	s_mov_b32 m0, s69
	v_lshl_add_u64 v[160:161], s[62:63], 0, v[214:215]
	ds_read_b128 v[152:155], v252 offset:32768
	ds_read_b128 v[156:159], v252 offset:33792
	ds_read_b128 v[168:171], v252 offset:34816
	ds_read_b128 v[172:175], v252 offset:35840
	ds_read_b128 v[184:187], v252 offset:36864
	ds_read_b128 v[188:191], v252 offset:37888
	ds_read_b128 v[192:195], v252 offset:38912
	ds_read_b128 v[196:199], v252 offset:39936
	global_load_lds_dwordx4 v[160:161], off
	v_lshl_add_u64 v[160:161], s[62:63], 0, v[212:213]
	s_mov_b32 m0, s70
	s_nop 0
	global_load_lds_dwordx4 v[160:161], off
	s_waitcnt vmcnt(8)
	s_waitcnt lgkmcnt(0)
	s_barrier
	s_waitcnt lgkmcnt(0)
	v_mfma_f32_16x16x32_bf16 v[160:163], v[60:63], v[152:155], v[180:183]
	v_mfma_f32_16x16x32_bf16 v[180:183], v[64:67], v[156:159], v[160:163]
	v_mfma_f32_16x16x32_bf16 v[160:163], v[68:71], v[152:155], v[176:179]
	v_mfma_f32_16x16x32_bf16 v[148:151], v[60:63], v[168:171], v[148:151]
	v_mfma_f32_16x16x32_bf16 v[144:147], v[68:71], v[168:171], v[144:147]
	v_mfma_f32_16x16x32_bf16 v[124:127], v[60:63], v[184:187], v[124:127]
	v_mfma_f32_16x16x32_bf16 v[120:123], v[68:71], v[184:187], v[120:123]
	v_mfma_f32_16x16x32_bf16 v[96:99], v[60:63], v[192:195], v[96:99]
	v_mfma_f32_16x16x32_bf16 v[92:95], v[68:71], v[192:195], v[92:95]
	v_mfma_f32_16x16x32_bf16 v[176:179], v[72:75], v[156:159], v[160:163]
	v_mfma_f32_16x16x32_bf16 v[148:151], v[64:67], v[172:175], v[148:151]
	v_mfma_f32_16x16x32_bf16 v[144:147], v[72:75], v[172:175], v[144:147]
	v_mfma_f32_16x16x32_bf16 v[124:127], v[64:67], v[188:191], v[124:127]
	v_mfma_f32_16x16x32_bf16 v[120:123], v[72:75], v[188:191], v[120:123]
	v_mfma_f32_16x16x32_bf16 v[96:99], v[64:67], v[196:199], v[96:99]
	v_mfma_f32_16x16x32_bf16 v[92:95], v[72:75], v[196:199], v[92:95]
	v_mfma_f32_16x16x32_bf16 v[160:163], v[100:103], v[152:155], v[164:167]
	v_mfma_f32_16x16x32_bf16 v[140:143], v[116:119], v[152:155], v[140:143]
	v_mfma_f32_16x16x32_bf16 v[132:135], v[100:103], v[168:171], v[132:135]
	v_mfma_f32_16x16x32_bf16 v[128:131], v[116:119], v[168:171], v[128:131]
	v_mfma_f32_16x16x32_bf16 v[108:111], v[100:103], v[184:187], v[108:111]
	v_mfma_f32_16x16x32_bf16 v[104:107], v[116:119], v[184:187], v[104:107]
	v_mfma_f32_16x16x32_bf16 v[88:91], v[100:103], v[192:195], v[88:91]
	v_mfma_f32_16x16x32_bf16 v[84:87], v[116:119], v[192:195], v[84:87]
	v_mfma_f32_16x16x32_bf16 v[164:167], v[112:115], v[156:159], v[160:163]
	v_mfma_f32_16x16x32_bf16 v[160:163], v[136:139], v[156:159], v[140:143]
	v_mfma_f32_16x16x32_bf16 v[132:135], v[112:115], v[172:175], v[132:135]
	v_mfma_f32_16x16x32_bf16 v[128:131], v[136:139], v[172:175], v[128:131]
	v_mfma_f32_16x16x32_bf16 v[108:111], v[112:115], v[188:191], v[108:111]
	v_mfma_f32_16x16x32_bf16 v[104:107], v[136:139], v[188:191], v[104:107]
	v_mfma_f32_16x16x32_bf16 v[88:91], v[112:115], v[196:199], v[88:91]
	v_mfma_f32_16x16x32_bf16 v[84:87], v[136:139], v[196:199], v[84:87]
	s_barrier
; #define PG8_STAGE(bufoff, gbase, voff) do { _Pragma("unroll") for (int _i = 0; _i < 2; ++_i) \
;         __builtin_amdgcn_global_load_lds((const unsigned*)((const char*)(gbase) + (voff)[_i]), (PG8_LAS unsigned*)(lds + (bufoff) + ldsw + _i * 8192), 16, 0, 0); } while (0)
; #define PG8_LDA(dst, b, h) do { _Pragma("unroll") for (int m = 0; m < 4; ++m) _Pragma("unroll") for (int k = 0; k < 2; ++k) dst[m][k] = *(const PG8_LAS bf16x8*)(lds + PG8_SA(b, h) + aoff + m * 2048 + k * 1024); } while (0)
; #define PG8_MMA(ai, bj, At, Bt) do { __builtin_amdgcn_s_setprio(1); _Pragma("unroll") for (int m = 0; m < 4; ++m) _Pragma("unroll") for (int n = 0; n < 2; ++n) _Pragma("unroll") for (int k = 0; k < 2; ++k) \
;         acc[ai][bj][m][n] = __builtin_amdgcn_mfma_f32_16x16x32_bf16(Bt[n][k], At[m][k], acc[ai][bj][m][n], 0, 0, 0); __builtin_amdgcn_s_setprio(0); } while (0)
; #define PG8_WAIT_V(n) asm volatile("s_waitcnt vmcnt(" #n ")" ::: "memory")
; #define PG8_WAIT_L(n) asm volatile("s_waitcnt lgkmcnt(" #n ")" ::: "memory")
; #define PG8_BAR __builtin_amdgcn_s_barrier()
; #define PG8_SCHED __builtin_amdgcn_sched_barrier(0)
; template <class Epi, class Sched, bool ALIGN_EPI = true>
; __device__ __forceinline__ void gemm_phase(PG8_LAS unsigned char* lds, const Gemm g, const Sched& S, const Epi& E, const int tid) {
;     ...
;             PG8_LDA(At, 1, 1); PG8_STAGE(PG8_SB(1, 0), b3, voffB); PG8_STAGE(PG8_SB(1, 1), b3 + hstepB, voffB); PG8_STAGE(PG8_SA(1, 0), a3, voffA);
;             PG8_WAIT_V(8); PG8_WAIT_L(0); PG8_BAR; PG8_MMA(1, 0, At, B0); PG8_MMA(1, 1, At, B1); PG8_BAR; PG8_SCHED;
;         }
	s_add_i32 s15, s15, s67
	v_lshl_add_u64 v[196:197], v[200:201], 0, s[36:37]
	s_mov_b32 m0, s15
	ds_read_b128 v[140:143], v252 offset:49152
	ds_read_b128 v[152:155], v252 offset:50176
	ds_read_b128 v[156:159], v252 offset:51200
	ds_read_b128 v[168:171], v252 offset:52224
	ds_read_b128 v[172:175], v252 offset:53248
	ds_read_b128 v[184:187], v252 offset:54272
	ds_read_b128 v[188:191], v252 offset:55296
	ds_read_b128 v[192:195], v252 offset:56320
	global_load_lds_dwordx4 v[196:197], off
	s_add_i32 m0, s15, 0x2000
	s_add_u32 s22, s22, 0x20080
	v_lshl_add_u64 v[196:197], v[202:203], 0, s[36:37]
	s_addc_u32 s23, s23, 0
	s_add_i32 s15, s16, s67
	global_load_lds_dwordx4 v[196:197], off
	v_lshl_add_u64 v[196:197], s[22:23], 0, v[2:3]
	s_mov_b32 m0, s15
	s_nop 0
	global_load_lds_dwordx4 v[196:197], off
	v_lshl_add_u64 v[196:197], s[22:23], 0, v[210:211]
	s_add_i32 m0, s15, 0x2000
	s_nop 0
	global_load_lds_dwordx4 v[196:197], off
	v_lshl_add_u64 v[196:197], v[204:205], 0, s[36:37]
	s_mov_b32 m0, s75
	s_nop 0
	global_load_lds_dwordx4 v[196:197], off
	v_lshl_add_u64 v[196:197], v[206:207], 0, s[36:37]
	s_mov_b32 m0, s76
	s_nop 0
	global_load_lds_dwordx4 v[196:197], off
	s_waitcnt vmcnt(8)
	s_waitcnt lgkmcnt(0)
	s_barrier
	s_waitcnt lgkmcnt(0)
	v_mfma_f32_16x16x32_bf16 v[80:83], v[60:63], v[140:143], v[80:83]
	v_mfma_f32_16x16x32_bf16 v[76:79], v[68:71], v[140:143], v[76:79]
	v_mfma_f32_16x16x32_bf16 v[48:51], v[60:63], v[156:159], v[48:51]
	v_mfma_f32_16x16x32_bf16 v[44:47], v[68:71], v[156:159], v[44:47]
	v_mfma_f32_16x16x32_bf16 v[32:35], v[60:63], v[172:175], v[32:35]
	v_mfma_f32_16x16x32_bf16 v[28:31], v[68:71], v[172:175], v[28:31]
	v_mfma_f32_16x16x32_bf16 v[16:19], v[60:63], v[188:191], v[16:19]
	v_mfma_f32_16x16x32_bf16 v[12:15], v[68:71], v[188:191], v[12:15]
	v_mfma_f32_16x16x32_bf16 v[80:83], v[64:67], v[152:155], v[80:83]
	v_mfma_f32_16x16x32_bf16 v[76:79], v[72:75], v[152:155], v[76:79]
	v_mfma_f32_16x16x32_bf16 v[48:51], v[64:67], v[168:171], v[48:51]
	v_mfma_f32_16x16x32_bf16 v[44:47], v[72:75], v[168:171], v[44:47]
	v_mfma_f32_16x16x32_bf16 v[32:35], v[64:67], v[184:187], v[32:35]
	v_mfma_f32_16x16x32_bf16 v[28:31], v[72:75], v[184:187], v[28:31]
	v_mfma_f32_16x16x32_bf16 v[16:19], v[64:67], v[192:195], v[16:19]
	v_mfma_f32_16x16x32_bf16 v[12:15], v[72:75], v[192:195], v[12:15]
	v_mfma_f32_16x16x32_bf16 v[56:59], v[100:103], v[140:143], v[56:59]
	v_mfma_f32_16x16x32_bf16 v[52:55], v[116:119], v[140:143], v[52:55]
	v_mfma_f32_16x16x32_bf16 v[40:43], v[100:103], v[156:159], v[40:43]
	v_mfma_f32_16x16x32_bf16 v[36:39], v[116:119], v[156:159], v[36:39]
	v_mfma_f32_16x16x32_bf16 v[24:27], v[100:103], v[172:175], v[24:27]
	v_mfma_f32_16x16x32_bf16 v[20:23], v[116:119], v[172:175], v[20:23]
	v_mfma_f32_16x16x32_bf16 v[8:11], v[100:103], v[188:191], v[8:11]
	v_mfma_f32_16x16x32_bf16 v[4:7], v[116:119], v[188:191], v[4:7]
	v_mfma_f32_16x16x32_bf16 v[56:59], v[112:115], v[152:155], v[56:59]
	v_mfma_f32_16x16x32_bf16 v[52:55], v[136:139], v[152:155], v[52:55]
	v_mfma_f32_16x16x32_bf16 v[40:43], v[112:115], v[168:171], v[40:43]
	v_mfma_f32_16x16x32_bf16 v[36:39], v[136:139], v[168:171], v[36:39]
	v_mfma_f32_16x16x32_bf16 v[24:27], v[112:115], v[184:187], v[24:27]
	v_mfma_f32_16x16x32_bf16 v[20:23], v[136:139], v[184:187], v[20:23]
	v_mfma_f32_16x16x32_bf16 v[8:11], v[112:115], v[192:195], v[8:11]
	v_mfma_f32_16x16x32_bf16 v[4:7], v[136:139], v[192:195], v[4:7]
	s_barrier
	s_add_i32 s53, s53, 2
	s_add_u32 s12, s12, 0x100
	s_addc_u32 s13, s13, 0
	s_add_u32 s20, s20, 0x100
	s_addc_u32 s21, s21, 0
	s_cmp_gt_u32 s53, 5
	s_cbranch_scc0 .LBB0_426
	s_and_b64 vcc, exec, s[48:49]
	s_cbranch_vccz .LBB0_429
	s_barrier

; #define PG8_STAGE(bufoff, gbase, voff) do { _Pragma("unroll") for (int _i = 0; _i < 2; ++_i) \
;         __builtin_amdgcn_global_load_lds((const unsigned*)((const char*)(gbase) + (voff)[_i]), (PG8_LAS unsigned*)(lds + (bufoff) + ldsw + _i * 8192), 16, 0, 0); } while (0)
; #define PG8_LDA(dst, b, h) do { _Pragma("unroll") for (int m = 0; m < 4; ++m) _Pragma("unroll") for (int k = 0; k < 2; ++k) dst[m][k] = *(const PG8_LAS bf16x8*)(lds + PG8_SA(b, h) + aoff + m * 2048 + k * 1024); } while (0)
; #define PG8_LDB(dst, b, h) do { _Pragma("unroll") for (int n = 0; n < 2; ++n) _Pragma("unroll") for (int k = 0; k < 2; ++k) dst[n][k] = *(const PG8_LAS bf16x8*)(lds + PG8_SB(b, h) + boff + n * 2048 + k * 1024); } while (0)
; #define PG8_MMA(ai, bj, At, Bt) do { __builtin_amdgcn_s_setprio(1); _Pragma("unroll") for (int m = 0; m < 4; ++m) _Pragma("unroll") for (int n = 0; n < 2; ++n) _Pragma("unroll") for (int k = 0; k < 2; ++k) \
;         acc[ai][bj][m][n] = __builtin_amdgcn_mfma_f32_16x16x32_bf16(Bt[n][k], At[m][k], acc[ai][bj][m][n], 0, 0, 0); __builtin_amdgcn_s_setprio(0); } while (0)
; #define PG8_WAIT_V(n) asm volatile("s_waitcnt vmcnt(" #n ")" ::: "memory")
; #define PG8_WAIT_L(n) asm volatile("s_waitcnt lgkmcnt(" #n ")" ::: "memory")
; #define PG8_BAR __builtin_amdgcn_s_barrier()
; template <class Epi, class Sched, bool ALIGN_EPI = true>
; __device__ __forceinline__ void gemm_phase(PG8_LAS unsigned char* lds, const Gemm g, const Sched& S, const Epi& E, const int tid) {
;     ...
;             const bool last = (t == nt - 2);
;             const char* a1 = cA + (size_t)(t + 1) * kstep;
;             const char* a2 = last ? nA : cA + (size_t)(t + 2) * kstep; const char* b2 = last ? nB : cB + (size_t)(t + 2) * kstep;
;             const char* a3 = a2 + kstep; const char* b3 = b2 + kstep;
;             if (last && has_next) S.a_ready(nxt);
;             PG8_LDB(B0, 0, 0); PG8_LDB(B1, 0, 1); PG8_SCHED; PG8_LDA(At, 0, 0); PG8_STAGE(PG8_SA(1, 1), a1 + hstepA, voffA);
;             PG8_WAIT_V(8); PG8_WAIT_L(0); PG8_BAR; PG8_MMA(0, 0, At, B0); PG8_MMA(0, 1, At, B1); PG8_BAR; PG8_SCHED;
;             PG8_LDA(At, 0, 1); PG8_STAGE(PG8_SB(0, 0), b2, voffB); PG8_STAGE(PG8_SB(0, 1), b2 + hstepB, voffB); PG8_STAGE(PG8_SA(0, 0), a2, voffA);
;             PG8_WAIT_V(8); PG8_WAIT_L(0); PG8_BAR; PG8_MMA(1, 0, At, B0); PG8_MMA(1, 1, At, B1); PG8_BAR; PG8_SCHED;
.LBB0_514:
	s_add_u32 s44, s42, 0xfff80080
	s_addc_u32 s45, s43, -1
	s_add_i32 s57, 0, 0x10000
	s_cmp_eq_u32 s56, 28
	s_cselect_b32 s47, s13, s45
	s_cselect_b32 s46, s52, s44
	s_cselect_b32 s45, s23, s55
	s_cselect_b32 s44, s53, s54
	s_add_i32 s60, 0, 0x14000
	v_add_u32_e32 v158, s57, v147
	v_add_u32_e32 v174, s60, v147
	ds_read_b128 v[142:145], v158
	ds_read_b128 v[150:153], v158 offset:1024
	ds_read_b128 v[154:157], v158 offset:2048
	ds_read_b128 v[158:161], v158 offset:3072
	ds_read_b128 v[162:165], v174
	ds_read_b128 v[166:169], v174 offset:1024
	ds_read_b128 v[170:173], v174 offset:2048
	ds_read_b128 v[174:177], v174 offset:3072
	v_lshl_add_u64 v[206:207], s[42:43], 0, v[138:139]
	s_add_i32 m0, s7, 0xc000
	ds_read_b128 v[178:181], v149
	ds_read_b128 v[182:185], v149 offset:1024
	ds_read_b128 v[186:189], v149 offset:2048
	ds_read_b128 v[190:193], v149 offset:3072
	ds_read_b128 v[194:197], v149 offset:4096
	ds_read_b128 v[198:201], v149 offset:5120
	ds_read_b128 v[202:205], v149 offset:6144
	ds_read_b128 v[210:213], v149 offset:7168
	global_load_lds_dwordx4 v[206:207], off
	v_lshl_add_u64 v[206:207], s[42:43], 0, v[140:141]
	s_add_i32 m0, s7, 0xe000
	s_nop 0
	global_load_lds_dwordx4 v[206:207], off
	s_waitcnt vmcnt(8)
	s_waitcnt lgkmcnt(0)
	s_barrier
	s_waitcnt lgkmcnt(0)
	v_mfma_f32_16x16x32_bf16 v[128:131], v[142:145], v[178:181], v[128:131]
	v_mfma_f32_16x16x32_bf16 v[124:127], v[154:157], v[178:181], v[124:127]
	v_mfma_f32_16x16x32_bf16 v[120:123], v[142:145], v[186:189], v[120:123]
	v_mfma_f32_16x16x32_bf16 v[112:115], v[154:157], v[186:189], v[112:115]
	v_mfma_f32_16x16x32_bf16 v[104:107], v[142:145], v[194:197], v[104:107]
	v_mfma_f32_16x16x32_bf16 v[96:99], v[154:157], v[194:197], v[96:99]
	v_mfma_f32_16x16x32_bf16 v[88:91], v[142:145], v[202:205], v[88:91]
	v_mfma_f32_16x16x32_bf16 v[80:83], v[154:157], v[202:205], v[80:83]
	v_mfma_f32_16x16x32_bf16 v[128:131], v[150:153], v[182:185], v[128:131]
	v_mfma_f32_16x16x32_bf16 v[124:127], v[158:161], v[182:185], v[124:127]
	v_mfma_f32_16x16x32_bf16 v[120:123], v[150:153], v[190:193], v[120:123]
	v_mfma_f32_16x16x32_bf16 v[112:115], v[158:161], v[190:193], v[112:115]
	v_mfma_f32_16x16x32_bf16 v[104:107], v[150:153], v[198:201], v[104:107]
	v_mfma_f32_16x16x32_bf16 v[96:99], v[158:161], v[198:201], v[96:99]
	v_mfma_f32_16x16x32_bf16 v[88:91], v[150:153], v[210:213], v[88:91]
	v_mfma_f32_16x16x32_bf16 v[80:83], v[158:161], v[210:213], v[80:83]
	v_mfma_f32_16x16x32_bf16 v[116:119], v[162:165], v[178:181], v[116:119]
	v_mfma_f32_16x16x32_bf16 v[108:111], v[170:173], v[178:181], v[108:111]
	v_mfma_f32_16x16x32_bf16 v[100:103], v[162:165], v[186:189], v[100:103]
	v_mfma_f32_16x16x32_bf16 v[92:95], v[170:173], v[186:189], v[92:95]
	v_mfma_f32_16x16x32_bf16 v[84:87], v[162:165], v[194:197], v[84:87]
	v_mfma_f32_16x16x32_bf16 v[76:79], v[170:173], v[194:197], v[76:79]
	v_mfma_f32_16x16x32_bf16 v[72:75], v[162:165], v[202:205], v[72:75]
	v_mfma_f32_16x16x32_bf16 v[68:71], v[170:173], v[202:205], v[68:71]
	v_mfma_f32_16x16x32_bf16 v[116:119], v[166:169], v[182:185], v[116:119]
	v_mfma_f32_16x16x32_bf16 v[108:111], v[174:177], v[182:185], v[108:111]
	v_mfma_f32_16x16x32_bf16 v[100:103], v[166:169], v[190:193], v[100:103]
	v_mfma_f32_16x16x32_bf16 v[92:95], v[174:177], v[190:193], v[92:95]
	v_mfma_f32_16x16x32_bf16 v[84:87], v[166:169], v[198:201], v[84:87]
	v_mfma_f32_16x16x32_bf16 v[76:79], v[174:177], v[198:201], v[76:79]
	v_mfma_f32_16x16x32_bf16 v[72:75], v[166:169], v[210:213], v[72:75]
	v_mfma_f32_16x16x32_bf16 v[68:71], v[174:177], v[210:213], v[68:71]
	s_barrier
	s_add_i32 s57, s57, s21
	v_lshl_add_u64 v[206:207], s[44:45], 0, v[2:3]
	s_mov_b32 m0, s57
	ds_read_b128 v[178:181], v149 offset:16384
	ds_read_b128 v[182:185], v149 offset:17408
	ds_read_b128 v[186:189], v149 offset:18432
	ds_read_b128 v[190:193], v149 offset:19456
	ds_read_b128 v[194:197], v149 offset:20480
	ds_read_b128 v[198:201], v149 offset:21504
	ds_read_b128 v[202:205], v149 offset:22528
	ds_read_b128 v[210:213], v149 offset:23552
	global_load_lds_dwordx4 v[206:207], off
	s_add_i32 m0, s57, 0x2000
	s_add_u32 s58, s44, 0x80000
	v_lshl_add_u64 v[214:215], s[44:45], 0, v[132:133]
	s_addc_u32 s59, s45, 0
	s_add_i32 s57, s60, s21
	global_load_lds_dwordx4 v[214:215], off
	v_lshl_add_u64 v[216:217], s[58:59], 0, v[2:3]
	s_mov_b32 m0, s57
	v_lshl_add_u64 v[218:219], s[46:47], 0, v[134:135]
	global_load_lds_dwordx4 v[216:217], off
	v_lshl_add_u64 v[216:217], s[58:59], 0, v[132:133]
	s_add_i32 m0, s57, 0x2000
	s_nop 0
	global_load_lds_dwordx4 v[216:217], off
	v_lshl_add_u64 v[216:217], s[46:47], 0, v[136:137]
	s_mov_b32 m0, s7
	s_nop 0
	global_load_lds_dwordx4 v[216:217], off
	s_mov_b32 m0, s11
	s_nop 0
	global_load_lds_dwordx4 v[218:219], off
	s_waitcnt vmcnt(8)
	s_waitcnt lgkmcnt(0)
	s_barrier
; #define PG8_STAGE(bufoff, gbase, voff) do { _Pragma("unroll") for (int _i = 0; _i < 2; ++_i) \
;         __builtin_amdgcn_global_load_lds((const unsigned*)((const char*)(gbase) + (voff)[_i]), (PG8_LAS unsigned*)(lds + (bufoff) + ldsw + _i * 8192), 16, 0, 0); } while (0)
; #define PG8_LDA(dst, b, h) do { _Pragma("unroll") for (int m = 0; m < 4; ++m) _Pragma("unroll") for (int k = 0; k < 2; ++k) dst[m][k] = *(const PG8_LAS bf16x8*)(lds + PG8_SA(b, h) + aoff + m * 2048 + k * 1024); } while (0)
; #define PG8_LDB(dst, b, h) do { _Pragma("unroll") for (int n = 0; n < 2; ++n) _Pragma("unroll") for (int k = 0; k < 2; ++k) dst[n][k] = *(const PG8_LAS bf16x8*)(lds + PG8_SB(b, h) + boff + n * 2048 + k * 1024); } while (0)
; #define PG8_MMA(ai, bj, At, Bt) do { __builtin_amdgcn_s_setprio(1); _Pragma("unroll") for (int m = 0; m < 4; ++m) _Pragma("unroll") for (int n = 0; n < 2; ++n) _Pragma("unroll") for (int k = 0; k < 2; ++k) \
;         acc[ai][bj][m][n] = __builtin_amdgcn_mfma_f32_16x16x32_bf16(Bt[n][k], At[m][k], acc[ai][bj][m][n], 0, 0, 0); __builtin_amdgcn_s_setprio(0); } while (0)
; #define PG8_WAIT_V(n) asm volatile("s_waitcnt vmcnt(" #n ")" ::: "memory")
; #define PG8_WAIT_L(n) asm volatile("s_waitcnt lgkmcnt(" #n ")" ::: "memory")
; #define PG8_BAR __builtin_amdgcn_s_barrier()
; #define PG8_SCHED __builtin_amdgcn_sched_barrier(0)
; template <class Epi, class Sched, bool ALIGN_EPI = true>
; __device__ __forceinline__ void gemm_phase(PG8_LAS unsigned char* lds, const Gemm g, const Sched& S, const Epi& E, const int tid) {
;     ...
;             PG8_WAIT_V(8); PG8_WAIT_L(0); PG8_BAR; PG8_MMA(1, 0, At, B0); PG8_MMA(1, 1, At, B1); PG8_BAR; PG8_SCHED;
;             PG8_LDB(B0, 1, 0); PG8_LDB(B1, 1, 1); PG8_SCHED; PG8_LDA(At, 1, 0); PG8_STAGE(PG8_SA(0, 1), a2 + hstepA, voffA);
;             PG8_WAIT_V(8); PG8_WAIT_L(0); PG8_BAR; PG8_MMA(0, 0, At, B0); PG8_MMA(0, 1, At, B1); PG8_BAR; PG8_SCHED;
;             PG8_LDA(At, 1, 1); PG8_STAGE(PG8_SB(1, 0), b3, voffB); PG8_STAGE(PG8_SB(1, 1), b3 + hstepB, voffB); PG8_STAGE(PG8_SA(1, 0), a3, voffA);
;             PG8_WAIT_V(8); PG8_WAIT_L(0); PG8_BAR; PG8_MMA(1, 0, At, B0); PG8_MMA(1, 1, At, B1); PG8_BAR; PG8_SCHED;
	s_waitcnt lgkmcnt(0)
	v_mfma_f32_16x16x32_bf16 v[64:67], v[142:145], v[178:181], v[64:67]
	v_mfma_f32_16x16x32_bf16 v[60:63], v[154:157], v[178:181], v[60:63]
	v_mfma_f32_16x16x32_bf16 v[56:59], v[142:145], v[186:189], v[56:59]
	v_mfma_f32_16x16x32_bf16 v[48:51], v[154:157], v[186:189], v[48:51]
	v_mfma_f32_16x16x32_bf16 v[40:43], v[142:145], v[194:197], v[40:43]
	v_mfma_f32_16x16x32_bf16 v[32:35], v[154:157], v[194:197], v[32:35]
	v_mfma_f32_16x16x32_bf16 v[24:27], v[142:145], v[202:205], v[24:27]
	v_mfma_f32_16x16x32_bf16 v[16:19], v[154:157], v[202:205], v[16:19]
	v_mfma_f32_16x16x32_bf16 v[64:67], v[150:153], v[182:185], v[64:67]
	v_mfma_f32_16x16x32_bf16 v[60:63], v[158:161], v[182:185], v[60:63]
	v_mfma_f32_16x16x32_bf16 v[56:59], v[150:153], v[190:193], v[56:59]
	v_mfma_f32_16x16x32_bf16 v[48:51], v[158:161], v[190:193], v[48:51]
	v_mfma_f32_16x16x32_bf16 v[40:43], v[150:153], v[198:201], v[40:43]
	v_mfma_f32_16x16x32_bf16 v[32:35], v[158:161], v[198:201], v[32:35]
	v_mfma_f32_16x16x32_bf16 v[24:27], v[150:153], v[210:213], v[24:27]
	v_mfma_f32_16x16x32_bf16 v[16:19], v[158:161], v[210:213], v[16:19]
	v_mfma_f32_16x16x32_bf16 v[52:55], v[162:165], v[178:181], v[52:55]
	v_mfma_f32_16x16x32_bf16 v[44:47], v[170:173], v[178:181], v[44:47]
	v_mfma_f32_16x16x32_bf16 v[36:39], v[162:165], v[186:189], v[36:39]
	v_mfma_f32_16x16x32_bf16 v[28:31], v[170:173], v[186:189], v[28:31]
	v_mfma_f32_16x16x32_bf16 v[20:23], v[162:165], v[194:197], v[20:23]
	v_mfma_f32_16x16x32_bf16 v[12:15], v[170:173], v[194:197], v[12:15]
	v_mfma_f32_16x16x32_bf16 v[8:11], v[162:165], v[202:205], v[8:11]
	v_mfma_f32_16x16x32_bf16 v[4:7], v[170:173], v[202:205], v[4:7]
	v_mfma_f32_16x16x32_bf16 v[52:55], v[166:169], v[182:185], v[52:55]
	v_mfma_f32_16x16x32_bf16 v[44:47], v[174:177], v[182:185], v[44:47]
	v_mfma_f32_16x16x32_bf16 v[36:39], v[166:169], v[190:193], v[36:39]
	v_mfma_f32_16x16x32_bf16 v[28:31], v[174:177], v[190:193], v[28:31]
	v_mfma_f32_16x16x32_bf16 v[20:23], v[166:169], v[198:201], v[20:23]
	v_mfma_f32_16x16x32_bf16 v[12:15], v[174:177], v[198:201], v[12:15]
	v_mfma_f32_16x16x32_bf16 v[8:11], v[166:169], v[210:213], v[8:11]
	v_mfma_f32_16x16x32_bf16 v[4:7], v[174:177], v[210:213], v[4:7]
	s_barrier
	s_add_i32 s57, 0, 0x18000
	s_add_i32 s58, 0, 0x1c000
	v_add_u32_e32 v158, s57, v147
	v_add_u32_e32 v174, s58, v147
	ds_read_b128 v[142:145], v158
	ds_read_b128 v[150:153], v158 offset:1024
	ds_read_b128 v[154:157], v158 offset:2048
	ds_read_b128 v[158:161], v158 offset:3072
	ds_read_b128 v[162:165], v174
	ds_read_b128 v[166:169], v174 offset:1024
	ds_read_b128 v[170:173], v174 offset:2048
	ds_read_b128 v[174:177], v174 offset:3072
	s_add_u32 s46, s46, 0x80000
	s_addc_u32 s47, s47, 0
	s_mov_b32 m0, s30
	v_lshl_add_u64 v[220:221], s[46:47], 0, v[136:137]
	ds_read_b128 v[178:181], v149 offset:32768
	ds_read_b128 v[182:185], v149 offset:33792
	ds_read_b128 v[186:189], v149 offset:34816
	ds_read_b128 v[190:193], v149 offset:35840
	ds_read_b128 v[194:197], v149 offset:36864
	ds_read_b128 v[198:201], v149 offset:37888
	ds_read_b128 v[202:205], v149 offset:38912
	ds_read_b128 v[210:213], v149 offset:39936
	global_load_lds_dwordx4 v[220:221], off
	v_lshl_add_u64 v[220:221], s[46:47], 0, v[134:135]
	s_mov_b32 m0, s48
	s_nop 0
	global_load_lds_dwordx4 v[220:221], off
	s_waitcnt vmcnt(8)
	s_waitcnt lgkmcnt(0)
	s_barrier
	s_waitcnt lgkmcnt(0)
	v_mfma_f32_16x16x32_bf16 v[128:131], v[142:145], v[178:181], v[128:131]
	v_mfma_f32_16x16x32_bf16 v[124:127], v[154:157], v[178:181], v[124:127]
	v_mfma_f32_16x16x32_bf16 v[120:123], v[142:145], v[186:189], v[120:123]
	v_mfma_f32_16x16x32_bf16 v[112:115], v[154:157], v[186:189], v[112:115]
	v_mfma_f32_16x16x32_bf16 v[104:107], v[142:145], v[194:197], v[104:107]
	v_mfma_f32_16x16x32_bf16 v[96:99], v[154:157], v[194:197], v[96:99]
	v_mfma_f32_16x16x32_bf16 v[88:91], v[142:145], v[202:205], v[88:91]
	v_mfma_f32_16x16x32_bf16 v[80:83], v[154:157], v[202:205], v[80:83]
	v_mfma_f32_16x16x32_bf16 v[128:131], v[150:153], v[182:185], v[128:131]
	v_mfma_f32_16x16x32_bf16 v[124:127], v[158:161], v[182:185], v[124:127]
	v_mfma_f32_16x16x32_bf16 v[120:123], v[150:153], v[190:193], v[120:123]
	v_mfma_f32_16x16x32_bf16 v[112:115], v[158:161], v[190:193], v[112:115]
	v_mfma_f32_16x16x32_bf16 v[104:107], v[150:153], v[198:201], v[104:107]
	v_mfma_f32_16x16x32_bf16 v[96:99], v[158:161], v[198:201], v[96:99]
	v_mfma_f32_16x16x32_bf16 v[88:91], v[150:153], v[210:213], v[88:91]
	v_mfma_f32_16x16x32_bf16 v[80:83], v[158:161], v[210:213], v[80:83]
	v_mfma_f32_16x16x32_bf16 v[116:119], v[162:165], v[178:181], v[116:119]
	v_mfma_f32_16x16x32_bf16 v[108:111], v[170:173], v[178:181], v[108:111]
	v_mfma_f32_16x16x32_bf16 v[100:103], v[162:165], v[186:189], v[100:103]
	v_mfma_f32_16x16x32_bf16 v[92:95], v[170:173], v[186:189], v[92:95]
	v_mfma_f32_16x16x32_bf16 v[84:87], v[162:165], v[194:197], v[84:87]
	v_mfma_f32_16x16x32_bf16 v[76:79], v[170:173], v[194:197], v[76:79]
	v_mfma_f32_16x16x32_bf16 v[72:75], v[162:165], v[202:205], v[72:75]
	v_mfma_f32_16x16x32_bf16 v[68:71], v[170:173], v[202:205], v[68:71]
	v_mfma_f32_16x16x32_bf16 v[116:119], v[166:169], v[182:185], v[116:119]
	v_mfma_f32_16x16x32_bf16 v[108:111], v[174:177], v[182:185], v[108:111]
	v_mfma_f32_16x16x32_bf16 v[100:103], v[166:169], v[190:193], v[100:103]
	v_mfma_f32_16x16x32_bf16 v[92:95], v[174:177], v[190:193], v[92:95]
	v_mfma_f32_16x16x32_bf16 v[84:87], v[166:169], v[198:201], v[84:87]
	v_mfma_f32_16x16x32_bf16 v[76:79], v[174:177], v[198:201], v[76:79]
	v_mfma_f32_16x16x32_bf16 v[72:75], v[166:169], v[210:213], v[72:75]
	v_mfma_f32_16x16x32_bf16 v[68:71], v[174:177], v[210:213], v[68:71]
	s_barrier
; #define PG8_STAGE(bufoff, gbase, voff) do { _Pragma("unroll") for (int _i = 0; _i < 2; ++_i) \
;         __builtin_amdgcn_global_load_lds((const unsigned*)((const char*)(gbase) + (voff)[_i]), (PG8_LAS unsigned*)(lds + (bufoff) + ldsw + _i * 8192), 16, 0, 0); } while (0)
; #define PG8_LDA(dst, b, h) do { _Pragma("unroll") for (int m = 0; m < 4; ++m) _Pragma("unroll") for (int k = 0; k < 2; ++k) dst[m][k] = *(const PG8_LAS bf16x8*)(lds + PG8_SA(b, h) + aoff + m * 2048 + k * 1024); } while (0)
; #define PG8_MMA(ai, bj, At, Bt) do { __builtin_amdgcn_s_setprio(1); _Pragma("unroll") for (int m = 0; m < 4; ++m) _Pragma("unroll") for (int n = 0; n < 2; ++n) _Pragma("unroll") for (int k = 0; k < 2; ++k) \
;         acc[ai][bj][m][n] = __builtin_amdgcn_mfma_f32_16x16x32_bf16(Bt[n][k], At[m][k], acc[ai][bj][m][n], 0, 0, 0); __builtin_amdgcn_s_setprio(0); } while (0)
; #define PG8_WAIT_V(n) asm volatile("s_waitcnt vmcnt(" #n ")" ::: "memory")
; #define PG8_WAIT_L(n) asm volatile("s_waitcnt lgkmcnt(" #n ")" ::: "memory")
; #define PG8_BAR __builtin_amdgcn_s_barrier()
; #define PG8_SCHED __builtin_amdgcn_sched_barrier(0)
; template <class Epi, class Sched, bool ALIGN_EPI = true>
; __device__ __forceinline__ void gemm_phase(PG8_LAS unsigned char* lds, const Gemm g, const Sched& S, const Epi& E, const int tid) {
;     ...
;             PG8_LDA(At, 1, 1); PG8_STAGE(PG8_SB(1, 0), b3, voffB); PG8_STAGE(PG8_SB(1, 1), b3 + hstepB, voffB); PG8_STAGE(PG8_SA(1, 0), a3, voffA);
;             PG8_WAIT_V(8); PG8_WAIT_L(0); PG8_BAR; PG8_MMA(1, 0, At, B0); PG8_MMA(1, 1, At, B1); PG8_BAR; PG8_SCHED;
;         }
	s_add_i32 s46, s57, s21
	v_lshl_add_u64 v[206:207], v[206:207], 0, s[36:37]
	s_mov_b32 m0, s46
	ds_read_b128 v[178:181], v149 offset:49152
	ds_read_b128 v[182:185], v149 offset:50176
	ds_read_b128 v[186:189], v149 offset:51200
	ds_read_b128 v[190:193], v149 offset:52224
	ds_read_b128 v[194:197], v149 offset:53248
	ds_read_b128 v[198:201], v149 offset:54272
	ds_read_b128 v[202:205], v149 offset:55296
	ds_read_b128 v[210:213], v149 offset:56320
	global_load_lds_dwordx4 v[206:207], off
	s_add_i32 m0, s46, 0x2000
	s_add_u32 s44, s44, 0x80080
	v_lshl_add_u64 v[206:207], v[214:215], 0, s[36:37]
	s_addc_u32 s45, s45, 0
	s_add_i32 s46, s58, s21
	global_load_lds_dwordx4 v[206:207], off
	v_lshl_add_u64 v[206:207], s[44:45], 0, v[2:3]
	s_mov_b32 m0, s46
	s_nop 0
	global_load_lds_dwordx4 v[206:207], off
	v_lshl_add_u64 v[206:207], s[44:45], 0, v[132:133]
	s_add_i32 m0, s46, 0x2000
	s_nop 0
	global_load_lds_dwordx4 v[206:207], off
	v_lshl_add_u64 v[206:207], v[216:217], 0, s[36:37]
	s_mov_b32 m0, s49
	s_nop 0
	global_load_lds_dwordx4 v[206:207], off
	v_lshl_add_u64 v[206:207], v[218:219], 0, s[36:37]
	s_mov_b32 m0, s50
	s_nop 0
	global_load_lds_dwordx4 v[206:207], off
	s_waitcnt vmcnt(8)
	s_waitcnt lgkmcnt(0)
	s_barrier
	s_waitcnt lgkmcnt(0)
	v_mfma_f32_16x16x32_bf16 v[64:67], v[142:145], v[178:181], v[64:67]
	v_mfma_f32_16x16x32_bf16 v[60:63], v[154:157], v[178:181], v[60:63]
	v_mfma_f32_16x16x32_bf16 v[56:59], v[142:145], v[186:189], v[56:59]
	v_mfma_f32_16x16x32_bf16 v[48:51], v[154:157], v[186:189], v[48:51]
	v_mfma_f32_16x16x32_bf16 v[40:43], v[142:145], v[194:197], v[40:43]
	v_mfma_f32_16x16x32_bf16 v[32:35], v[154:157], v[194:197], v[32:35]
	v_mfma_f32_16x16x32_bf16 v[24:27], v[142:145], v[202:205], v[24:27]
	v_mfma_f32_16x16x32_bf16 v[16:19], v[154:157], v[202:205], v[16:19]
	v_mfma_f32_16x16x32_bf16 v[64:67], v[150:153], v[182:185], v[64:67]
	v_mfma_f32_16x16x32_bf16 v[60:63], v[158:161], v[182:185], v[60:63]
	v_mfma_f32_16x16x32_bf16 v[56:59], v[150:153], v[190:193], v[56:59]
	v_mfma_f32_16x16x32_bf16 v[48:51], v[158:161], v[190:193], v[48:51]
	v_mfma_f32_16x16x32_bf16 v[40:43], v[150:153], v[198:201], v[40:43]
	v_mfma_f32_16x16x32_bf16 v[32:35], v[158:161], v[198:201], v[32:35]
	v_mfma_f32_16x16x32_bf16 v[24:27], v[150:153], v[210:213], v[24:27]
	v_mfma_f32_16x16x32_bf16 v[16:19], v[158:161], v[210:213], v[16:19]
	v_mfma_f32_16x16x32_bf16 v[52:55], v[162:165], v[178:181], v[52:55]
	v_mfma_f32_16x16x32_bf16 v[44:47], v[170:173], v[178:181], v[44:47]
	v_mfma_f32_16x16x32_bf16 v[36:39], v[162:165], v[186:189], v[36:39]
	v_mfma_f32_16x16x32_bf16 v[28:31], v[170:173], v[186:189], v[28:31]
	v_mfma_f32_16x16x32_bf16 v[20:23], v[162:165], v[194:197], v[20:23]
	v_mfma_f32_16x16x32_bf16 v[12:15], v[170:173], v[194:197], v[12:15]
	v_mfma_f32_16x16x32_bf16 v[8:11], v[162:165], v[202:205], v[8:11]
	v_mfma_f32_16x16x32_bf16 v[4:7], v[170:173], v[202:205], v[4:7]
	v_mfma_f32_16x16x32_bf16 v[52:55], v[166:169], v[182:185], v[52:55]
	v_mfma_f32_16x16x32_bf16 v[44:47], v[174:177], v[182:185], v[44:47]
	v_mfma_f32_16x16x32_bf16 v[36:39], v[166:169], v[190:193], v[36:39]
	v_mfma_f32_16x16x32_bf16 v[28:31], v[174:177], v[190:193], v[28:31]
	v_mfma_f32_16x16x32_bf16 v[20:23], v[166:169], v[198:201], v[20:23]
	v_mfma_f32_16x16x32_bf16 v[12:15], v[174:177], v[198:201], v[12:15]
	v_mfma_f32_16x16x32_bf16 v[8:11], v[166:169], v[210:213], v[8:11]
	v_mfma_f32_16x16x32_bf16 v[4:7], v[174:177], v[210:213], v[4:7]
	s_barrier
	s_add_i32 s56, s56, 2
	s_add_u32 s42, s42, 0x100
	s_addc_u32 s43, s43, 0
	s_add_u32 s54, s54, 0x100
	s_addc_u32 s55, s55, 0
	s_cmp_gt_u32 s56, 29
	s_cbranch_scc0 .LBB0_514
; __device__ __forceinline__ unsigned cvt_pk_bf16(float lo, float hi) { unsigned r; asm volatile("v_cvt_pk_bf16_f32 %0, %1, %2" : "=v"(r) : "v"(lo), "v"(hi)); return r; }
;     __device__ __forceinline__ void operator()(const f32x4 (&acc)[2][2][4][2], const Unit& u, int wr, int wc, int fr, int fq) const {
;         const int row0 = u.pm * BM + wr * 64 + fr; const int col0 = u.pn * BM + wc * 32 + 8 * fq;
; #pragma unroll
;         for (int ai = 0; ai < 2; ++ai)
; #pragma unroll
;             for (int m = 0; m < 4; ++m) { bf16_t* rowp = O + (size_t)(row0 + ai * HALF + m * 16) * ldc + col0;
; #pragma unroll
;                 for (int bj = 0; bj < 2; ++bj) { const f32x4 v0 = acc[ai][bj][m][0], v1 = acc[ai][bj][m][1];
;                     u32x4 w; w.x = cvt_pk_bf16(v0[0], v0[1]); w.y = cvt_pk_bf16(v0[2], v0[3]); w.z = cvt_pk_bf16(v1[0], v1[1]); w.w = cvt_pk_bf16(v1[2], v1[3]);
;                     *(u32x4*)(rowp + bj * HALF) = w; } }
	v_lshl_or_b32 v144, s10, 8, v148
	v_lshl_add_u32 v152, s6, 8, v146
	v_ashrrev_i32_e32 v145, 31, v144
	v_mov_b64_e32 v[142:143], s[0:1]
	s_movk_i32 s3, 0x3200
	v_mad_i64_i32 v[150:151], s[42:43], v152, s3, v[142:143]
	v_lshlrev_b64 v[144:145], 1, v[144:145]
	v_lshl_add_u64 v[150:151], v[150:151], 0, v[144:145]
	v_cvt_pk_bf16_f32 v128, v128, v129
	v_cvt_pk_bf16_f32 v129, v130, v131
	v_cvt_pk_bf16_f32 v130, v124, v125
	v_cvt_pk_bf16_f32 v131, v126, v127
	global_store_dwordx4 v[150:151], v[128:131], off
	v_cvt_pk_bf16_f32 v116, v116, v117
	v_cvt_pk_bf16_f32 v117, v118, v119
	v_cvt_pk_bf16_f32 v118, v108, v109
	v_or_b32_e32 v108, 16, v152
	v_mad_i64_i32 v[108:109], s[42:43], v108, s3, v[142:143]
	v_cvt_pk_bf16_f32 v119, v110, v111
	global_store_dwordx4 v[150:151], v[116:119], off offset:256
	s_and_b64 vcc, exec, s[4:5]
	s_mov_b32 s10, s22
	v_lshl_add_u64 v[116:117], v[108:109], 0, v[144:145]
	v_cvt_pk_bf16_f32 v108, v120, v121
	v_cvt_pk_bf16_f32 v109, v122, v123
	v_cvt_pk_bf16_f32 v110, v112, v113
	v_cvt_pk_bf16_f32 v111, v114, v115
	global_store_dwordx4 v[116:117], v[108:111], off
	v_cvt_pk_bf16_f32 v100, v100, v101
	v_cvt_pk_bf16_f32 v101, v102, v103
	v_cvt_pk_bf16_f32 v102, v92, v93
	v_or_b32_e32 v92, 32, v152
	v_mad_i64_i32 v[92:93], s[42:43], v92, s3, v[142:143]
	v_cvt_pk_bf16_f32 v103, v94, v95
	global_store_dwordx4 v[116:117], v[100:103], off offset:256
	s_mov_b32 s6, s12
	s_mov_b64 s[44:45], s[40:41]
	v_lshl_add_u64 v[100:101], v[92:93], 0, v[144:145]
	v_cvt_pk_bf16_f32 v92, v104, v105
	v_cvt_pk_bf16_f32 v93, v106, v107
	v_cvt_pk_bf16_f32 v94, v96, v97
	v_cvt_pk_bf16_f32 v95, v98, v99
	global_store_dwordx4 v[100:101], v[92:95], off
	v_cvt_pk_bf16_f32 v84, v84, v85
	v_cvt_pk_bf16_f32 v85, v86, v87
	v_cvt_pk_bf16_f32 v86, v76, v77
	v_or_b32_e32 v76, 48, v152
	v_mad_i64_i32 v[76:77], s[42:43], v76, s3, v[142:143]
	v_cvt_pk_bf16_f32 v87, v78, v79
	global_store_dwordx4 v[100:101], v[84:87], off offset:256
	s_nop 1
	v_lshl_add_u64 v[84:85], v[76:77], 0, v[144:145]
	v_cvt_pk_bf16_f32 v76, v88, v89
	v_cvt_pk_bf16_f32 v77, v90, v91
	v_cvt_pk_bf16_f32 v78, v80, v81
	v_cvt_pk_bf16_f32 v79, v82, v83
	global_store_dwordx4 v[84:85], v[76:79], off
	v_cvt_pk_bf16_f32 v72, v72, v73
	v_cvt_pk_bf16_f32 v73, v74, v75
	v_cvt_pk_bf16_f32 v74, v68, v69
	v_add_u32_e32 v68, 0x80, v152
	v_mad_i64_i32 v[68:69], s[42:43], v68, s3, v[142:143]
	v_lshl_add_u64 v[68:69], v[68:69], 0, v[144:145]
	v_cvt_pk_bf16_f32 v75, v70, v71
	global_store_dwordx4 v[84:85], v[72:75], off offset:256
	v_cvt_pk_bf16_f32 v64, v64, v65
	v_cvt_pk_bf16_f32 v65, v66, v67
	v_cvt_pk_bf16_f32 v66, v60, v61
	v_cvt_pk_bf16_f32 v67, v62, v63
	global_store_dwordx4 v[68:69], v[64:67], off
	v_cvt_pk_bf16_f32 v52, v52, v53
	v_cvt_pk_bf16_f32 v53, v54, v55
	v_cvt_pk_bf16_f32 v54, v44, v45
	v_add_u32_e32 v44, 0x90, v152
	v_mad_i64_i32 v[44:45], s[42:43], v44, s3, v[142:143]
	v_cvt_pk_bf16_f32 v55, v46, v47
	global_store_dwordx4 v[68:69], v[52:55], off offset:256
	s_nop 1
	v_lshl_add_u64 v[52:53], v[44:45], 0, v[144:145]
	v_cvt_pk_bf16_f32 v44, v56, v57
	v_cvt_pk_bf16_f32 v45, v58, v59
	v_cvt_pk_bf16_f32 v46, v48, v49
	v_cvt_pk_bf16_f32 v47, v50, v51
	global_store_dwordx4 v[52:53], v[44:47], off
	v_cvt_pk_bf16_f32 v36, v36, v37
	v_cvt_pk_bf16_f32 v37, v38, v39
	v_cvt_pk_bf16_f32 v38, v28, v29
	v_add_u32_e32 v28, 0xa0, v152
	v_mad_i64_i32 v[28:29], s[42:43], v28, s3, v[142:143]
	v_cvt_pk_bf16_f32 v39, v30, v31
	global_store_dwordx4 v[52:53], v[36:39], off offset:256
	s_nop 1
	v_lshl_add_u64 v[36:37], v[28:29], 0, v[144:145]
	v_cvt_pk_bf16_f32 v28, v40, v41
	v_cvt_pk_bf16_f32 v29, v42, v43
	v_cvt_pk_bf16_f32 v30, v32, v33
	v_cvt_pk_bf16_f32 v31, v34, v35
	global_store_dwordx4 v[36:37], v[28:31], off
	v_cvt_pk_bf16_f32 v20, v20, v21
	v_cvt_pk_bf16_f32 v21, v22, v23
	v_cvt_pk_bf16_f32 v22, v12, v13
	v_add_u32_e32 v12, 0xb0, v152
	v_mad_i64_i32 v[12:13], s[42:43], v12, s3, v[142:143]
	v_cvt_pk_bf16_f32 v23, v14, v15
	global_store_dwordx4 v[36:37], v[20:23], off offset:256
	s_mov_b64 s[42:43], s[38:39]
	s_nop 0
	v_lshl_add_u64 v[20:21], v[12:13], 0, v[144:145]
	v_cvt_pk_bf16_f32 v12, v24, v25
	v_cvt_pk_bf16_f32 v13, v26, v27
	v_cvt_pk_bf16_f32 v14, v16, v17
	v_cvt_pk_bf16_f32 v15, v18, v19
	global_store_dwordx4 v[20:21], v[12:15], off
	v_cvt_pk_bf16_f32 v8, v8, v9
	v_cvt_pk_bf16_f32 v9, v10, v11
	v_cvt_pk_bf16_f32 v10, v4, v5
	v_cvt_pk_bf16_f32 v11, v6, v7
	global_store_dwordx4 v[20:21], v[8:11], off offset:256
	s_cbranch_vccz .LBB0_507
	s_waitcnt vmcnt(0)
	s_cmpk_gt_u32 s8, 0xff
	s_cbranch_scc1 .LBB0_518
	s_barrier

; __device__ __forceinline__ unsigned pk2(float lo, float hi) { return pg8::pkc(lo, hi); }
; __device__ __forceinline__ void ph_g2(Frame& F) {
;     const int gt = F.vcu * NWAVES * 64 + F.tid, NGT = F.G * NWAVES * 64;
;     const bf16* UT = (const bf16*)(F.ws + WS_UT); bf16* ST = (bf16*)(F.ws + WS_ST); const float* AL = (const float*)(F.ws + WS_AL);
;     for (int it = gt; it < 64 * 128 * 16; it += NGT) {
;         const int chain = it >> 11, rem = it & 2047, dv = rem >> 4, dk4 = (rem & 15) * 4;
;         const int dir = chain & 1, h = (chain >> 1) & 7, b = chain >> 4;
;         float S0 = 0.f, S1 = 0.f, S2 = 0.f, S3 = 0.f;
;         const size_t base = (size_t)chain * 68 * 8192 + dv * 64 + dk4;
; #pragma unroll 34
;         for (int s = 0; s < 68; ++s) {
;             const v2u uw = *(const v2u*)(UT + base + (size_t)s * 8192);
;             const int rc = chain_slot_rc(b, dir, s);
;             const f32x4 a = *(const f32x4*)(AL + (size_t)(dir * NRC + rc) * 512 + 64 * h + dk4);
;             v2u o; if (dir) { o.x = pk2(S0 * a.x, S1 * a.y); o.y = pk2(S2 * a.z, S3 * a.w); } else { o.x = pk2(S0, S1); o.y = pk2(S2, S3); }
;             *(v2u*)(ST + base + (size_t)s * 8192) = o;
;             S0 = fmaf(a.x, S0, bflo(uw.x)); S1 = fmaf(a.y, S1, bfhi(uw.x)); S2 = fmaf(a.z, S2, bflo(uw.y)); S3 = fmaf(a.w, S3, bfhi(uw.y));
.LBB0_792:
	v_readfirstlane_b32 s0, v22
	v_and_b32_e32 v4, 0x7ff, v22
	v_and_b32_e32 v5, 15, v22
	v_lshlrev_b32_e32 v4, 3, v4
	v_lshlrev_b32_e32 v5, 4, v5
	s_lshr_b32 s1, s0, 11
	s_and_b32 s48, s1, 1
	s_bfe_u32 s49, s1, 0x30001
	s_lshr_b32 s4, s1, 4
	s_mul_i32 s5, s1, 0x110000
	s_add_u32 s8, s42, 0x39d90000
	s_addc_u32 s9, s43, 0
	s_add_u32 s8, s8, s5
	s_addc_u32 s9, s9, 0
	s_add_u32 s10, s42, 0x3e190000
	s_addc_u32 s11, s43, 0
	s_add_u32 s10, s10, s5
	s_addc_u32 s11, s11, 0
	s_mul_i32 s5, s48, 0x88000
	s_lshl_b32 s49, s49, 8
	s_add_i32 s5, s5, s49
	s_add_u32 s38, s42, 0x39c80000
	s_addc_u32 s39, s43, 0
	s_add_u32 s38, s38, s5
	s_addc_u32 s39, s39, 0
	v_mov_b32_e32 v8, 0
	v_mov_b32_e32 v9, 0
	v_mov_b32_e32 v10, 0
	v_mov_b32_e32 v11, 0
	s_cmp_eq_u32 s48, 0
	s_cbranch_scc0 .Lg2_dir1
	s_lshl_b32 s0, s4, 17
	s_add_u32 s40, s38, s0
	s_addc_u32 s41, s39, 0
	s_lshl_b32 s0, s4, 13
	s_add_i32 s0, s0, 0x80000
	s_add_u32 s38, s38, s0
	s_addc_u32 s39, s39, 0
	global_load_dwordx2 v[32:33], v4, s[8:9]
	global_load_dwordx4 v[34:37], v5, s[38:39]
	s_add_u32 s8, s8, 0x4000
	s_addc_u32 s9, s9, 0
	s_add_u32 s38, s38, 0x800
	s_addc_u32 s39, s39, 0
	global_load_dwordx2 v[38:39], v4, s[8:9]
	global_load_dwordx4 v[40:43], v5, s[38:39]
	s_add_u32 s8, s8, 0x4000
	s_addc_u32 s9, s9, 0
	s_add_u32 s38, s38, 0x800
	s_addc_u32 s39, s39, 0
	global_load_dwordx2 v[44:45], v4, s[8:9]
	global_load_dwordx4 v[46:49], v5, s[38:39]
	s_add_u32 s8, s8, 0x4000
	s_addc_u32 s9, s9, 0
	s_add_u32 s38, s38, 0x800
	s_addc_u32 s39, s39, 0
	global_load_dwordx2 v[50:51], v4, s[8:9]
	global_load_dwordx4 v[52:55], v5, s[38:39]
	s_add_u32 s8, s8, 0x4000
	s_addc_u32 s9, s9, 0
	s_add_u32 s38, s38, 0x800
	s_addc_u32 s39, s39, 0
	s_mov_b64 s[38:39], s[40:41]
	global_load_dwordx2 v[56:57], v4, s[8:9]
	global_load_dwordx4 v[58:61], v5, s[38:39]
	s_add_u32 s8, s8, 0x4000
	s_addc_u32 s9, s9, 0
	s_add_u32 s38, s38, 0x800
	s_addc_u32 s39, s39, 0
	global_load_dwordx2 v[62:63], v4, s[8:9]
	global_load_dwordx4 v[64:67], v5, s[38:39]
	s_add_u32 s8, s8, 0x4000
	s_addc_u32 s9, s9, 0
	s_add_u32 s38, s38, 0x800
	s_addc_u32 s39, s39, 0
	global_load_dwordx2 v[68:69], v4, s[8:9]
	global_load_dwordx4 v[70:73], v5, s[38:39]
	s_add_u32 s8, s8, 0x4000
	s_addc_u32 s9, s9, 0
	s_add_u32 s38, s38, 0x800
	s_addc_u32 s39, s39, 0
	global_load_dwordx2 v[74:75], v4, s[8:9]
	global_load_dwordx4 v[76:79], v5, s[38:39]
	s_add_u32 s8, s8, 0x4000
	s_addc_u32 s9, s9, 0
	s_add_u32 s38, s38, 0x800
	s_addc_u32 s39, s39, 0
	global_load_dwordx2 v[80:81], v4, s[8:9]
	global_load_dwordx4 v[82:85], v5, s[38:39]
	s_add_u32 s8, s8, 0x4000
	s_addc_u32 s9, s9, 0
	s_add_u32 s38, s38, 0x800
	s_addc_u32 s39, s39, 0
	global_load_dwordx2 v[86:87], v4, s[8:9]
	global_load_dwordx4 v[88:91], v5, s[38:39]
	s_add_u32 s8, s8, 0x4000
	s_addc_u32 s9, s9, 0
	s_add_u32 s38, s38, 0x800
	s_addc_u32 s39, s39, 0
	global_load_dwordx2 v[92:93], v4, s[8:9]
	global_load_dwordx4 v[94:97], v5, s[38:39]
	s_add_u32 s8, s8, 0x4000
	s_addc_u32 s9, s9, 0
	s_add_u32 s38, s38, 0x800
	s_addc_u32 s39, s39, 0
	global_load_dwordx2 v[98:99], v4, s[8:9]
	global_load_dwordx4 v[100:103], v5, s[38:39]
	s_add_u32 s8, s8, 0x4000
	s_addc_u32 s9, s9, 0
	s_add_u32 s38, s38, 0x800
	s_addc_u32 s39, s39, 0
	global_load_dwordx2 v[104:105], v4, s[8:9]
	global_load_dwordx4 v[106:109], v5, s[38:39]
	s_add_u32 s8, s8, 0x4000
	s_addc_u32 s9, s9, 0
	s_add_u32 s38, s38, 0x800
	s_addc_u32 s39, s39, 0
	global_load_dwordx2 v[110:111], v4, s[8:9]
	global_load_dwordx4 v[112:115], v5, s[38:39]
	s_add_u32 s8, s8, 0x4000
	s_addc_u32 s9, s9, 0
	s_add_u32 s38, s38, 0x800
	s_addc_u32 s39, s39, 0
	global_load_dwordx2 v[116:117], v4, s[8:9]
	global_load_dwordx4 v[118:121], v5, s[38:39]
	s_add_u32 s8, s8, 0x4000
	s_addc_u32 s9, s9, 0
	s_add_u32 s38, s38, 0x800
	s_addc_u32 s39, s39, 0
	global_load_dwordx2 v[122:123], v4, s[8:9]
	global_load_dwordx4 v[124:127], v5, s[38:39]
	s_add_u32 s8, s8, 0x4000
	s_addc_u32 s9, s9, 0
	s_add_u32 s38, s38, 0x800
	s_addc_u32 s39, s39, 0
	global_load_dwordx2 v[128:129], v4, s[8:9]
	global_load_dwordx4 v[130:133], v5, s[38:39]
	s_add_u32 s8, s8, 0x4000
	s_addc_u32 s9, s9, 0
	s_add_u32 s38, s38, 0x800
	s_addc_u32 s39, s39, 0
	s_waitcnt vmcnt(32)
	v_cvt_pk_bf16_f32 v16, v8, v9
	v_cvt_pk_bf16_f32 v17, v10, v11
	global_store_dwordx2 v4, v[16:17], s[10:11]
	s_add_u32 s10, s10, 0x4000
	s_addc_u32 s11, s11, 0
	v_lshlrev_b32_e32 v12, 16, v32
	v_and_b32_e32 v13, 0xffff0000, v32
	v_lshlrev_b32_e32 v14, 16, v33
	v_and_b32_e32 v15, 0xffff0000, v33
	v_pk_fma_f32 v[8:9], v[34:35], v[8:9], v[12:13]
	v_pk_fma_f32 v[10:11], v[36:37], v[10:11], v[14:15]
	global_load_dwordx2 v[32:33], v4, s[8:9]
	global_load_dwordx4 v[34:37], v5, s[38:39]
	s_add_u32 s8, s8, 0x4000
	s_addc_u32 s9, s9, 0
	s_add_u32 s38, s38, 0x800
	s_addc_u32 s39, s39, 0
	s_waitcnt vmcnt(33)
	v_cvt_pk_bf16_f32 v18, v8, v9
	v_cvt_pk_bf16_f32 v19, v10, v11
	global_store_dwordx2 v4, v[18:19], s[10:11]
	s_add_u32 s10, s10, 0x4000
	s_addc_u32 s11, s11, 0
	v_lshlrev_b32_e32 v12, 16, v38
	v_and_b32_e32 v13, 0xffff0000, v38
	v_lshlrev_b32_e32 v14, 16, v39
	v_and_b32_e32 v15, 0xffff0000, v39
	v_pk_fma_f32 v[8:9], v[40:41], v[8:9], v[12:13]
	v_pk_fma_f32 v[10:11], v[42:43], v[10:11], v[14:15]
	global_load_dwordx2 v[38:39], v4, s[8:9]
	global_load_dwordx4 v[40:43], v5, s[38:39]
	s_add_u32 s8, s8, 0x4000
	s_addc_u32 s9, s9, 0
	s_add_u32 s38, s38, 0x800
	s_addc_u32 s39, s39, 0
	s_waitcnt vmcnt(34)
; __device__ __forceinline__ unsigned pk2(float lo, float hi) { return pg8::pkc(lo, hi); }
; __device__ __forceinline__ void ph_g2(Frame& F) {
;     ...
;         for (int s = 0; s < 68; ++s) {
;             const v2u uw = *(const v2u*)(UT + base + (size_t)s * 8192);
;             const int rc = chain_slot_rc(b, dir, s);
;             const f32x4 a = *(const f32x4*)(AL + (size_t)(dir * NRC + rc) * 512 + 64 * h + dk4);
;             v2u o; if (dir) { o.x = pk2(S0 * a.x, S1 * a.y); o.y = pk2(S2 * a.z, S3 * a.w); } else { o.x = pk2(S0, S1); o.y = pk2(S2, S3); }
;             *(v2u*)(ST + base + (size_t)s * 8192) = o;
;             S0 = fmaf(a.x, S0, bflo(uw.x)); S1 = fmaf(a.y, S1, bfhi(uw.x)); S2 = fmaf(a.z, S2, bflo(uw.y)); S3 = fmaf(a.w, S3, bfhi(uw.y));
	v_cvt_pk_bf16_f32 v20, v8, v9
	v_cvt_pk_bf16_f32 v21, v10, v11
	global_store_dwordx2 v4, v[20:21], s[10:11]
	s_add_u32 s10, s10, 0x4000
	s_addc_u32 s11, s11, 0
	v_lshlrev_b32_e32 v12, 16, v44
	v_and_b32_e32 v13, 0xffff0000, v44
	v_lshlrev_b32_e32 v14, 16, v45
	v_and_b32_e32 v15, 0xffff0000, v45
	v_pk_fma_f32 v[8:9], v[46:47], v[8:9], v[12:13]
	v_pk_fma_f32 v[10:11], v[48:49], v[10:11], v[14:15]
	global_load_dwordx2 v[44:45], v4, s[8:9]
	global_load_dwordx4 v[46:49], v5, s[38:39]
	s_add_u32 s8, s8, 0x4000
	s_addc_u32 s9, s9, 0
	s_add_u32 s38, s38, 0x800
	s_addc_u32 s39, s39, 0
	s_waitcnt vmcnt(35)
	v_cvt_pk_bf16_f32 v24, v8, v9
	v_cvt_pk_bf16_f32 v25, v10, v11
	global_store_dwordx2 v4, v[24:25], s[10:11]
	s_add_u32 s10, s10, 0x4000
	s_addc_u32 s11, s11, 0
	v_lshlrev_b32_e32 v12, 16, v50
	v_and_b32_e32 v13, 0xffff0000, v50
	v_lshlrev_b32_e32 v14, 16, v51
	v_and_b32_e32 v15, 0xffff0000, v51
	v_pk_fma_f32 v[8:9], v[52:53], v[8:9], v[12:13]
	v_pk_fma_f32 v[10:11], v[54:55], v[10:11], v[14:15]
	global_load_dwordx2 v[50:51], v4, s[8:9]
	global_load_dwordx4 v[52:55], v5, s[38:39]
	s_add_u32 s8, s8, 0x4000
	s_addc_u32 s9, s9, 0
	s_add_u32 s38, s38, 0x800
	s_addc_u32 s39, s39, 0
	s_waitcnt vmcnt(36)
	v_cvt_pk_bf16_f32 v16, v8, v9
	v_cvt_pk_bf16_f32 v17, v10, v11
	global_store_dwordx2 v4, v[16:17], s[10:11]
	s_add_u32 s10, s10, 0x4000
	s_addc_u32 s11, s11, 0
	v_lshlrev_b32_e32 v12, 16, v56
	v_and_b32_e32 v13, 0xffff0000, v56
	v_lshlrev_b32_e32 v14, 16, v57
	v_and_b32_e32 v15, 0xffff0000, v57
	v_pk_fma_f32 v[8:9], v[58:59], v[8:9], v[12:13]
	v_pk_fma_f32 v[10:11], v[60:61], v[10:11], v[14:15]
	global_load_dwordx2 v[56:57], v4, s[8:9]
	global_load_dwordx4 v[58:61], v5, s[38:39]
	s_add_u32 s8, s8, 0x4000
	s_addc_u32 s9, s9, 0
	s_add_u32 s38, s38, 0x800
	s_addc_u32 s39, s39, 0
	s_waitcnt vmcnt(37)
	v_cvt_pk_bf16_f32 v18, v8, v9
	v_cvt_pk_bf16_f32 v19, v10, v11
	global_store_dwordx2 v4, v[18:19], s[10:11]
	s_add_u32 s10, s10, 0x4000
	s_addc_u32 s11, s11, 0
	v_lshlrev_b32_e32 v12, 16, v62
	v_and_b32_e32 v13, 0xffff0000, v62
	v_lshlrev_b32_e32 v14, 16, v63
	v_and_b32_e32 v15, 0xffff0000, v63
	v_pk_fma_f32 v[8:9], v[64:65], v[8:9], v[12:13]
	v_pk_fma_f32 v[10:11], v[66:67], v[10:11], v[14:15]
	global_load_dwordx2 v[62:63], v4, s[8:9]
	global_load_dwordx4 v[64:67], v5, s[38:39]
	s_add_u32 s8, s8, 0x4000
	s_addc_u32 s9, s9, 0
	s_add_u32 s38, s38, 0x800
	s_addc_u32 s39, s39, 0
	s_waitcnt vmcnt(38)
	v_cvt_pk_bf16_f32 v20, v8, v9
	v_cvt_pk_bf16_f32 v21, v10, v11
	global_store_dwordx2 v4, v[20:21], s[10:11]
	s_add_u32 s10, s10, 0x4000
	s_addc_u32 s11, s11, 0
	v_lshlrev_b32_e32 v12, 16, v68
	v_and_b32_e32 v13, 0xffff0000, v68
	v_lshlrev_b32_e32 v14, 16, v69
	v_and_b32_e32 v15, 0xffff0000, v69
	v_pk_fma_f32 v[8:9], v[70:71], v[8:9], v[12:13]
	v_pk_fma_f32 v[10:11], v[72:73], v[10:11], v[14:15]
	global_load_dwordx2 v[68:69], v4, s[8:9]
	global_load_dwordx4 v[70:73], v5, s[38:39]
	s_add_u32 s8, s8, 0x4000
	s_addc_u32 s9, s9, 0
	s_add_u32 s38, s38, 0x800
	s_addc_u32 s39, s39, 0
	s_waitcnt vmcnt(39)
	v_cvt_pk_bf16_f32 v24, v8, v9
	v_cvt_pk_bf16_f32 v25, v10, v11
	global_store_dwordx2 v4, v[24:25], s[10:11]
	s_add_u32 s10, s10, 0x4000
	s_addc_u32 s11, s11, 0
	v_lshlrev_b32_e32 v12, 16, v74
	v_and_b32_e32 v13, 0xffff0000, v74
	v_lshlrev_b32_e32 v14, 16, v75
	v_and_b32_e32 v15, 0xffff0000, v75
	v_pk_fma_f32 v[8:9], v[76:77], v[8:9], v[12:13]
	v_pk_fma_f32 v[10:11], v[78:79], v[10:11], v[14:15]
	global_load_dwordx2 v[74:75], v4, s[8:9]
	global_load_dwordx4 v[76:79], v5, s[38:39]
	s_add_u32 s8, s8, 0x4000
	s_addc_u32 s9, s9, 0
	s_add_u32 s38, s38, 0x800
	s_addc_u32 s39, s39, 0
	s_waitcnt vmcnt(40)
	v_cvt_pk_bf16_f32 v16, v8, v9
	v_cvt_pk_bf16_f32 v17, v10, v11
	global_store_dwordx2 v4, v[16:17], s[10:11]
	s_add_u32 s10, s10, 0x4000
	s_addc_u32 s11, s11, 0
	v_lshlrev_b32_e32 v12, 16, v80
	v_and_b32_e32 v13, 0xffff0000, v80
	v_lshlrev_b32_e32 v14, 16, v81
	v_and_b32_e32 v15, 0xffff0000, v81
	v_pk_fma_f32 v[8:9], v[82:83], v[8:9], v[12:13]
	v_pk_fma_f32 v[10:11], v[84:85], v[10:11], v[14:15]
	global_load_dwordx2 v[80:81], v4, s[8:9]
	global_load_dwordx4 v[82:85], v5, s[38:39]
	s_add_u32 s8, s8, 0x4000
	s_addc_u32 s9, s9, 0
	s_add_u32 s38, s38, 0x800
	s_addc_u32 s39, s39, 0
	s_waitcnt vmcnt(41)
	v_cvt_pk_bf16_f32 v18, v8, v9
	v_cvt_pk_bf16_f32 v19, v10, v11
	global_store_dwordx2 v4, v[18:19], s[10:11]
	s_add_u32 s10, s10, 0x4000
	s_addc_u32 s11, s11, 0
	v_lshlrev_b32_e32 v12, 16, v86
	v_and_b32_e32 v13, 0xffff0000, v86
	v_lshlrev_b32_e32 v14, 16, v87
	v_and_b32_e32 v15, 0xffff0000, v87
	v_pk_fma_f32 v[8:9], v[88:89], v[8:9], v[12:13]
	v_pk_fma_f32 v[10:11], v[90:91], v[10:11], v[14:15]
	global_load_dwordx2 v[86:87], v4, s[8:9]
	global_load_dwordx4 v[88:91], v5, s[38:39]
	s_add_u32 s8, s8, 0x4000
	s_addc_u32 s9, s9, 0
	s_add_u32 s38, s38, 0x800
	s_addc_u32 s39, s39, 0
	s_waitcnt vmcnt(42)
	v_cvt_pk_bf16_f32 v20, v8, v9
	v_cvt_pk_bf16_f32 v21, v10, v11
	global_store_dwordx2 v4, v[20:21], s[10:11]
	s_add_u32 s10, s10, 0x4000
	s_addc_u32 s11, s11, 0
	v_lshlrev_b32_e32 v12, 16, v92
	v_and_b32_e32 v13, 0xffff0000, v92
	v_lshlrev_b32_e32 v14, 16, v93
	v_and_b32_e32 v15, 0xffff0000, v93
	v_pk_fma_f32 v[8:9], v[94:95], v[8:9], v[12:13]
	v_pk_fma_f32 v[10:11], v[96:97], v[10:11], v[14:15]
	global_load_dwordx2 v[92:93], v4, s[8:9]
	global_load_dwordx4 v[94:97], v5, s[38:39]
	s_add_u32 s8, s8, 0x4000
	s_addc_u32 s9, s9, 0
	s_add_u32 s38, s38, 0x800
	s_addc_u32 s39, s39, 0
	s_waitcnt vmcnt(43)
; __device__ __forceinline__ unsigned pk2(float lo, float hi) { return pg8::pkc(lo, hi); }
; __device__ __forceinline__ void ph_g2(Frame& F) {
;     ...
;         for (int s = 0; s < 68; ++s) {
;             const v2u uw = *(const v2u*)(UT + base + (size_t)s * 8192);
;             const int rc = chain_slot_rc(b, dir, s);
;             const f32x4 a = *(const f32x4*)(AL + (size_t)(dir * NRC + rc) * 512 + 64 * h + dk4);
;             v2u o; if (dir) { o.x = pk2(S0 * a.x, S1 * a.y); o.y = pk2(S2 * a.z, S3 * a.w); } else { o.x = pk2(S0, S1); o.y = pk2(S2, S3); }
;             *(v2u*)(ST + base + (size_t)s * 8192) = o;
;             S0 = fmaf(a.x, S0, bflo(uw.x)); S1 = fmaf(a.y, S1, bfhi(uw.x)); S2 = fmaf(a.z, S2, bflo(uw.y)); S3 = fmaf(a.w, S3, bfhi(uw.y));
	v_cvt_pk_bf16_f32 v24, v8, v9
	v_cvt_pk_bf16_f32 v25, v10, v11
	global_store_dwordx2 v4, v[24:25], s[10:11]
	s_add_u32 s10, s10, 0x4000
	s_addc_u32 s11, s11, 0
	v_lshlrev_b32_e32 v12, 16, v98
	v_and_b32_e32 v13, 0xffff0000, v98
	v_lshlrev_b32_e32 v14, 16, v99
	v_and_b32_e32 v15, 0xffff0000, v99
	v_pk_fma_f32 v[8:9], v[100:101], v[8:9], v[12:13]
	v_pk_fma_f32 v[10:11], v[102:103], v[10:11], v[14:15]
	global_load_dwordx2 v[98:99], v4, s[8:9]
	global_load_dwordx4 v[100:103], v5, s[38:39]
	s_add_u32 s8, s8, 0x4000
	s_addc_u32 s9, s9, 0
	s_add_u32 s38, s38, 0x800
	s_addc_u32 s39, s39, 0
	s_waitcnt vmcnt(44)
	v_cvt_pk_bf16_f32 v16, v8, v9
	v_cvt_pk_bf16_f32 v17, v10, v11
	global_store_dwordx2 v4, v[16:17], s[10:11]
	s_add_u32 s10, s10, 0x4000
	s_addc_u32 s11, s11, 0
	v_lshlrev_b32_e32 v12, 16, v104
	v_and_b32_e32 v13, 0xffff0000, v104
	v_lshlrev_b32_e32 v14, 16, v105
	v_and_b32_e32 v15, 0xffff0000, v105
	v_pk_fma_f32 v[8:9], v[106:107], v[8:9], v[12:13]
	v_pk_fma_f32 v[10:11], v[108:109], v[10:11], v[14:15]
	global_load_dwordx2 v[104:105], v4, s[8:9]
	global_load_dwordx4 v[106:109], v5, s[38:39]
	s_add_u32 s8, s8, 0x4000
	s_addc_u32 s9, s9, 0
	s_add_u32 s38, s38, 0x800
	s_addc_u32 s39, s39, 0
	s_waitcnt vmcnt(45)
	v_cvt_pk_bf16_f32 v18, v8, v9
	v_cvt_pk_bf16_f32 v19, v10, v11
	global_store_dwordx2 v4, v[18:19], s[10:11]
	s_add_u32 s10, s10, 0x4000
	s_addc_u32 s11, s11, 0
	v_lshlrev_b32_e32 v12, 16, v110
	v_and_b32_e32 v13, 0xffff0000, v110
	v_lshlrev_b32_e32 v14, 16, v111
	v_and_b32_e32 v15, 0xffff0000, v111
	v_pk_fma_f32 v[8:9], v[112:113], v[8:9], v[12:13]
	v_pk_fma_f32 v[10:11], v[114:115], v[10:11], v[14:15]
	global_load_dwordx2 v[110:111], v4, s[8:9]
	global_load_dwordx4 v[112:115], v5, s[38:39]
	s_add_u32 s8, s8, 0x4000
	s_addc_u32 s9, s9, 0
	s_add_u32 s38, s38, 0x800
	s_addc_u32 s39, s39, 0
	s_waitcnt vmcnt(46)
	v_cvt_pk_bf16_f32 v20, v8, v9
	v_cvt_pk_bf16_f32 v21, v10, v11
	global_store_dwordx2 v4, v[20:21], s[10:11]
	s_add_u32 s10, s10, 0x4000
	s_addc_u32 s11, s11, 0
	v_lshlrev_b32_e32 v12, 16, v116
	v_and_b32_e32 v13, 0xffff0000, v116
	v_lshlrev_b32_e32 v14, 16, v117
	v_and_b32_e32 v15, 0xffff0000, v117
	v_pk_fma_f32 v[8:9], v[118:119], v[8:9], v[12:13]
	v_pk_fma_f32 v[10:11], v[120:121], v[10:11], v[14:15]
	global_load_dwordx2 v[116:117], v4, s[8:9]
	global_load_dwordx4 v[118:121], v5, s[38:39]
	s_add_u32 s8, s8, 0x4000
	s_addc_u32 s9, s9, 0
	s_add_u32 s38, s38, 0x800
	s_addc_u32 s39, s39, 0
	s_waitcnt vmcnt(47)
	v_cvt_pk_bf16_f32 v24, v8, v9
	v_cvt_pk_bf16_f32 v25, v10, v11
	global_store_dwordx2 v4, v[24:25], s[10:11]
	s_add_u32 s10, s10, 0x4000
	s_addc_u32 s11, s11, 0
	v_lshlrev_b32_e32 v12, 16, v122
	v_and_b32_e32 v13, 0xffff0000, v122
	v_lshlrev_b32_e32 v14, 16, v123
	v_and_b32_e32 v15, 0xffff0000, v123
	v_pk_fma_f32 v[8:9], v[124:125], v[8:9], v[12:13]
	v_pk_fma_f32 v[10:11], v[126:127], v[10:11], v[14:15]
	global_load_dwordx2 v[122:123], v4, s[8:9]
	global_load_dwordx4 v[124:127], v5, s[38:39]
	s_add_u32 s8, s8, 0x4000
	s_addc_u32 s9, s9, 0
	s_add_u32 s38, s38, 0x800
	s_addc_u32 s39, s39, 0
	s_waitcnt vmcnt(48)
	v_cvt_pk_bf16_f32 v16, v8, v9
	v_cvt_pk_bf16_f32 v17, v10, v11
	global_store_dwordx2 v4, v[16:17], s[10:11]
	s_add_u32 s10, s10, 0x4000
	s_addc_u32 s11, s11, 0
	v_lshlrev_b32_e32 v12, 16, v128
	v_and_b32_e32 v13, 0xffff0000, v128
	v_lshlrev_b32_e32 v14, 16, v129
	v_and_b32_e32 v15, 0xffff0000, v129
	v_pk_fma_f32 v[8:9], v[130:131], v[8:9], v[12:13]
	v_pk_fma_f32 v[10:11], v[132:133], v[10:11], v[14:15]
	global_load_dwordx2 v[128:129], v4, s[8:9]
	global_load_dwordx4 v[130:133], v5, s[38:39]
	s_add_u32 s8, s8, 0x4000
	s_addc_u32 s9, s9, 0
	s_add_u32 s38, s38, 0x800
	s_addc_u32 s39, s39, 0
	s_waitcnt vmcnt(48)
	v_cvt_pk_bf16_f32 v18, v8, v9
	v_cvt_pk_bf16_f32 v19, v10, v11
	global_store_dwordx2 v4, v[18:19], s[10:11]
	s_add_u32 s10, s10, 0x4000
	s_addc_u32 s11, s11, 0
	v_lshlrev_b32_e32 v12, 16, v32
	v_and_b32_e32 v13, 0xffff0000, v32
	v_lshlrev_b32_e32 v14, 16, v33
	v_and_b32_e32 v15, 0xffff0000, v33
	v_pk_fma_f32 v[8:9], v[34:35], v[8:9], v[12:13]
	v_pk_fma_f32 v[10:11], v[36:37], v[10:11], v[14:15]
	global_load_dwordx2 v[32:33], v4, s[8:9]
	global_load_dwordx4 v[34:37], v5, s[38:39]
	s_add_u32 s8, s8, 0x4000
	s_addc_u32 s9, s9, 0
	s_add_u32 s38, s38, 0x800
	s_addc_u32 s39, s39, 0
	s_waitcnt vmcnt(48)
	v_cvt_pk_bf16_f32 v20, v8, v9
	v_cvt_pk_bf16_f32 v21, v10, v11
	global_store_dwordx2 v4, v[20:21], s[10:11]
	s_add_u32 s10, s10, 0x4000
	s_addc_u32 s11, s11, 0
	v_lshlrev_b32_e32 v12, 16, v38
	v_and_b32_e32 v13, 0xffff0000, v38
	v_lshlrev_b32_e32 v14, 16, v39
	v_and_b32_e32 v15, 0xffff0000, v39
	v_pk_fma_f32 v[8:9], v[40:41], v[8:9], v[12:13]
	v_pk_fma_f32 v[10:11], v[42:43], v[10:11], v[14:15]
	global_load_dwordx2 v[38:39], v4, s[8:9]
	global_load_dwordx4 v[40:43], v5, s[38:39]
	s_add_u32 s8, s8, 0x4000
	s_addc_u32 s9, s9, 0
	s_add_u32 s38, s38, 0x800
	s_addc_u32 s39, s39, 0
	s_waitcnt vmcnt(48)
	v_cvt_pk_bf16_f32 v24, v8, v9
	v_cvt_pk_bf16_f32 v25, v10, v11
	global_store_dwordx2 v4, v[24:25], s[10:11]
	s_add_u32 s10, s10, 0x4000
	s_addc_u32 s11, s11, 0
	v_lshlrev_b32_e32 v12, 16, v44
	v_and_b32_e32 v13, 0xffff0000, v44
	v_lshlrev_b32_e32 v14, 16, v45
	v_and_b32_e32 v15, 0xffff0000, v45
	v_pk_fma_f32 v[8:9], v[46:47], v[8:9], v[12:13]
	v_pk_fma_f32 v[10:11], v[48:49], v[10:11], v[14:15]
	global_load_dwordx2 v[44:45], v4, s[8:9]
	global_load_dwordx4 v[46:49], v5, s[38:39]
	s_add_u32 s8, s8, 0x4000
	s_addc_u32 s9, s9, 0
	s_add_u32 s38, s38, 0x800
	s_addc_u32 s39, s39, 0
	s_waitcnt vmcnt(48)
; __device__ __forceinline__ unsigned pk2(float lo, float hi) { return pg8::pkc(lo, hi); }
; __device__ __forceinline__ void ph_g2(Frame& F) {
;     ...
;         for (int s = 0; s < 68; ++s) {
;             const v2u uw = *(const v2u*)(UT + base + (size_t)s * 8192);
;             const int rc = chain_slot_rc(b, dir, s);
;             const f32x4 a = *(const f32x4*)(AL + (size_t)(dir * NRC + rc) * 512 + 64 * h + dk4);
;             v2u o; if (dir) { o.x = pk2(S0 * a.x, S1 * a.y); o.y = pk2(S2 * a.z, S3 * a.w); } else { o.x = pk2(S0, S1); o.y = pk2(S2, S3); }
;             *(v2u*)(ST + base + (size_t)s * 8192) = o;
;             S0 = fmaf(a.x, S0, bflo(uw.x)); S1 = fmaf(a.y, S1, bfhi(uw.x)); S2 = fmaf(a.z, S2, bflo(uw.y)); S3 = fmaf(a.w, S3, bfhi(uw.y));
	v_cvt_pk_bf16_f32 v16, v8, v9
	v_cvt_pk_bf16_f32 v17, v10, v11
	global_store_dwordx2 v4, v[16:17], s[10:11]
	s_add_u32 s10, s10, 0x4000
	s_addc_u32 s11, s11, 0
	v_lshlrev_b32_e32 v12, 16, v50
	v_and_b32_e32 v13, 0xffff0000, v50
	v_lshlrev_b32_e32 v14, 16, v51
	v_and_b32_e32 v15, 0xffff0000, v51
	v_pk_fma_f32 v[8:9], v[52:53], v[8:9], v[12:13]
	v_pk_fma_f32 v[10:11], v[54:55], v[10:11], v[14:15]
	global_load_dwordx2 v[50:51], v4, s[8:9]
	global_load_dwordx4 v[52:55], v5, s[38:39]
	s_add_u32 s8, s8, 0x4000
	s_addc_u32 s9, s9, 0
	s_add_u32 s38, s38, 0x800
	s_addc_u32 s39, s39, 0
	s_waitcnt vmcnt(48)
	v_cvt_pk_bf16_f32 v18, v8, v9
	v_cvt_pk_bf16_f32 v19, v10, v11
	global_store_dwordx2 v4, v[18:19], s[10:11]
	s_add_u32 s10, s10, 0x4000
	s_addc_u32 s11, s11, 0
	v_lshlrev_b32_e32 v12, 16, v56
	v_and_b32_e32 v13, 0xffff0000, v56
	v_lshlrev_b32_e32 v14, 16, v57
	v_and_b32_e32 v15, 0xffff0000, v57
	v_pk_fma_f32 v[8:9], v[58:59], v[8:9], v[12:13]
	v_pk_fma_f32 v[10:11], v[60:61], v[10:11], v[14:15]
	global_load_dwordx2 v[56:57], v4, s[8:9]
	global_load_dwordx4 v[58:61], v5, s[38:39]
	s_add_u32 s8, s8, 0x4000
	s_addc_u32 s9, s9, 0
	s_add_u32 s38, s38, 0x800
	s_addc_u32 s39, s39, 0
	s_waitcnt vmcnt(48)
	v_cvt_pk_bf16_f32 v20, v8, v9
	v_cvt_pk_bf16_f32 v21, v10, v11
	global_store_dwordx2 v4, v[20:21], s[10:11]
	s_add_u32 s10, s10, 0x4000
	s_addc_u32 s11, s11, 0
	v_lshlrev_b32_e32 v12, 16, v62
	v_and_b32_e32 v13, 0xffff0000, v62
	v_lshlrev_b32_e32 v14, 16, v63
	v_and_b32_e32 v15, 0xffff0000, v63
	v_pk_fma_f32 v[8:9], v[64:65], v[8:9], v[12:13]
	v_pk_fma_f32 v[10:11], v[66:67], v[10:11], v[14:15]
	global_load_dwordx2 v[62:63], v4, s[8:9]
	global_load_dwordx4 v[64:67], v5, s[38:39]
	s_add_u32 s8, s8, 0x4000
	s_addc_u32 s9, s9, 0
	s_add_u32 s38, s38, 0x800
	s_addc_u32 s39, s39, 0
	s_waitcnt vmcnt(48)
	v_cvt_pk_bf16_f32 v24, v8, v9
	v_cvt_pk_bf16_f32 v25, v10, v11
	global_store_dwordx2 v4, v[24:25], s[10:11]
	s_add_u32 s10, s10, 0x4000
	s_addc_u32 s11, s11, 0
	v_lshlrev_b32_e32 v12, 16, v68
	v_and_b32_e32 v13, 0xffff0000, v68
	v_lshlrev_b32_e32 v14, 16, v69
	v_and_b32_e32 v15, 0xffff0000, v69
	v_pk_fma_f32 v[8:9], v[70:71], v[8:9], v[12:13]
	v_pk_fma_f32 v[10:11], v[72:73], v[10:11], v[14:15]
	global_load_dwordx2 v[68:69], v4, s[8:9]
	global_load_dwordx4 v[70:73], v5, s[38:39]
	s_add_u32 s8, s8, 0x4000
	s_addc_u32 s9, s9, 0
	s_add_u32 s38, s38, 0x800
	s_addc_u32 s39, s39, 0
	s_waitcnt vmcnt(48)
	v_cvt_pk_bf16_f32 v16, v8, v9
	v_cvt_pk_bf16_f32 v17, v10, v11
	global_store_dwordx2 v4, v[16:17], s[10:11]
	s_add_u32 s10, s10, 0x4000
	s_addc_u32 s11, s11, 0
	v_lshlrev_b32_e32 v12, 16, v74
	v_and_b32_e32 v13, 0xffff0000, v74
	v_lshlrev_b32_e32 v14, 16, v75
	v_and_b32_e32 v15, 0xffff0000, v75
	v_pk_fma_f32 v[8:9], v[76:77], v[8:9], v[12:13]
	v_pk_fma_f32 v[10:11], v[78:79], v[10:11], v[14:15]
	global_load_dwordx2 v[74:75], v4, s[8:9]
	global_load_dwordx4 v[76:79], v5, s[38:39]
	s_add_u32 s8, s8, 0x4000
	s_addc_u32 s9, s9, 0
	s_add_u32 s38, s38, 0x800
	s_addc_u32 s39, s39, 0
	s_waitcnt vmcnt(48)
	v_cvt_pk_bf16_f32 v18, v8, v9
	v_cvt_pk_bf16_f32 v19, v10, v11
	global_store_dwordx2 v4, v[18:19], s[10:11]
	s_add_u32 s10, s10, 0x4000
	s_addc_u32 s11, s11, 0
	v_lshlrev_b32_e32 v12, 16, v80
	v_and_b32_e32 v13, 0xffff0000, v80
	v_lshlrev_b32_e32 v14, 16, v81
	v_and_b32_e32 v15, 0xffff0000, v81
	v_pk_fma_f32 v[8:9], v[82:83], v[8:9], v[12:13]
	v_pk_fma_f32 v[10:11], v[84:85], v[10:11], v[14:15]
	global_load_dwordx2 v[80:81], v4, s[8:9]
	global_load_dwordx4 v[82:85], v5, s[38:39]
	s_add_u32 s8, s8, 0x4000
	s_addc_u32 s9, s9, 0
	s_add_u32 s38, s38, 0x800
	s_addc_u32 s39, s39, 0
	s_waitcnt vmcnt(48)
	v_cvt_pk_bf16_f32 v20, v8, v9
	v_cvt_pk_bf16_f32 v21, v10, v11
	global_store_dwordx2 v4, v[20:21], s[10:11]
	s_add_u32 s10, s10, 0x4000
	s_addc_u32 s11, s11, 0
	v_lshlrev_b32_e32 v12, 16, v86
	v_and_b32_e32 v13, 0xffff0000, v86
	v_lshlrev_b32_e32 v14, 16, v87
	v_and_b32_e32 v15, 0xffff0000, v87
	v_pk_fma_f32 v[8:9], v[88:89], v[8:9], v[12:13]
	v_pk_fma_f32 v[10:11], v[90:91], v[10:11], v[14:15]
	global_load_dwordx2 v[86:87], v4, s[8:9]
	global_load_dwordx4 v[88:91], v5, s[38:39]
	s_add_u32 s8, s8, 0x4000
	s_addc_u32 s9, s9, 0
	s_add_u32 s38, s38, 0x800
	s_addc_u32 s39, s39, 0
	s_waitcnt vmcnt(48)
	v_cvt_pk_bf16_f32 v24, v8, v9
	v_cvt_pk_bf16_f32 v25, v10, v11
	global_store_dwordx2 v4, v[24:25], s[10:11]
	s_add_u32 s10, s10, 0x4000
	s_addc_u32 s11, s11, 0
	v_lshlrev_b32_e32 v12, 16, v92
	v_and_b32_e32 v13, 0xffff0000, v92
	v_lshlrev_b32_e32 v14, 16, v93
	v_and_b32_e32 v15, 0xffff0000, v93
	v_pk_fma_f32 v[8:9], v[94:95], v[8:9], v[12:13]
	v_pk_fma_f32 v[10:11], v[96:97], v[10:11], v[14:15]
	global_load_dwordx2 v[92:93], v4, s[8:9]
	global_load_dwordx4 v[94:97], v5, s[38:39]
	s_add_u32 s8, s8, 0x4000
	s_addc_u32 s9, s9, 0
	s_add_u32 s38, s38, 0x800
	s_addc_u32 s39, s39, 0
	s_waitcnt vmcnt(48)
	v_cvt_pk_bf16_f32 v16, v8, v9
	v_cvt_pk_bf16_f32 v17, v10, v11
	global_store_dwordx2 v4, v[16:17], s[10:11]
	s_add_u32 s10, s10, 0x4000
	s_addc_u32 s11, s11, 0
	v_lshlrev_b32_e32 v12, 16, v98
	v_and_b32_e32 v13, 0xffff0000, v98
	v_lshlrev_b32_e32 v14, 16, v99
	v_and_b32_e32 v15, 0xffff0000, v99
	v_pk_fma_f32 v[8:9], v[100:101], v[8:9], v[12:13]
	v_pk_fma_f32 v[10:11], v[102:103], v[10:11], v[14:15]
	global_load_dwordx2 v[98:99], v4, s[8:9]
	global_load_dwordx4 v[100:103], v5, s[38:39]
	s_add_u32 s8, s8, 0x4000
	s_addc_u32 s9, s9, 0
	s_add_u32 s38, s38, 0x800
	s_addc_u32 s39, s39, 0
	s_waitcnt vmcnt(48)
; __device__ __forceinline__ unsigned pk2(float lo, float hi) { return pg8::pkc(lo, hi); }
; __device__ __forceinline__ void ph_g2(Frame& F) {
;     ...
;         for (int s = 0; s < 68; ++s) {
;             const v2u uw = *(const v2u*)(UT + base + (size_t)s * 8192);
;             const int rc = chain_slot_rc(b, dir, s);
;             const f32x4 a = *(const f32x4*)(AL + (size_t)(dir * NRC + rc) * 512 + 64 * h + dk4);
;             v2u o; if (dir) { o.x = pk2(S0 * a.x, S1 * a.y); o.y = pk2(S2 * a.z, S3 * a.w); } else { o.x = pk2(S0, S1); o.y = pk2(S2, S3); }
;             *(v2u*)(ST + base + (size_t)s * 8192) = o;
;             S0 = fmaf(a.x, S0, bflo(uw.x)); S1 = fmaf(a.y, S1, bfhi(uw.x)); S2 = fmaf(a.z, S2, bflo(uw.y)); S3 = fmaf(a.w, S3, bfhi(uw.y));
	v_cvt_pk_bf16_f32 v18, v8, v9
	v_cvt_pk_bf16_f32 v19, v10, v11
	global_store_dwordx2 v4, v[18:19], s[10:11]
	s_add_u32 s10, s10, 0x4000
	s_addc_u32 s11, s11, 0
	v_lshlrev_b32_e32 v12, 16, v104
	v_and_b32_e32 v13, 0xffff0000, v104
	v_lshlrev_b32_e32 v14, 16, v105
	v_and_b32_e32 v15, 0xffff0000, v105
	v_pk_fma_f32 v[8:9], v[106:107], v[8:9], v[12:13]
	v_pk_fma_f32 v[10:11], v[108:109], v[10:11], v[14:15]
	global_load_dwordx2 v[104:105], v4, s[8:9]
	global_load_dwordx4 v[106:109], v5, s[38:39]
	s_add_u32 s8, s8, 0x4000
	s_addc_u32 s9, s9, 0
	s_add_u32 s38, s38, 0x800
	s_addc_u32 s39, s39, 0
	s_waitcnt vmcnt(48)
	v_cvt_pk_bf16_f32 v20, v8, v9
	v_cvt_pk_bf16_f32 v21, v10, v11
	global_store_dwordx2 v4, v[20:21], s[10:11]
	s_add_u32 s10, s10, 0x4000
	s_addc_u32 s11, s11, 0
	v_lshlrev_b32_e32 v12, 16, v110
	v_and_b32_e32 v13, 0xffff0000, v110
	v_lshlrev_b32_e32 v14, 16, v111
	v_and_b32_e32 v15, 0xffff0000, v111
	v_pk_fma_f32 v[8:9], v[112:113], v[8:9], v[12:13]
	v_pk_fma_f32 v[10:11], v[114:115], v[10:11], v[14:15]
	global_load_dwordx2 v[110:111], v4, s[8:9]
	global_load_dwordx4 v[112:115], v5, s[38:39]
	s_add_u32 s8, s8, 0x4000
	s_addc_u32 s9, s9, 0
	s_add_u32 s38, s38, 0x800
	s_addc_u32 s39, s39, 0
	s_waitcnt vmcnt(48)
	v_cvt_pk_bf16_f32 v24, v8, v9
	v_cvt_pk_bf16_f32 v25, v10, v11
	global_store_dwordx2 v4, v[24:25], s[10:11]
	s_add_u32 s10, s10, 0x4000
	s_addc_u32 s11, s11, 0
	v_lshlrev_b32_e32 v12, 16, v116
	v_and_b32_e32 v13, 0xffff0000, v116
	v_lshlrev_b32_e32 v14, 16, v117
	v_and_b32_e32 v15, 0xffff0000, v117
	v_pk_fma_f32 v[8:9], v[118:119], v[8:9], v[12:13]
	v_pk_fma_f32 v[10:11], v[120:121], v[10:11], v[14:15]
	global_load_dwordx2 v[116:117], v4, s[8:9]
	global_load_dwordx4 v[118:121], v5, s[38:39]
	s_add_u32 s8, s8, 0x4000
	s_addc_u32 s9, s9, 0
	s_add_u32 s38, s38, 0x800
	s_addc_u32 s39, s39, 0
	s_waitcnt vmcnt(48)
	v_cvt_pk_bf16_f32 v16, v8, v9
	v_cvt_pk_bf16_f32 v17, v10, v11
	global_store_dwordx2 v4, v[16:17], s[10:11]
	s_add_u32 s10, s10, 0x4000
	s_addc_u32 s11, s11, 0
	v_lshlrev_b32_e32 v12, 16, v122
	v_and_b32_e32 v13, 0xffff0000, v122
	v_lshlrev_b32_e32 v14, 16, v123
	v_and_b32_e32 v15, 0xffff0000, v123
	v_pk_fma_f32 v[8:9], v[124:125], v[8:9], v[12:13]
	v_pk_fma_f32 v[10:11], v[126:127], v[10:11], v[14:15]
	global_load_dwordx2 v[122:123], v4, s[8:9]
	global_load_dwordx4 v[124:127], v5, s[38:39]
	s_add_u32 s8, s8, 0x4000
	s_addc_u32 s9, s9, 0
	s_add_u32 s38, s38, 0x800
	s_addc_u32 s39, s39, 0
	s_waitcnt vmcnt(48)
	v_cvt_pk_bf16_f32 v18, v8, v9
	v_cvt_pk_bf16_f32 v19, v10, v11
	global_store_dwordx2 v4, v[18:19], s[10:11]
	s_add_u32 s10, s10, 0x4000
	s_addc_u32 s11, s11, 0
	v_lshlrev_b32_e32 v12, 16, v128
	v_and_b32_e32 v13, 0xffff0000, v128
	v_lshlrev_b32_e32 v14, 16, v129
	v_and_b32_e32 v15, 0xffff0000, v129
	v_pk_fma_f32 v[8:9], v[130:131], v[8:9], v[12:13]
	v_pk_fma_f32 v[10:11], v[132:133], v[10:11], v[14:15]
	global_load_dwordx2 v[128:129], v4, s[8:9]
	global_load_dwordx4 v[130:133], v5, s[38:39]
	s_add_u32 s8, s8, 0x4000
	s_addc_u32 s9, s9, 0
	s_add_u32 s38, s38, 0x800
	s_addc_u32 s39, s39, 0
	s_waitcnt vmcnt(48)
	v_cvt_pk_bf16_f32 v20, v8, v9
	v_cvt_pk_bf16_f32 v21, v10, v11
	global_store_dwordx2 v4, v[20:21], s[10:11]
	s_add_u32 s10, s10, 0x4000
	s_addc_u32 s11, s11, 0
	v_lshlrev_b32_e32 v12, 16, v32
	v_and_b32_e32 v13, 0xffff0000, v32
	v_lshlrev_b32_e32 v14, 16, v33
	v_and_b32_e32 v15, 0xffff0000, v33
	v_pk_fma_f32 v[8:9], v[34:35], v[8:9], v[12:13]
	v_pk_fma_f32 v[10:11], v[36:37], v[10:11], v[14:15]
	global_load_dwordx2 v[32:33], v4, s[8:9]
	global_load_dwordx4 v[34:37], v5, s[38:39]
	s_add_u32 s8, s8, 0x4000
	s_addc_u32 s9, s9, 0
	s_add_u32 s38, s38, 0x800
	s_addc_u32 s39, s39, 0
	s_waitcnt vmcnt(48)
	v_cvt_pk_bf16_f32 v24, v8, v9
	v_cvt_pk_bf16_f32 v25, v10, v11
	global_store_dwordx2 v4, v[24:25], s[10:11]
	s_add_u32 s10, s10, 0x4000
	s_addc_u32 s11, s11, 0
	v_lshlrev_b32_e32 v12, 16, v38
	v_and_b32_e32 v13, 0xffff0000, v38
	v_lshlrev_b32_e32 v14, 16, v39
	v_and_b32_e32 v15, 0xffff0000, v39
	v_pk_fma_f32 v[8:9], v[40:41], v[8:9], v[12:13]
	v_pk_fma_f32 v[10:11], v[42:43], v[10:11], v[14:15]
	global_load_dwordx2 v[38:39], v4, s[8:9]
	global_load_dwordx4 v[40:43], v5, s[38:39]
	s_add_u32 s8, s8, 0x4000
	s_addc_u32 s9, s9, 0
	s_add_u32 s38, s38, 0x800
	s_addc_u32 s39, s39, 0
	s_waitcnt vmcnt(48)
	v_cvt_pk_bf16_f32 v16, v8, v9
	v_cvt_pk_bf16_f32 v17, v10, v11
	global_store_dwordx2 v4, v[16:17], s[10:11]
	s_add_u32 s10, s10, 0x4000
	s_addc_u32 s11, s11, 0
	v_lshlrev_b32_e32 v12, 16, v44
	v_and_b32_e32 v13, 0xffff0000, v44
	v_lshlrev_b32_e32 v14, 16, v45
	v_and_b32_e32 v15, 0xffff0000, v45
	v_pk_fma_f32 v[8:9], v[46:47], v[8:9], v[12:13]
	v_pk_fma_f32 v[10:11], v[48:49], v[10:11], v[14:15]
	global_load_dwordx2 v[44:45], v4, s[8:9]
	global_load_dwordx4 v[46:49], v5, s[38:39]
	s_add_u32 s8, s8, 0x4000
	s_addc_u32 s9, s9, 0
	s_add_u32 s38, s38, 0x800
	s_addc_u32 s39, s39, 0
	s_waitcnt vmcnt(48)
	v_cvt_pk_bf16_f32 v18, v8, v9
	v_cvt_pk_bf16_f32 v19, v10, v11
	global_store_dwordx2 v4, v[18:19], s[10:11]
	s_add_u32 s10, s10, 0x4000
	s_addc_u32 s11, s11, 0
	v_lshlrev_b32_e32 v12, 16, v50
	v_and_b32_e32 v13, 0xffff0000, v50
	v_lshlrev_b32_e32 v14, 16, v51
	v_and_b32_e32 v15, 0xffff0000, v51
	v_pk_fma_f32 v[8:9], v[52:53], v[8:9], v[12:13]
	v_pk_fma_f32 v[10:11], v[54:55], v[10:11], v[14:15]
	global_load_dwordx2 v[50:51], v4, s[8:9]
	global_load_dwordx4 v[52:55], v5, s[38:39]
	s_add_u32 s8, s8, 0x4000
	s_addc_u32 s9, s9, 0
	s_add_u32 s38, s38, 0x800
	s_addc_u32 s39, s39, 0
	s_waitcnt vmcnt(48)
; __device__ __forceinline__ unsigned pk2(float lo, float hi) { return pg8::pkc(lo, hi); }
; __device__ __forceinline__ void ph_g2(Frame& F) {
;     ...
;         for (int s = 0; s < 68; ++s) {
;             const v2u uw = *(const v2u*)(UT + base + (size_t)s * 8192);
;             const int rc = chain_slot_rc(b, dir, s);
;             const f32x4 a = *(const f32x4*)(AL + (size_t)(dir * NRC + rc) * 512 + 64 * h + dk4);
;             v2u o; if (dir) { o.x = pk2(S0 * a.x, S1 * a.y); o.y = pk2(S2 * a.z, S3 * a.w); } else { o.x = pk2(S0, S1); o.y = pk2(S2, S3); }
;             *(v2u*)(ST + base + (size_t)s * 8192) = o;
;             S0 = fmaf(a.x, S0, bflo(uw.x)); S1 = fmaf(a.y, S1, bfhi(uw.x)); S2 = fmaf(a.z, S2, bflo(uw.y)); S3 = fmaf(a.w, S3, bfhi(uw.y));
	v_cvt_pk_bf16_f32 v20, v8, v9
	v_cvt_pk_bf16_f32 v21, v10, v11
	global_store_dwordx2 v4, v[20:21], s[10:11]
	s_add_u32 s10, s10, 0x4000
	s_addc_u32 s11, s11, 0
	v_lshlrev_b32_e32 v12, 16, v56
	v_and_b32_e32 v13, 0xffff0000, v56
	v_lshlrev_b32_e32 v14, 16, v57
	v_and_b32_e32 v15, 0xffff0000, v57
	v_pk_fma_f32 v[8:9], v[58:59], v[8:9], v[12:13]
	v_pk_fma_f32 v[10:11], v[60:61], v[10:11], v[14:15]
	global_load_dwordx2 v[56:57], v4, s[8:9]
	global_load_dwordx4 v[58:61], v5, s[38:39]
	s_add_u32 s8, s8, 0x4000
	s_addc_u32 s9, s9, 0
	s_add_u32 s38, s38, 0x800
	s_addc_u32 s39, s39, 0
	s_waitcnt vmcnt(48)
	v_cvt_pk_bf16_f32 v24, v8, v9
	v_cvt_pk_bf16_f32 v25, v10, v11
	global_store_dwordx2 v4, v[24:25], s[10:11]
	s_add_u32 s10, s10, 0x4000
	s_addc_u32 s11, s11, 0
	v_lshlrev_b32_e32 v12, 16, v62
	v_and_b32_e32 v13, 0xffff0000, v62
	v_lshlrev_b32_e32 v14, 16, v63
	v_and_b32_e32 v15, 0xffff0000, v63
	v_pk_fma_f32 v[8:9], v[64:65], v[8:9], v[12:13]
	v_pk_fma_f32 v[10:11], v[66:67], v[10:11], v[14:15]
	global_load_dwordx2 v[62:63], v4, s[8:9]
	global_load_dwordx4 v[64:67], v5, s[38:39]
	s_add_u32 s8, s8, 0x4000
	s_addc_u32 s9, s9, 0
	s_add_u32 s38, s38, 0x800
	s_addc_u32 s39, s39, 0
	s_waitcnt vmcnt(48)
	v_cvt_pk_bf16_f32 v16, v8, v9
	v_cvt_pk_bf16_f32 v17, v10, v11
	global_store_dwordx2 v4, v[16:17], s[10:11]
	s_add_u32 s10, s10, 0x4000
	s_addc_u32 s11, s11, 0
	v_lshlrev_b32_e32 v12, 16, v68
	v_and_b32_e32 v13, 0xffff0000, v68
	v_lshlrev_b32_e32 v14, 16, v69
	v_and_b32_e32 v15, 0xffff0000, v69
	v_pk_fma_f32 v[8:9], v[70:71], v[8:9], v[12:13]
	v_pk_fma_f32 v[10:11], v[72:73], v[10:11], v[14:15]
	global_load_dwordx2 v[68:69], v4, s[8:9]
	global_load_dwordx4 v[70:73], v5, s[38:39]
	s_add_u32 s8, s8, 0x4000
	s_addc_u32 s9, s9, 0
	s_add_u32 s38, s38, 0x800
	s_addc_u32 s39, s39, 0
	s_waitcnt vmcnt(48)
	v_cvt_pk_bf16_f32 v18, v8, v9
	v_cvt_pk_bf16_f32 v19, v10, v11
	global_store_dwordx2 v4, v[18:19], s[10:11]
	s_add_u32 s10, s10, 0x4000
	s_addc_u32 s11, s11, 0
	v_lshlrev_b32_e32 v12, 16, v74
	v_and_b32_e32 v13, 0xffff0000, v74
	v_lshlrev_b32_e32 v14, 16, v75
	v_and_b32_e32 v15, 0xffff0000, v75
	v_pk_fma_f32 v[8:9], v[76:77], v[8:9], v[12:13]
	v_pk_fma_f32 v[10:11], v[78:79], v[10:11], v[14:15]
	global_load_dwordx2 v[74:75], v4, s[8:9]
	global_load_dwordx4 v[76:79], v5, s[38:39]
	s_add_u32 s8, s8, 0x4000
	s_addc_u32 s9, s9, 0
	s_add_u32 s38, s38, 0x800
	s_addc_u32 s39, s39, 0
	s_waitcnt vmcnt(48)
	v_cvt_pk_bf16_f32 v20, v8, v9
	v_cvt_pk_bf16_f32 v21, v10, v11
	global_store_dwordx2 v4, v[20:21], s[10:11]
	s_add_u32 s10, s10, 0x4000
	s_addc_u32 s11, s11, 0
	v_lshlrev_b32_e32 v12, 16, v80
	v_and_b32_e32 v13, 0xffff0000, v80
	v_lshlrev_b32_e32 v14, 16, v81
	v_and_b32_e32 v15, 0xffff0000, v81
	v_pk_fma_f32 v[8:9], v[82:83], v[8:9], v[12:13]
	v_pk_fma_f32 v[10:11], v[84:85], v[10:11], v[14:15]
	global_load_dwordx2 v[80:81], v4, s[8:9]
	global_load_dwordx4 v[82:85], v5, s[38:39]
	s_add_u32 s8, s8, 0x4000
	s_addc_u32 s9, s9, 0
	s_add_u32 s38, s38, 0x800
	s_addc_u32 s39, s39, 0
	s_waitcnt vmcnt(48)
	v_cvt_pk_bf16_f32 v24, v8, v9
	v_cvt_pk_bf16_f32 v25, v10, v11
	global_store_dwordx2 v4, v[24:25], s[10:11]
	s_add_u32 s10, s10, 0x4000
	s_addc_u32 s11, s11, 0
	v_lshlrev_b32_e32 v12, 16, v86
	v_and_b32_e32 v13, 0xffff0000, v86
	v_lshlrev_b32_e32 v14, 16, v87
	v_and_b32_e32 v15, 0xffff0000, v87
	v_pk_fma_f32 v[8:9], v[88:89], v[8:9], v[12:13]
	v_pk_fma_f32 v[10:11], v[90:91], v[10:11], v[14:15]
	global_load_dwordx2 v[86:87], v4, s[8:9]
	global_load_dwordx4 v[88:91], v5, s[38:39]
	s_add_u32 s8, s8, 0x4000
	s_addc_u32 s9, s9, 0
	s_add_u32 s38, s38, 0x800
	s_addc_u32 s39, s39, 0
	s_waitcnt vmcnt(48)
	v_cvt_pk_bf16_f32 v16, v8, v9
	v_cvt_pk_bf16_f32 v17, v10, v11
	global_store_dwordx2 v4, v[16:17], s[10:11]
	s_add_u32 s10, s10, 0x4000
	s_addc_u32 s11, s11, 0
	v_lshlrev_b32_e32 v12, 16, v92
	v_and_b32_e32 v13, 0xffff0000, v92
	v_lshlrev_b32_e32 v14, 16, v93
	v_and_b32_e32 v15, 0xffff0000, v93
	v_pk_fma_f32 v[8:9], v[94:95], v[8:9], v[12:13]
	v_pk_fma_f32 v[10:11], v[96:97], v[10:11], v[14:15]
	global_load_dwordx2 v[92:93], v4, s[8:9]
	global_load_dwordx4 v[94:97], v5, s[38:39]
	s_add_u32 s8, s8, 0x4000
	s_addc_u32 s9, s9, 0
	s_add_u32 s38, s38, 0x800
	s_addc_u32 s39, s39, 0
	s_waitcnt vmcnt(48)
	v_cvt_pk_bf16_f32 v18, v8, v9
	v_cvt_pk_bf16_f32 v19, v10, v11
	global_store_dwordx2 v4, v[18:19], s[10:11]
	s_add_u32 s10, s10, 0x4000
	s_addc_u32 s11, s11, 0
	v_lshlrev_b32_e32 v12, 16, v98
	v_and_b32_e32 v13, 0xffff0000, v98
	v_lshlrev_b32_e32 v14, 16, v99
	v_and_b32_e32 v15, 0xffff0000, v99
	v_pk_fma_f32 v[8:9], v[100:101], v[8:9], v[12:13]
	v_pk_fma_f32 v[10:11], v[102:103], v[10:11], v[14:15]
	global_load_dwordx2 v[98:99], v4, s[8:9]
	global_load_dwordx4 v[100:103], v5, s[38:39]
	s_add_u32 s8, s8, 0x4000
	s_addc_u32 s9, s9, 0
	s_add_u32 s38, s38, 0x800
	s_addc_u32 s39, s39, 0
	s_waitcnt vmcnt(48)
	v_cvt_pk_bf16_f32 v20, v8, v9
	v_cvt_pk_bf16_f32 v21, v10, v11
	global_store_dwordx2 v4, v[20:21], s[10:11]
	s_add_u32 s10, s10, 0x4000
	s_addc_u32 s11, s11, 0
	v_lshlrev_b32_e32 v12, 16, v104
	v_and_b32_e32 v13, 0xffff0000, v104
	v_lshlrev_b32_e32 v14, 16, v105
	v_and_b32_e32 v15, 0xffff0000, v105
	v_pk_fma_f32 v[8:9], v[106:107], v[8:9], v[12:13]
	v_pk_fma_f32 v[10:11], v[108:109], v[10:11], v[14:15]
	global_load_dwordx2 v[104:105], v4, s[8:9]
	global_load_dwordx4 v[106:109], v5, s[38:39]
	s_add_u32 s8, s8, 0x4000
	s_addc_u32 s9, s9, 0
	s_add_u32 s38, s38, 0x800
	s_addc_u32 s39, s39, 0
	s_waitcnt vmcnt(48)
; __device__ __forceinline__ unsigned pk2(float lo, float hi) { return pg8::pkc(lo, hi); }
; __device__ __forceinline__ void ph_g2(Frame& F) {
;     ...
;         for (int s = 0; s < 68; ++s) {
;             const v2u uw = *(const v2u*)(UT + base + (size_t)s * 8192);
;             const int rc = chain_slot_rc(b, dir, s);
;             const f32x4 a = *(const f32x4*)(AL + (size_t)(dir * NRC + rc) * 512 + 64 * h + dk4);
;             v2u o; if (dir) { o.x = pk2(S0 * a.x, S1 * a.y); o.y = pk2(S2 * a.z, S3 * a.w); } else { o.x = pk2(S0, S1); o.y = pk2(S2, S3); }
;             *(v2u*)(ST + base + (size_t)s * 8192) = o;
;             S0 = fmaf(a.x, S0, bflo(uw.x)); S1 = fmaf(a.y, S1, bfhi(uw.x)); S2 = fmaf(a.z, S2, bflo(uw.y)); S3 = fmaf(a.w, S3, bfhi(uw.y));
	v_cvt_pk_bf16_f32 v24, v8, v9
	v_cvt_pk_bf16_f32 v25, v10, v11
	global_store_dwordx2 v4, v[24:25], s[10:11]
	s_add_u32 s10, s10, 0x4000
	s_addc_u32 s11, s11, 0
	v_lshlrev_b32_e32 v12, 16, v110
	v_and_b32_e32 v13, 0xffff0000, v110
	v_lshlrev_b32_e32 v14, 16, v111
	v_and_b32_e32 v15, 0xffff0000, v111
	v_pk_fma_f32 v[8:9], v[112:113], v[8:9], v[12:13]
	v_pk_fma_f32 v[10:11], v[114:115], v[10:11], v[14:15]
	global_load_dwordx2 v[110:111], v4, s[8:9]
	global_load_dwordx4 v[112:115], v5, s[38:39]
	s_add_u32 s8, s8, 0x4000
	s_addc_u32 s9, s9, 0
	s_add_u32 s38, s38, 0x800
	s_addc_u32 s39, s39, 0
	s_waitcnt vmcnt(48)
	v_cvt_pk_bf16_f32 v16, v8, v9
	v_cvt_pk_bf16_f32 v17, v10, v11
	global_store_dwordx2 v4, v[16:17], s[10:11]
	s_add_u32 s10, s10, 0x4000
	s_addc_u32 s11, s11, 0
	v_lshlrev_b32_e32 v12, 16, v116
	v_and_b32_e32 v13, 0xffff0000, v116
	v_lshlrev_b32_e32 v14, 16, v117
	v_and_b32_e32 v15, 0xffff0000, v117
	v_pk_fma_f32 v[8:9], v[118:119], v[8:9], v[12:13]
	v_pk_fma_f32 v[10:11], v[120:121], v[10:11], v[14:15]
	global_load_dwordx2 v[116:117], v4, s[8:9]
	global_load_dwordx4 v[118:121], v5, s[38:39]
	s_add_u32 s8, s8, 0x4000
	s_addc_u32 s9, s9, 0
	s_add_u32 s38, s38, 0x800
	s_addc_u32 s39, s39, 0
	s_waitcnt vmcnt(48)
	v_cvt_pk_bf16_f32 v18, v8, v9
	v_cvt_pk_bf16_f32 v19, v10, v11
	global_store_dwordx2 v4, v[18:19], s[10:11]
	s_add_u32 s10, s10, 0x4000
	s_addc_u32 s11, s11, 0
	v_lshlrev_b32_e32 v12, 16, v122
	v_and_b32_e32 v13, 0xffff0000, v122
	v_lshlrev_b32_e32 v14, 16, v123
	v_and_b32_e32 v15, 0xffff0000, v123
	v_pk_fma_f32 v[8:9], v[124:125], v[8:9], v[12:13]
	v_pk_fma_f32 v[10:11], v[126:127], v[10:11], v[14:15]
	global_load_dwordx2 v[122:123], v4, s[8:9]
	global_load_dwordx4 v[124:127], v5, s[38:39]
	s_add_u32 s8, s8, 0x4000
	s_addc_u32 s9, s9, 0
	s_add_u32 s38, s38, 0x800
	s_addc_u32 s39, s39, 0
	s_waitcnt vmcnt(48)
	v_cvt_pk_bf16_f32 v20, v8, v9
	v_cvt_pk_bf16_f32 v21, v10, v11
	global_store_dwordx2 v4, v[20:21], s[10:11]
	s_add_u32 s10, s10, 0x4000
	s_addc_u32 s11, s11, 0
	v_lshlrev_b32_e32 v12, 16, v128
	v_and_b32_e32 v13, 0xffff0000, v128
	v_lshlrev_b32_e32 v14, 16, v129
	v_and_b32_e32 v15, 0xffff0000, v129
	v_pk_fma_f32 v[8:9], v[130:131], v[8:9], v[12:13]
	v_pk_fma_f32 v[10:11], v[132:133], v[10:11], v[14:15]
	global_load_dwordx2 v[128:129], v4, s[8:9]
	global_load_dwordx4 v[130:133], v5, s[38:39]
	s_add_u32 s8, s8, 0x4000
	s_addc_u32 s9, s9, 0
	s_add_u32 s38, s38, 0x800
	s_addc_u32 s39, s39, 0
	s_waitcnt vmcnt(48)
	v_cvt_pk_bf16_f32 v24, v8, v9
	v_cvt_pk_bf16_f32 v25, v10, v11
	global_store_dwordx2 v4, v[24:25], s[10:11]
	s_add_u32 s10, s10, 0x4000
	s_addc_u32 s11, s11, 0
	v_lshlrev_b32_e32 v12, 16, v32
	v_and_b32_e32 v13, 0xffff0000, v32
	v_lshlrev_b32_e32 v14, 16, v33
	v_and_b32_e32 v15, 0xffff0000, v33
	v_pk_fma_f32 v[8:9], v[34:35], v[8:9], v[12:13]
	v_pk_fma_f32 v[10:11], v[36:37], v[10:11], v[14:15]
	s_waitcnt vmcnt(46)
	v_cvt_pk_bf16_f32 v16, v8, v9
	v_cvt_pk_bf16_f32 v17, v10, v11
	global_store_dwordx2 v4, v[16:17], s[10:11]
	s_add_u32 s10, s10, 0x4000
	s_addc_u32 s11, s11, 0
	v_lshlrev_b32_e32 v12, 16, v38
	v_and_b32_e32 v13, 0xffff0000, v38
	v_lshlrev_b32_e32 v14, 16, v39
	v_and_b32_e32 v15, 0xffff0000, v39
	v_pk_fma_f32 v[8:9], v[40:41], v[8:9], v[12:13]
	v_pk_fma_f32 v[10:11], v[42:43], v[10:11], v[14:15]
	s_waitcnt vmcnt(44)
	v_cvt_pk_bf16_f32 v18, v8, v9
	v_cvt_pk_bf16_f32 v19, v10, v11
	global_store_dwordx2 v4, v[18:19], s[10:11]
	s_add_u32 s10, s10, 0x4000
	s_addc_u32 s11, s11, 0
	v_lshlrev_b32_e32 v12, 16, v44
	v_and_b32_e32 v13, 0xffff0000, v44
	v_lshlrev_b32_e32 v14, 16, v45
	v_and_b32_e32 v15, 0xffff0000, v45
	v_pk_fma_f32 v[8:9], v[46:47], v[8:9], v[12:13]
	v_pk_fma_f32 v[10:11], v[48:49], v[10:11], v[14:15]
	s_waitcnt vmcnt(42)
	v_cvt_pk_bf16_f32 v20, v8, v9
	v_cvt_pk_bf16_f32 v21, v10, v11
	global_store_dwordx2 v4, v[20:21], s[10:11]
	s_add_u32 s10, s10, 0x4000
	s_addc_u32 s11, s11, 0
	v_lshlrev_b32_e32 v12, 16, v50
	v_and_b32_e32 v13, 0xffff0000, v50
	v_lshlrev_b32_e32 v14, 16, v51
	v_and_b32_e32 v15, 0xffff0000, v51
	v_pk_fma_f32 v[8:9], v[52:53], v[8:9], v[12:13]
	v_pk_fma_f32 v[10:11], v[54:55], v[10:11], v[14:15]
	s_waitcnt vmcnt(40)
	v_cvt_pk_bf16_f32 v24, v8, v9
	v_cvt_pk_bf16_f32 v25, v10, v11
	global_store_dwordx2 v4, v[24:25], s[10:11]
	s_add_u32 s10, s10, 0x4000
	s_addc_u32 s11, s11, 0
	v_lshlrev_b32_e32 v12, 16, v56
	v_and_b32_e32 v13, 0xffff0000, v56
	v_lshlrev_b32_e32 v14, 16, v57
	v_and_b32_e32 v15, 0xffff0000, v57
	v_pk_fma_f32 v[8:9], v[58:59], v[8:9], v[12:13]
	v_pk_fma_f32 v[10:11], v[60:61], v[10:11], v[14:15]
	s_waitcnt vmcnt(38)
	v_cvt_pk_bf16_f32 v16, v8, v9
	v_cvt_pk_bf16_f32 v17, v10, v11
	global_store_dwordx2 v4, v[16:17], s[10:11]
	s_add_u32 s10, s10, 0x4000
	s_addc_u32 s11, s11, 0
	v_lshlrev_b32_e32 v12, 16, v62
	v_and_b32_e32 v13, 0xffff0000, v62
	v_lshlrev_b32_e32 v14, 16, v63
	v_and_b32_e32 v15, 0xffff0000, v63
	v_pk_fma_f32 v[8:9], v[64:65], v[8:9], v[12:13]
	v_pk_fma_f32 v[10:11], v[66:67], v[10:11], v[14:15]
	s_waitcnt vmcnt(36)
	v_cvt_pk_bf16_f32 v18, v8, v9
	v_cvt_pk_bf16_f32 v19, v10, v11
	global_store_dwordx2 v4, v[18:19], s[10:11]
	s_add_u32 s10, s10, 0x4000
	s_addc_u32 s11, s11, 0
	v_lshlrev_b32_e32 v12, 16, v68
	v_and_b32_e32 v13, 0xffff0000, v68
	v_lshlrev_b32_e32 v14, 16, v69
	v_and_b32_e32 v15, 0xffff0000, v69
	v_pk_fma_f32 v[8:9], v[70:71], v[8:9], v[12:13]
	v_pk_fma_f32 v[10:11], v[72:73], v[10:11], v[14:15]
	s_waitcnt vmcnt(34)
	v_cvt_pk_bf16_f32 v20, v8, v9
	v_cvt_pk_bf16_f32 v21, v10, v11
	global_store_dwordx2 v4, v[20:21], s[10:11]
	s_add_u32 s10, s10, 0x4000
	s_addc_u32 s11, s11, 0
	v_lshlrev_b32_e32 v12, 16, v74
	v_and_b32_e32 v13, 0xffff0000, v74
	v_lshlrev_b32_e32 v14, 16, v75
	v_and_b32_e32 v15, 0xffff0000, v75
	v_pk_fma_f32 v[8:9], v[76:77], v[8:9], v[12:13]
	v_pk_fma_f32 v[10:11], v[78:79], v[10:11], v[14:15]
	s_waitcnt vmcnt(32)
; __device__ __forceinline__ unsigned pk2(float lo, float hi) { return pg8::pkc(lo, hi); }
; __device__ __forceinline__ void ph_g2(Frame& F) {
;     ...
;         const int dir = chain & 1, h = (chain >> 1) & 7, b = chain >> 4;
;         float S0 = 0.f, S1 = 0.f, S2 = 0.f, S3 = 0.f;
;         const size_t base = (size_t)chain * 68 * 8192 + dv * 64 + dk4;
; #pragma unroll 34
;         for (int s = 0; s < 68; ++s) {
;             const v2u uw = *(const v2u*)(UT + base + (size_t)s * 8192);
;             const int rc = chain_slot_rc(b, dir, s);
;             const f32x4 a = *(const f32x4*)(AL + (size_t)(dir * NRC + rc) * 512 + 64 * h + dk4);
;             v2u o; if (dir) { o.x = pk2(S0 * a.x, S1 * a.y); o.y = pk2(S2 * a.z, S3 * a.w); } else { o.x = pk2(S0, S1); o.y = pk2(S2, S3); }
;             *(v2u*)(ST + base + (size_t)s * 8192) = o;
;             S0 = fmaf(a.x, S0, bflo(uw.x)); S1 = fmaf(a.y, S1, bfhi(uw.x)); S2 = fmaf(a.z, S2, bflo(uw.y)); S3 = fmaf(a.w, S3, bfhi(uw.y));
	v_cvt_pk_bf16_f32 v24, v8, v9
	v_cvt_pk_bf16_f32 v25, v10, v11
	global_store_dwordx2 v4, v[24:25], s[10:11]
	s_add_u32 s10, s10, 0x4000
	s_addc_u32 s11, s11, 0
	v_lshlrev_b32_e32 v12, 16, v80
	v_and_b32_e32 v13, 0xffff0000, v80
	v_lshlrev_b32_e32 v14, 16, v81
	v_and_b32_e32 v15, 0xffff0000, v81
	v_pk_fma_f32 v[8:9], v[82:83], v[8:9], v[12:13]
	v_pk_fma_f32 v[10:11], v[84:85], v[10:11], v[14:15]
	s_waitcnt vmcnt(30)
	v_cvt_pk_bf16_f32 v16, v8, v9
	v_cvt_pk_bf16_f32 v17, v10, v11
	global_store_dwordx2 v4, v[16:17], s[10:11]
	s_add_u32 s10, s10, 0x4000
	s_addc_u32 s11, s11, 0
	v_lshlrev_b32_e32 v12, 16, v86
	v_and_b32_e32 v13, 0xffff0000, v86
	v_lshlrev_b32_e32 v14, 16, v87
	v_and_b32_e32 v15, 0xffff0000, v87
	v_pk_fma_f32 v[8:9], v[88:89], v[8:9], v[12:13]
	v_pk_fma_f32 v[10:11], v[90:91], v[10:11], v[14:15]
	s_waitcnt vmcnt(28)
	v_cvt_pk_bf16_f32 v18, v8, v9
	v_cvt_pk_bf16_f32 v19, v10, v11
	global_store_dwordx2 v4, v[18:19], s[10:11]
	s_add_u32 s10, s10, 0x4000
	s_addc_u32 s11, s11, 0
	v_lshlrev_b32_e32 v12, 16, v92
	v_and_b32_e32 v13, 0xffff0000, v92
	v_lshlrev_b32_e32 v14, 16, v93
	v_and_b32_e32 v15, 0xffff0000, v93
	v_pk_fma_f32 v[8:9], v[94:95], v[8:9], v[12:13]
	v_pk_fma_f32 v[10:11], v[96:97], v[10:11], v[14:15]
	s_waitcnt vmcnt(26)
	v_cvt_pk_bf16_f32 v20, v8, v9
	v_cvt_pk_bf16_f32 v21, v10, v11
	global_store_dwordx2 v4, v[20:21], s[10:11]
	s_add_u32 s10, s10, 0x4000
	s_addc_u32 s11, s11, 0
	v_lshlrev_b32_e32 v12, 16, v98
	v_and_b32_e32 v13, 0xffff0000, v98
	v_lshlrev_b32_e32 v14, 16, v99
	v_and_b32_e32 v15, 0xffff0000, v99
	v_pk_fma_f32 v[8:9], v[100:101], v[8:9], v[12:13]
	v_pk_fma_f32 v[10:11], v[102:103], v[10:11], v[14:15]
	s_waitcnt vmcnt(24)
	v_cvt_pk_bf16_f32 v24, v8, v9
	v_cvt_pk_bf16_f32 v25, v10, v11
	global_store_dwordx2 v4, v[24:25], s[10:11]
	s_add_u32 s10, s10, 0x4000
	s_addc_u32 s11, s11, 0
	v_lshlrev_b32_e32 v12, 16, v104
	v_and_b32_e32 v13, 0xffff0000, v104
	v_lshlrev_b32_e32 v14, 16, v105
	v_and_b32_e32 v15, 0xffff0000, v105
	v_pk_fma_f32 v[8:9], v[106:107], v[8:9], v[12:13]
	v_pk_fma_f32 v[10:11], v[108:109], v[10:11], v[14:15]
	s_waitcnt vmcnt(22)
	v_cvt_pk_bf16_f32 v16, v8, v9
	v_cvt_pk_bf16_f32 v17, v10, v11
	global_store_dwordx2 v4, v[16:17], s[10:11]
	s_add_u32 s10, s10, 0x4000
	s_addc_u32 s11, s11, 0
	v_lshlrev_b32_e32 v12, 16, v110
	v_and_b32_e32 v13, 0xffff0000, v110
	v_lshlrev_b32_e32 v14, 16, v111
	v_and_b32_e32 v15, 0xffff0000, v111
	v_pk_fma_f32 v[8:9], v[112:113], v[8:9], v[12:13]
	v_pk_fma_f32 v[10:11], v[114:115], v[10:11], v[14:15]
	s_waitcnt vmcnt(20)
	v_cvt_pk_bf16_f32 v18, v8, v9
	v_cvt_pk_bf16_f32 v19, v10, v11
	global_store_dwordx2 v4, v[18:19], s[10:11]
	s_add_u32 s10, s10, 0x4000
	s_addc_u32 s11, s11, 0
	v_lshlrev_b32_e32 v12, 16, v116
	v_and_b32_e32 v13, 0xffff0000, v116
	v_lshlrev_b32_e32 v14, 16, v117
	v_and_b32_e32 v15, 0xffff0000, v117
	v_pk_fma_f32 v[8:9], v[118:119], v[8:9], v[12:13]
	v_pk_fma_f32 v[10:11], v[120:121], v[10:11], v[14:15]
	s_waitcnt vmcnt(18)
	v_cvt_pk_bf16_f32 v20, v8, v9
	v_cvt_pk_bf16_f32 v21, v10, v11
	global_store_dwordx2 v4, v[20:21], s[10:11]
	s_add_u32 s10, s10, 0x4000
	s_addc_u32 s11, s11, 0
	v_lshlrev_b32_e32 v12, 16, v122
	v_and_b32_e32 v13, 0xffff0000, v122
	v_lshlrev_b32_e32 v14, 16, v123
	v_and_b32_e32 v15, 0xffff0000, v123
	v_pk_fma_f32 v[8:9], v[124:125], v[8:9], v[12:13]
	v_pk_fma_f32 v[10:11], v[126:127], v[10:11], v[14:15]
	s_waitcnt vmcnt(16)
	v_cvt_pk_bf16_f32 v24, v8, v9
	v_cvt_pk_bf16_f32 v25, v10, v11
	global_store_dwordx2 v4, v[24:25], s[10:11]
	s_add_u32 s10, s10, 0x4000
	s_addc_u32 s11, s11, 0
	v_lshlrev_b32_e32 v12, 16, v128
	v_and_b32_e32 v13, 0xffff0000, v128
	v_lshlrev_b32_e32 v14, 16, v129
	v_and_b32_e32 v15, 0xffff0000, v129
	v_pk_fma_f32 v[8:9], v[130:131], v[8:9], v[12:13]
	v_pk_fma_f32 v[10:11], v[132:133], v[10:11], v[14:15]
	s_branch .LBB0_791
.Lg2_dir1:
	s_lshl_b32 s0, s4, 17
	s_add_i32 s0, s0, 0x1f800
	s_add_u32 s40, s38, s0
	s_addc_u32 s41, s39, 0
	s_lshl_b32 s0, s4, 13
	s_add_i32 s0, s0, 0x81800
	s_add_u32 s38, s38, s0
	s_addc_u32 s39, s39, 0
	global_load_dwordx2 v[32:33], v4, s[8:9]
	global_load_dwordx4 v[34:37], v5, s[38:39]
	s_add_u32 s8, s8, 0x4000
	s_addc_u32 s9, s9, 0
	s_sub_u32 s38, s38, 0x800
	s_subb_u32 s39, s39, 0
	global_load_dwordx2 v[38:39], v4, s[8:9]
	global_load_dwordx4 v[40:43], v5, s[38:39]
	s_add_u32 s8, s8, 0x4000
	s_addc_u32 s9, s9, 0
	s_sub_u32 s38, s38, 0x800
	s_subb_u32 s39, s39, 0
	global_load_dwordx2 v[44:45], v4, s[8:9]
	global_load_dwordx4 v[46:49], v5, s[38:39]
	s_add_u32 s8, s8, 0x4000
	s_addc_u32 s9, s9, 0
	s_sub_u32 s38, s38, 0x800
	s_subb_u32 s39, s39, 0
	global_load_dwordx2 v[50:51], v4, s[8:9]
	global_load_dwordx4 v[52:55], v5, s[38:39]
	s_add_u32 s8, s8, 0x4000
	s_addc_u32 s9, s9, 0
	s_sub_u32 s38, s38, 0x800
	s_subb_u32 s39, s39, 0
	s_mov_b64 s[38:39], s[40:41]
	global_load_dwordx2 v[56:57], v4, s[8:9]
	global_load_dwordx4 v[58:61], v5, s[38:39]
	s_add_u32 s8, s8, 0x4000
	s_addc_u32 s9, s9, 0
	s_sub_u32 s38, s38, 0x800
	s_subb_u32 s39, s39, 0
	global_load_dwordx2 v[62:63], v4, s[8:9]
	global_load_dwordx4 v[64:67], v5, s[38:39]
	s_add_u32 s8, s8, 0x4000
	s_addc_u32 s9, s9, 0
	s_sub_u32 s38, s38, 0x800
	s_subb_u32 s39, s39, 0
	global_load_dwordx2 v[68:69], v4, s[8:9]
	global_load_dwordx4 v[70:73], v5, s[38:39]
	s_add_u32 s8, s8, 0x4000
	s_addc_u32 s9, s9, 0
	s_sub_u32 s38, s38, 0x800
	s_subb_u32 s39, s39, 0
	global_load_dwordx2 v[74:75], v4, s[8:9]
	global_load_dwordx4 v[76:79], v5, s[38:39]
	s_add_u32 s8, s8, 0x4000
	s_addc_u32 s9, s9, 0
	s_sub_u32 s38, s38, 0x800
	s_subb_u32 s39, s39, 0
	global_load_dwordx2 v[80:81], v4, s[8:9]
	global_load_dwordx4 v[82:85], v5, s[38:39]
	s_add_u32 s8, s8, 0x4000
; __device__ __forceinline__ unsigned pk2(float lo, float hi) { return pg8::pkc(lo, hi); }
; __device__ __forceinline__ void ph_g2(Frame& F) {
;     ...
;         for (int s = 0; s < 68; ++s) {
;             const v2u uw = *(const v2u*)(UT + base + (size_t)s * 8192);
;             const int rc = chain_slot_rc(b, dir, s);
;             const f32x4 a = *(const f32x4*)(AL + (size_t)(dir * NRC + rc) * 512 + 64 * h + dk4);
;             v2u o; if (dir) { o.x = pk2(S0 * a.x, S1 * a.y); o.y = pk2(S2 * a.z, S3 * a.w); } else { o.x = pk2(S0, S1); o.y = pk2(S2, S3); }
;             *(v2u*)(ST + base + (size_t)s * 8192) = o;
;             S0 = fmaf(a.x, S0, bflo(uw.x)); S1 = fmaf(a.y, S1, bfhi(uw.x)); S2 = fmaf(a.z, S2, bflo(uw.y)); S3 = fmaf(a.w, S3, bfhi(uw.y));
	s_addc_u32 s9, s9, 0
	s_sub_u32 s38, s38, 0x800
	s_subb_u32 s39, s39, 0
	global_load_dwordx2 v[86:87], v4, s[8:9]
	global_load_dwordx4 v[88:91], v5, s[38:39]
	s_add_u32 s8, s8, 0x4000
	s_addc_u32 s9, s9, 0
	s_sub_u32 s38, s38, 0x800
	s_subb_u32 s39, s39, 0
	global_load_dwordx2 v[92:93], v4, s[8:9]
	global_load_dwordx4 v[94:97], v5, s[38:39]
	s_add_u32 s8, s8, 0x4000
	s_addc_u32 s9, s9, 0
	s_sub_u32 s38, s38, 0x800
	s_subb_u32 s39, s39, 0
	global_load_dwordx2 v[98:99], v4, s[8:9]
	global_load_dwordx4 v[100:103], v5, s[38:39]
	s_add_u32 s8, s8, 0x4000
	s_addc_u32 s9, s9, 0
	s_sub_u32 s38, s38, 0x800
	s_subb_u32 s39, s39, 0
	global_load_dwordx2 v[104:105], v4, s[8:9]
	global_load_dwordx4 v[106:109], v5, s[38:39]
	s_add_u32 s8, s8, 0x4000
	s_addc_u32 s9, s9, 0
	s_sub_u32 s38, s38, 0x800
	s_subb_u32 s39, s39, 0
	global_load_dwordx2 v[110:111], v4, s[8:9]
	global_load_dwordx4 v[112:115], v5, s[38:39]
	s_add_u32 s8, s8, 0x4000
	s_addc_u32 s9, s9, 0
	s_sub_u32 s38, s38, 0x800
	s_subb_u32 s39, s39, 0
	global_load_dwordx2 v[116:117], v4, s[8:9]
	global_load_dwordx4 v[118:121], v5, s[38:39]
	s_add_u32 s8, s8, 0x4000
	s_addc_u32 s9, s9, 0
	s_sub_u32 s38, s38, 0x800
	s_subb_u32 s39, s39, 0
	global_load_dwordx2 v[122:123], v4, s[8:9]
	global_load_dwordx4 v[124:127], v5, s[38:39]
	s_add_u32 s8, s8, 0x4000
	s_addc_u32 s9, s9, 0
	s_sub_u32 s38, s38, 0x800
	s_subb_u32 s39, s39, 0
	global_load_dwordx2 v[128:129], v4, s[8:9]
	global_load_dwordx4 v[130:133], v5, s[38:39]
	s_add_u32 s8, s8, 0x4000
	s_addc_u32 s9, s9, 0
	s_sub_u32 s38, s38, 0x800
	s_subb_u32 s39, s39, 0
	s_waitcnt vmcnt(32)
	v_pk_mul_f32 v[26:27], v[8:9], v[34:35]
	v_pk_mul_f32 v[28:29], v[10:11], v[36:37]
	v_cvt_pk_bf16_f32 v16, v26, v27
	v_cvt_pk_bf16_f32 v17, v28, v29
	global_store_dwordx2 v4, v[16:17], s[10:11]
	s_add_u32 s10, s10, 0x4000
	s_addc_u32 s11, s11, 0
	v_lshlrev_b32_e32 v12, 16, v32
	v_and_b32_e32 v13, 0xffff0000, v32
	v_lshlrev_b32_e32 v14, 16, v33
	v_and_b32_e32 v15, 0xffff0000, v33
	v_pk_fma_f32 v[8:9], v[34:35], v[8:9], v[12:13]
	v_pk_fma_f32 v[10:11], v[36:37], v[10:11], v[14:15]
	global_load_dwordx2 v[32:33], v4, s[8:9]
	global_load_dwordx4 v[34:37], v5, s[38:39]
	s_add_u32 s8, s8, 0x4000
	s_addc_u32 s9, s9, 0
	s_sub_u32 s38, s38, 0x800
	s_subb_u32 s39, s39, 0
	s_waitcnt vmcnt(33)
	v_pk_mul_f32 v[26:27], v[8:9], v[40:41]
	v_pk_mul_f32 v[28:29], v[10:11], v[42:43]
	v_cvt_pk_bf16_f32 v18, v26, v27
	v_cvt_pk_bf16_f32 v19, v28, v29
	global_store_dwordx2 v4, v[18:19], s[10:11]
	s_add_u32 s10, s10, 0x4000
	s_addc_u32 s11, s11, 0
	v_lshlrev_b32_e32 v12, 16, v38
	v_and_b32_e32 v13, 0xffff0000, v38
	v_lshlrev_b32_e32 v14, 16, v39
	v_and_b32_e32 v15, 0xffff0000, v39
	v_pk_fma_f32 v[8:9], v[40:41], v[8:9], v[12:13]
	v_pk_fma_f32 v[10:11], v[42:43], v[10:11], v[14:15]
	global_load_dwordx2 v[38:39], v4, s[8:9]
	global_load_dwordx4 v[40:43], v5, s[38:39]
	s_add_u32 s8, s8, 0x4000
	s_addc_u32 s9, s9, 0
	s_sub_u32 s38, s38, 0x800
	s_subb_u32 s39, s39, 0
	s_waitcnt vmcnt(34)
	v_pk_mul_f32 v[26:27], v[8:9], v[46:47]
	v_pk_mul_f32 v[28:29], v[10:11], v[48:49]
	v_cvt_pk_bf16_f32 v20, v26, v27
	v_cvt_pk_bf16_f32 v21, v28, v29
	global_store_dwordx2 v4, v[20:21], s[10:11]
	s_add_u32 s10, s10, 0x4000
	s_addc_u32 s11, s11, 0
	v_lshlrev_b32_e32 v12, 16, v44
	v_and_b32_e32 v13, 0xffff0000, v44
	v_lshlrev_b32_e32 v14, 16, v45
	v_and_b32_e32 v15, 0xffff0000, v45
	v_pk_fma_f32 v[8:9], v[46:47], v[8:9], v[12:13]
	v_pk_fma_f32 v[10:11], v[48:49], v[10:11], v[14:15]
	global_load_dwordx2 v[44:45], v4, s[8:9]
	global_load_dwordx4 v[46:49], v5, s[38:39]
	s_add_u32 s8, s8, 0x4000
	s_addc_u32 s9, s9, 0
	s_sub_u32 s38, s38, 0x800
	s_subb_u32 s39, s39, 0
	s_waitcnt vmcnt(35)
	v_pk_mul_f32 v[26:27], v[8:9], v[52:53]
	v_pk_mul_f32 v[28:29], v[10:11], v[54:55]
	v_cvt_pk_bf16_f32 v24, v26, v27
	v_cvt_pk_bf16_f32 v25, v28, v29
	global_store_dwordx2 v4, v[24:25], s[10:11]
	s_add_u32 s10, s10, 0x4000
	s_addc_u32 s11, s11, 0
	v_lshlrev_b32_e32 v12, 16, v50
	v_and_b32_e32 v13, 0xffff0000, v50
	v_lshlrev_b32_e32 v14, 16, v51
	v_and_b32_e32 v15, 0xffff0000, v51
	v_pk_fma_f32 v[8:9], v[52:53], v[8:9], v[12:13]
	v_pk_fma_f32 v[10:11], v[54:55], v[10:11], v[14:15]
	global_load_dwordx2 v[50:51], v4, s[8:9]
	global_load_dwordx4 v[52:55], v5, s[38:39]
	s_add_u32 s8, s8, 0x4000
	s_addc_u32 s9, s9, 0
	s_sub_u32 s38, s38, 0x800
	s_subb_u32 s39, s39, 0
	s_waitcnt vmcnt(36)
	v_pk_mul_f32 v[26:27], v[8:9], v[58:59]
	v_pk_mul_f32 v[28:29], v[10:11], v[60:61]
	v_cvt_pk_bf16_f32 v16, v26, v27
	v_cvt_pk_bf16_f32 v17, v28, v29
	global_store_dwordx2 v4, v[16:17], s[10:11]
	s_add_u32 s10, s10, 0x4000
	s_addc_u32 s11, s11, 0
	v_lshlrev_b32_e32 v12, 16, v56
	v_and_b32_e32 v13, 0xffff0000, v56
	v_lshlrev_b32_e32 v14, 16, v57
	v_and_b32_e32 v15, 0xffff0000, v57
	v_pk_fma_f32 v[8:9], v[58:59], v[8:9], v[12:13]
	v_pk_fma_f32 v[10:11], v[60:61], v[10:11], v[14:15]
	global_load_dwordx2 v[56:57], v4, s[8:9]
	global_load_dwordx4 v[58:61], v5, s[38:39]
	s_add_u32 s8, s8, 0x4000
	s_addc_u32 s9, s9, 0
	s_sub_u32 s38, s38, 0x800
	s_subb_u32 s39, s39, 0
	s_waitcnt vmcnt(37)
	v_pk_mul_f32 v[26:27], v[8:9], v[64:65]
	v_pk_mul_f32 v[28:29], v[10:11], v[66:67]
	v_cvt_pk_bf16_f32 v18, v26, v27
	v_cvt_pk_bf16_f32 v19, v28, v29
	global_store_dwordx2 v4, v[18:19], s[10:11]
	s_add_u32 s10, s10, 0x4000
	s_addc_u32 s11, s11, 0
	v_lshlrev_b32_e32 v12, 16, v62
	v_and_b32_e32 v13, 0xffff0000, v62
	v_lshlrev_b32_e32 v14, 16, v63
	v_and_b32_e32 v15, 0xffff0000, v63
	v_pk_fma_f32 v[8:9], v[64:65], v[8:9], v[12:13]
	v_pk_fma_f32 v[10:11], v[66:67], v[10:11], v[14:15]
	global_load_dwordx2 v[62:63], v4, s[8:9]
	global_load_dwordx4 v[64:67], v5, s[38:39]
	s_add_u32 s8, s8, 0x4000
	s_addc_u32 s9, s9, 0
	s_sub_u32 s38, s38, 0x800
	s_subb_u32 s39, s39, 0
	s_waitcnt vmcnt(38)
; __device__ __forceinline__ unsigned pk2(float lo, float hi) { return pg8::pkc(lo, hi); }
; __device__ __forceinline__ void ph_g2(Frame& F) {
;     ...
;         for (int s = 0; s < 68; ++s) {
;             const v2u uw = *(const v2u*)(UT + base + (size_t)s * 8192);
;             const int rc = chain_slot_rc(b, dir, s);
;             const f32x4 a = *(const f32x4*)(AL + (size_t)(dir * NRC + rc) * 512 + 64 * h + dk4);
;             v2u o; if (dir) { o.x = pk2(S0 * a.x, S1 * a.y); o.y = pk2(S2 * a.z, S3 * a.w); } else { o.x = pk2(S0, S1); o.y = pk2(S2, S3); }
;             *(v2u*)(ST + base + (size_t)s * 8192) = o;
;             S0 = fmaf(a.x, S0, bflo(uw.x)); S1 = fmaf(a.y, S1, bfhi(uw.x)); S2 = fmaf(a.z, S2, bflo(uw.y)); S3 = fmaf(a.w, S3, bfhi(uw.y));
	v_pk_mul_f32 v[26:27], v[8:9], v[70:71]
	v_pk_mul_f32 v[28:29], v[10:11], v[72:73]
	v_cvt_pk_bf16_f32 v20, v26, v27
	v_cvt_pk_bf16_f32 v21, v28, v29
	global_store_dwordx2 v4, v[20:21], s[10:11]
	s_add_u32 s10, s10, 0x4000
	s_addc_u32 s11, s11, 0
	v_lshlrev_b32_e32 v12, 16, v68
	v_and_b32_e32 v13, 0xffff0000, v68
	v_lshlrev_b32_e32 v14, 16, v69
	v_and_b32_e32 v15, 0xffff0000, v69
	v_pk_fma_f32 v[8:9], v[70:71], v[8:9], v[12:13]
	v_pk_fma_f32 v[10:11], v[72:73], v[10:11], v[14:15]
	global_load_dwordx2 v[68:69], v4, s[8:9]
	global_load_dwordx4 v[70:73], v5, s[38:39]
	s_add_u32 s8, s8, 0x4000
	s_addc_u32 s9, s9, 0
	s_sub_u32 s38, s38, 0x800
	s_subb_u32 s39, s39, 0
	s_waitcnt vmcnt(39)
	v_pk_mul_f32 v[26:27], v[8:9], v[76:77]
	v_pk_mul_f32 v[28:29], v[10:11], v[78:79]
	v_cvt_pk_bf16_f32 v24, v26, v27
	v_cvt_pk_bf16_f32 v25, v28, v29
	global_store_dwordx2 v4, v[24:25], s[10:11]
	s_add_u32 s10, s10, 0x4000
	s_addc_u32 s11, s11, 0
	v_lshlrev_b32_e32 v12, 16, v74
	v_and_b32_e32 v13, 0xffff0000, v74
	v_lshlrev_b32_e32 v14, 16, v75
	v_and_b32_e32 v15, 0xffff0000, v75
	v_pk_fma_f32 v[8:9], v[76:77], v[8:9], v[12:13]
	v_pk_fma_f32 v[10:11], v[78:79], v[10:11], v[14:15]
	global_load_dwordx2 v[74:75], v4, s[8:9]
	global_load_dwordx4 v[76:79], v5, s[38:39]
	s_add_u32 s8, s8, 0x4000
	s_addc_u32 s9, s9, 0
	s_sub_u32 s38, s38, 0x800
	s_subb_u32 s39, s39, 0
	s_waitcnt vmcnt(40)
	v_pk_mul_f32 v[26:27], v[8:9], v[82:83]
	v_pk_mul_f32 v[28:29], v[10:11], v[84:85]
	v_cvt_pk_bf16_f32 v16, v26, v27
	v_cvt_pk_bf16_f32 v17, v28, v29
	global_store_dwordx2 v4, v[16:17], s[10:11]
	s_add_u32 s10, s10, 0x4000
	s_addc_u32 s11, s11, 0
	v_lshlrev_b32_e32 v12, 16, v80
	v_and_b32_e32 v13, 0xffff0000, v80
	v_lshlrev_b32_e32 v14, 16, v81
	v_and_b32_e32 v15, 0xffff0000, v81
	v_pk_fma_f32 v[8:9], v[82:83], v[8:9], v[12:13]
	v_pk_fma_f32 v[10:11], v[84:85], v[10:11], v[14:15]
	global_load_dwordx2 v[80:81], v4, s[8:9]
	global_load_dwordx4 v[82:85], v5, s[38:39]
	s_add_u32 s8, s8, 0x4000
	s_addc_u32 s9, s9, 0
	s_sub_u32 s38, s38, 0x800
	s_subb_u32 s39, s39, 0
	s_waitcnt vmcnt(41)
	v_pk_mul_f32 v[26:27], v[8:9], v[88:89]
	v_pk_mul_f32 v[28:29], v[10:11], v[90:91]
	v_cvt_pk_bf16_f32 v18, v26, v27
	v_cvt_pk_bf16_f32 v19, v28, v29
	global_store_dwordx2 v4, v[18:19], s[10:11]
	s_add_u32 s10, s10, 0x4000
	s_addc_u32 s11, s11, 0
	v_lshlrev_b32_e32 v12, 16, v86
	v_and_b32_e32 v13, 0xffff0000, v86
	v_lshlrev_b32_e32 v14, 16, v87
	v_and_b32_e32 v15, 0xffff0000, v87
	v_pk_fma_f32 v[8:9], v[88:89], v[8:9], v[12:13]
	v_pk_fma_f32 v[10:11], v[90:91], v[10:11], v[14:15]
	global_load_dwordx2 v[86:87], v4, s[8:9]
	global_load_dwordx4 v[88:91], v5, s[38:39]
	s_add_u32 s8, s8, 0x4000
	s_addc_u32 s9, s9, 0
	s_sub_u32 s38, s38, 0x800
	s_subb_u32 s39, s39, 0
	s_waitcnt vmcnt(42)
	v_pk_mul_f32 v[26:27], v[8:9], v[94:95]
	v_pk_mul_f32 v[28:29], v[10:11], v[96:97]
	v_cvt_pk_bf16_f32 v20, v26, v27
	v_cvt_pk_bf16_f32 v21, v28, v29
	global_store_dwordx2 v4, v[20:21], s[10:11]
	s_add_u32 s10, s10, 0x4000
	s_addc_u32 s11, s11, 0
	v_lshlrev_b32_e32 v12, 16, v92
	v_and_b32_e32 v13, 0xffff0000, v92
	v_lshlrev_b32_e32 v14, 16, v93
	v_and_b32_e32 v15, 0xffff0000, v93
	v_pk_fma_f32 v[8:9], v[94:95], v[8:9], v[12:13]
	v_pk_fma_f32 v[10:11], v[96:97], v[10:11], v[14:15]
	global_load_dwordx2 v[92:93], v4, s[8:9]
	global_load_dwordx4 v[94:97], v5, s[38:39]
	s_add_u32 s8, s8, 0x4000
	s_addc_u32 s9, s9, 0
	s_sub_u32 s38, s38, 0x800
	s_subb_u32 s39, s39, 0
	s_waitcnt vmcnt(43)
	v_pk_mul_f32 v[26:27], v[8:9], v[100:101]
	v_pk_mul_f32 v[28:29], v[10:11], v[102:103]
	v_cvt_pk_bf16_f32 v24, v26, v27
	v_cvt_pk_bf16_f32 v25, v28, v29
	global_store_dwordx2 v4, v[24:25], s[10:11]
	s_add_u32 s10, s10, 0x4000
	s_addc_u32 s11, s11, 0
	v_lshlrev_b32_e32 v12, 16, v98
	v_and_b32_e32 v13, 0xffff0000, v98
	v_lshlrev_b32_e32 v14, 16, v99
	v_and_b32_e32 v15, 0xffff0000, v99
	v_pk_fma_f32 v[8:9], v[100:101], v[8:9], v[12:13]
	v_pk_fma_f32 v[10:11], v[102:103], v[10:11], v[14:15]
	global_load_dwordx2 v[98:99], v4, s[8:9]
	global_load_dwordx4 v[100:103], v5, s[38:39]
	s_add_u32 s8, s8, 0x4000
	s_addc_u32 s9, s9, 0
	s_sub_u32 s38, s38, 0x800
	s_subb_u32 s39, s39, 0
	s_waitcnt vmcnt(44)
	v_pk_mul_f32 v[26:27], v[8:9], v[106:107]
	v_pk_mul_f32 v[28:29], v[10:11], v[108:109]
	v_cvt_pk_bf16_f32 v16, v26, v27
	v_cvt_pk_bf16_f32 v17, v28, v29
	global_store_dwordx2 v4, v[16:17], s[10:11]
	s_add_u32 s10, s10, 0x4000
	s_addc_u32 s11, s11, 0
	v_lshlrev_b32_e32 v12, 16, v104
	v_and_b32_e32 v13, 0xffff0000, v104
	v_lshlrev_b32_e32 v14, 16, v105
	v_and_b32_e32 v15, 0xffff0000, v105
	v_pk_fma_f32 v[8:9], v[106:107], v[8:9], v[12:13]
	v_pk_fma_f32 v[10:11], v[108:109], v[10:11], v[14:15]
	global_load_dwordx2 v[104:105], v4, s[8:9]
	global_load_dwordx4 v[106:109], v5, s[38:39]
	s_add_u32 s8, s8, 0x4000
	s_addc_u32 s9, s9, 0
	s_sub_u32 s38, s38, 0x800
	s_subb_u32 s39, s39, 0
	s_waitcnt vmcnt(45)
	v_pk_mul_f32 v[26:27], v[8:9], v[112:113]
	v_pk_mul_f32 v[28:29], v[10:11], v[114:115]
	v_cvt_pk_bf16_f32 v18, v26, v27
	v_cvt_pk_bf16_f32 v19, v28, v29
	global_store_dwordx2 v4, v[18:19], s[10:11]
	s_add_u32 s10, s10, 0x4000
	s_addc_u32 s11, s11, 0
	v_lshlrev_b32_e32 v12, 16, v110
	v_and_b32_e32 v13, 0xffff0000, v110
	v_lshlrev_b32_e32 v14, 16, v111
	v_and_b32_e32 v15, 0xffff0000, v111
	v_pk_fma_f32 v[8:9], v[112:113], v[8:9], v[12:13]
	v_pk_fma_f32 v[10:11], v[114:115], v[10:11], v[14:15]
	global_load_dwordx2 v[110:111], v4, s[8:9]
	global_load_dwordx4 v[112:115], v5, s[38:39]
	s_add_u32 s8, s8, 0x4000
	s_addc_u32 s9, s9, 0
	s_sub_u32 s38, s38, 0x800
	s_subb_u32 s39, s39, 0
	s_waitcnt vmcnt(46)
; __device__ __forceinline__ unsigned pk2(float lo, float hi) { return pg8::pkc(lo, hi); }
; __device__ __forceinline__ void ph_g2(Frame& F) {
;     ...
;         for (int s = 0; s < 68; ++s) {
;             const v2u uw = *(const v2u*)(UT + base + (size_t)s * 8192);
;             const int rc = chain_slot_rc(b, dir, s);
;             const f32x4 a = *(const f32x4*)(AL + (size_t)(dir * NRC + rc) * 512 + 64 * h + dk4);
;             v2u o; if (dir) { o.x = pk2(S0 * a.x, S1 * a.y); o.y = pk2(S2 * a.z, S3 * a.w); } else { o.x = pk2(S0, S1); o.y = pk2(S2, S3); }
;             *(v2u*)(ST + base + (size_t)s * 8192) = o;
;             S0 = fmaf(a.x, S0, bflo(uw.x)); S1 = fmaf(a.y, S1, bfhi(uw.x)); S2 = fmaf(a.z, S2, bflo(uw.y)); S3 = fmaf(a.w, S3, bfhi(uw.y));
	v_pk_mul_f32 v[26:27], v[8:9], v[118:119]
	v_pk_mul_f32 v[28:29], v[10:11], v[120:121]
	v_cvt_pk_bf16_f32 v20, v26, v27
	v_cvt_pk_bf16_f32 v21, v28, v29
	global_store_dwordx2 v4, v[20:21], s[10:11]
	s_add_u32 s10, s10, 0x4000
	s_addc_u32 s11, s11, 0
	v_lshlrev_b32_e32 v12, 16, v116
	v_and_b32_e32 v13, 0xffff0000, v116
	v_lshlrev_b32_e32 v14, 16, v117
	v_and_b32_e32 v15, 0xffff0000, v117
	v_pk_fma_f32 v[8:9], v[118:119], v[8:9], v[12:13]
	v_pk_fma_f32 v[10:11], v[120:121], v[10:11], v[14:15]
	global_load_dwordx2 v[116:117], v4, s[8:9]
	global_load_dwordx4 v[118:121], v5, s[38:39]
	s_add_u32 s8, s8, 0x4000
	s_addc_u32 s9, s9, 0
	s_sub_u32 s38, s38, 0x800
	s_subb_u32 s39, s39, 0
	s_waitcnt vmcnt(47)
	v_pk_mul_f32 v[26:27], v[8:9], v[124:125]
	v_pk_mul_f32 v[28:29], v[10:11], v[126:127]
	v_cvt_pk_bf16_f32 v24, v26, v27
	v_cvt_pk_bf16_f32 v25, v28, v29
	global_store_dwordx2 v4, v[24:25], s[10:11]
	s_add_u32 s10, s10, 0x4000
	s_addc_u32 s11, s11, 0
	v_lshlrev_b32_e32 v12, 16, v122
	v_and_b32_e32 v13, 0xffff0000, v122
	v_lshlrev_b32_e32 v14, 16, v123
	v_and_b32_e32 v15, 0xffff0000, v123
	v_pk_fma_f32 v[8:9], v[124:125], v[8:9], v[12:13]
	v_pk_fma_f32 v[10:11], v[126:127], v[10:11], v[14:15]
	global_load_dwordx2 v[122:123], v4, s[8:9]
	global_load_dwordx4 v[124:127], v5, s[38:39]
	s_add_u32 s8, s8, 0x4000
	s_addc_u32 s9, s9, 0
	s_sub_u32 s38, s38, 0x800
	s_subb_u32 s39, s39, 0
	s_waitcnt vmcnt(48)
	v_pk_mul_f32 v[26:27], v[8:9], v[130:131]
	v_pk_mul_f32 v[28:29], v[10:11], v[132:133]
	v_cvt_pk_bf16_f32 v16, v26, v27
	v_cvt_pk_bf16_f32 v17, v28, v29
	global_store_dwordx2 v4, v[16:17], s[10:11]
	s_add_u32 s10, s10, 0x4000
	s_addc_u32 s11, s11, 0
	v_lshlrev_b32_e32 v12, 16, v128
	v_and_b32_e32 v13, 0xffff0000, v128
	v_lshlrev_b32_e32 v14, 16, v129
	v_and_b32_e32 v15, 0xffff0000, v129
	v_pk_fma_f32 v[8:9], v[130:131], v[8:9], v[12:13]
	v_pk_fma_f32 v[10:11], v[132:133], v[10:11], v[14:15]
	global_load_dwordx2 v[128:129], v4, s[8:9]
	global_load_dwordx4 v[130:133], v5, s[38:39]
	s_add_u32 s8, s8, 0x4000
	s_addc_u32 s9, s9, 0
	s_sub_u32 s38, s38, 0x800
	s_subb_u32 s39, s39, 0
	s_waitcnt vmcnt(48)
	v_pk_mul_f32 v[26:27], v[8:9], v[34:35]
	v_pk_mul_f32 v[28:29], v[10:11], v[36:37]
	v_cvt_pk_bf16_f32 v18, v26, v27
	v_cvt_pk_bf16_f32 v19, v28, v29
	global_store_dwordx2 v4, v[18:19], s[10:11]
	s_add_u32 s10, s10, 0x4000
	s_addc_u32 s11, s11, 0
	v_lshlrev_b32_e32 v12, 16, v32
	v_and_b32_e32 v13, 0xffff0000, v32
	v_lshlrev_b32_e32 v14, 16, v33
	v_and_b32_e32 v15, 0xffff0000, v33
	v_pk_fma_f32 v[8:9], v[34:35], v[8:9], v[12:13]
	v_pk_fma_f32 v[10:11], v[36:37], v[10:11], v[14:15]
	global_load_dwordx2 v[32:33], v4, s[8:9]
	global_load_dwordx4 v[34:37], v5, s[38:39]
	s_add_u32 s8, s8, 0x4000
	s_addc_u32 s9, s9, 0
	s_sub_u32 s38, s38, 0x800
	s_subb_u32 s39, s39, 0
	s_waitcnt vmcnt(48)
	v_pk_mul_f32 v[26:27], v[8:9], v[40:41]
	v_pk_mul_f32 v[28:29], v[10:11], v[42:43]
	v_cvt_pk_bf16_f32 v20, v26, v27
	v_cvt_pk_bf16_f32 v21, v28, v29
	global_store_dwordx2 v4, v[20:21], s[10:11]
	s_add_u32 s10, s10, 0x4000
	s_addc_u32 s11, s11, 0
	v_lshlrev_b32_e32 v12, 16, v38
	v_and_b32_e32 v13, 0xffff0000, v38
	v_lshlrev_b32_e32 v14, 16, v39
	v_and_b32_e32 v15, 0xffff0000, v39
	v_pk_fma_f32 v[8:9], v[40:41], v[8:9], v[12:13]
	v_pk_fma_f32 v[10:11], v[42:43], v[10:11], v[14:15]
	global_load_dwordx2 v[38:39], v4, s[8:9]
	global_load_dwordx4 v[40:43], v5, s[38:39]
	s_add_u32 s8, s8, 0x4000
	s_addc_u32 s9, s9, 0
	s_sub_u32 s38, s38, 0x800
	s_subb_u32 s39, s39, 0
	s_waitcnt vmcnt(48)
	v_pk_mul_f32 v[26:27], v[8:9], v[46:47]
	v_pk_mul_f32 v[28:29], v[10:11], v[48:49]
	v_cvt_pk_bf16_f32 v24, v26, v27
	v_cvt_pk_bf16_f32 v25, v28, v29
	global_store_dwordx2 v4, v[24:25], s[10:11]
	s_add_u32 s10, s10, 0x4000
	s_addc_u32 s11, s11, 0
	v_lshlrev_b32_e32 v12, 16, v44
	v_and_b32_e32 v13, 0xffff0000, v44
	v_lshlrev_b32_e32 v14, 16, v45
	v_and_b32_e32 v15, 0xffff0000, v45
	v_pk_fma_f32 v[8:9], v[46:47], v[8:9], v[12:13]
	v_pk_fma_f32 v[10:11], v[48:49], v[10:11], v[14:15]
	global_load_dwordx2 v[44:45], v4, s[8:9]
	global_load_dwordx4 v[46:49], v5, s[38:39]
	s_add_u32 s8, s8, 0x4000
	s_addc_u32 s9, s9, 0
	s_sub_u32 s38, s38, 0x800
	s_subb_u32 s39, s39, 0
	s_waitcnt vmcnt(48)
	v_pk_mul_f32 v[26:27], v[8:9], v[52:53]
	v_pk_mul_f32 v[28:29], v[10:11], v[54:55]
	v_cvt_pk_bf16_f32 v16, v26, v27
	v_cvt_pk_bf16_f32 v17, v28, v29
	global_store_dwordx2 v4, v[16:17], s[10:11]
	s_add_u32 s10, s10, 0x4000
	s_addc_u32 s11, s11, 0
	v_lshlrev_b32_e32 v12, 16, v50
	v_and_b32_e32 v13, 0xffff0000, v50
	v_lshlrev_b32_e32 v14, 16, v51
	v_and_b32_e32 v15, 0xffff0000, v51
	v_pk_fma_f32 v[8:9], v[52:53], v[8:9], v[12:13]
	v_pk_fma_f32 v[10:11], v[54:55], v[10:11], v[14:15]
	global_load_dwordx2 v[50:51], v4, s[8:9]
	global_load_dwordx4 v[52:55], v5, s[38:39]
	s_add_u32 s8, s8, 0x4000
	s_addc_u32 s9, s9, 0
	s_sub_u32 s38, s38, 0x800
	s_subb_u32 s39, s39, 0
	s_waitcnt vmcnt(48)
	v_pk_mul_f32 v[26:27], v[8:9], v[58:59]
	v_pk_mul_f32 v[28:29], v[10:11], v[60:61]
	v_cvt_pk_bf16_f32 v18, v26, v27
	v_cvt_pk_bf16_f32 v19, v28, v29
	global_store_dwordx2 v4, v[18:19], s[10:11]
	s_add_u32 s10, s10, 0x4000
	s_addc_u32 s11, s11, 0
	v_lshlrev_b32_e32 v12, 16, v56
	v_and_b32_e32 v13, 0xffff0000, v56
	v_lshlrev_b32_e32 v14, 16, v57
	v_and_b32_e32 v15, 0xffff0000, v57
	v_pk_fma_f32 v[8:9], v[58:59], v[8:9], v[12:13]
	v_pk_fma_f32 v[10:11], v[60:61], v[10:11], v[14:15]
	global_load_dwordx2 v[56:57], v4, s[8:9]
	global_load_dwordx4 v[58:61], v5, s[38:39]
	s_add_u32 s8, s8, 0x4000
	s_addc_u32 s9, s9, 0
	s_sub_u32 s38, s38, 0x800
	s_subb_u32 s39, s39, 0
	s_waitcnt vmcnt(48)
; __device__ __forceinline__ unsigned pk2(float lo, float hi) { return pg8::pkc(lo, hi); }
; __device__ __forceinline__ void ph_g2(Frame& F) {
;     ...
;         for (int s = 0; s < 68; ++s) {
;             const v2u uw = *(const v2u*)(UT + base + (size_t)s * 8192);
;             const int rc = chain_slot_rc(b, dir, s);
;             const f32x4 a = *(const f32x4*)(AL + (size_t)(dir * NRC + rc) * 512 + 64 * h + dk4);
;             v2u o; if (dir) { o.x = pk2(S0 * a.x, S1 * a.y); o.y = pk2(S2 * a.z, S3 * a.w); } else { o.x = pk2(S0, S1); o.y = pk2(S2, S3); }
;             *(v2u*)(ST + base + (size_t)s * 8192) = o;
;             S0 = fmaf(a.x, S0, bflo(uw.x)); S1 = fmaf(a.y, S1, bfhi(uw.x)); S2 = fmaf(a.z, S2, bflo(uw.y)); S3 = fmaf(a.w, S3, bfhi(uw.y));
	v_pk_mul_f32 v[26:27], v[8:9], v[64:65]
	v_pk_mul_f32 v[28:29], v[10:11], v[66:67]
	v_cvt_pk_bf16_f32 v20, v26, v27
	v_cvt_pk_bf16_f32 v21, v28, v29
	global_store_dwordx2 v4, v[20:21], s[10:11]
	s_add_u32 s10, s10, 0x4000
	s_addc_u32 s11, s11, 0
	v_lshlrev_b32_e32 v12, 16, v62
	v_and_b32_e32 v13, 0xffff0000, v62
	v_lshlrev_b32_e32 v14, 16, v63
	v_and_b32_e32 v15, 0xffff0000, v63
	v_pk_fma_f32 v[8:9], v[64:65], v[8:9], v[12:13]
	v_pk_fma_f32 v[10:11], v[66:67], v[10:11], v[14:15]
	global_load_dwordx2 v[62:63], v4, s[8:9]
	global_load_dwordx4 v[64:67], v5, s[38:39]
	s_add_u32 s8, s8, 0x4000
	s_addc_u32 s9, s9, 0
	s_sub_u32 s38, s38, 0x800
	s_subb_u32 s39, s39, 0
	s_waitcnt vmcnt(48)
	v_pk_mul_f32 v[26:27], v[8:9], v[70:71]
	v_pk_mul_f32 v[28:29], v[10:11], v[72:73]
	v_cvt_pk_bf16_f32 v24, v26, v27
	v_cvt_pk_bf16_f32 v25, v28, v29
	global_store_dwordx2 v4, v[24:25], s[10:11]
	s_add_u32 s10, s10, 0x4000
	s_addc_u32 s11, s11, 0
	v_lshlrev_b32_e32 v12, 16, v68
	v_and_b32_e32 v13, 0xffff0000, v68
	v_lshlrev_b32_e32 v14, 16, v69
	v_and_b32_e32 v15, 0xffff0000, v69
	v_pk_fma_f32 v[8:9], v[70:71], v[8:9], v[12:13]
	v_pk_fma_f32 v[10:11], v[72:73], v[10:11], v[14:15]
	global_load_dwordx2 v[68:69], v4, s[8:9]
	global_load_dwordx4 v[70:73], v5, s[38:39]
	s_add_u32 s8, s8, 0x4000
	s_addc_u32 s9, s9, 0
	s_sub_u32 s38, s38, 0x800
	s_subb_u32 s39, s39, 0
	s_waitcnt vmcnt(48)
	v_pk_mul_f32 v[26:27], v[8:9], v[76:77]
	v_pk_mul_f32 v[28:29], v[10:11], v[78:79]
	v_cvt_pk_bf16_f32 v16, v26, v27
	v_cvt_pk_bf16_f32 v17, v28, v29
	global_store_dwordx2 v4, v[16:17], s[10:11]
	s_add_u32 s10, s10, 0x4000
	s_addc_u32 s11, s11, 0
	v_lshlrev_b32_e32 v12, 16, v74
	v_and_b32_e32 v13, 0xffff0000, v74
	v_lshlrev_b32_e32 v14, 16, v75
	v_and_b32_e32 v15, 0xffff0000, v75
	v_pk_fma_f32 v[8:9], v[76:77], v[8:9], v[12:13]
	v_pk_fma_f32 v[10:11], v[78:79], v[10:11], v[14:15]
	global_load_dwordx2 v[74:75], v4, s[8:9]
	global_load_dwordx4 v[76:79], v5, s[38:39]
	s_add_u32 s8, s8, 0x4000
	s_addc_u32 s9, s9, 0
	s_sub_u32 s38, s38, 0x800
	s_subb_u32 s39, s39, 0
	s_waitcnt vmcnt(48)
	v_pk_mul_f32 v[26:27], v[8:9], v[82:83]
	v_pk_mul_f32 v[28:29], v[10:11], v[84:85]
	v_cvt_pk_bf16_f32 v18, v26, v27
	v_cvt_pk_bf16_f32 v19, v28, v29
	global_store_dwordx2 v4, v[18:19], s[10:11]
	s_add_u32 s10, s10, 0x4000
	s_addc_u32 s11, s11, 0
	v_lshlrev_b32_e32 v12, 16, v80
	v_and_b32_e32 v13, 0xffff0000, v80
	v_lshlrev_b32_e32 v14, 16, v81
	v_and_b32_e32 v15, 0xffff0000, v81
	v_pk_fma_f32 v[8:9], v[82:83], v[8:9], v[12:13]
	v_pk_fma_f32 v[10:11], v[84:85], v[10:11], v[14:15]
	global_load_dwordx2 v[80:81], v4, s[8:9]
	global_load_dwordx4 v[82:85], v5, s[38:39]
	s_add_u32 s8, s8, 0x4000
	s_addc_u32 s9, s9, 0
	s_sub_u32 s38, s38, 0x800
	s_subb_u32 s39, s39, 0
	s_waitcnt vmcnt(48)
	v_pk_mul_f32 v[26:27], v[8:9], v[88:89]
	v_pk_mul_f32 v[28:29], v[10:11], v[90:91]
	v_cvt_pk_bf16_f32 v20, v26, v27
	v_cvt_pk_bf16_f32 v21, v28, v29
	global_store_dwordx2 v4, v[20:21], s[10:11]
	s_add_u32 s10, s10, 0x4000
	s_addc_u32 s11, s11, 0
	v_lshlrev_b32_e32 v12, 16, v86
	v_and_b32_e32 v13, 0xffff0000, v86
	v_lshlrev_b32_e32 v14, 16, v87
	v_and_b32_e32 v15, 0xffff0000, v87
	v_pk_fma_f32 v[8:9], v[88:89], v[8:9], v[12:13]
	v_pk_fma_f32 v[10:11], v[90:91], v[10:11], v[14:15]
	global_load_dwordx2 v[86:87], v4, s[8:9]
	global_load_dwordx4 v[88:91], v5, s[38:39]
	s_add_u32 s8, s8, 0x4000
	s_addc_u32 s9, s9, 0
	s_sub_u32 s38, s38, 0x800
	s_subb_u32 s39, s39, 0
	s_waitcnt vmcnt(48)
	v_pk_mul_f32 v[26:27], v[8:9], v[94:95]
	v_pk_mul_f32 v[28:29], v[10:11], v[96:97]
	v_cvt_pk_bf16_f32 v24, v26, v27
	v_cvt_pk_bf16_f32 v25, v28, v29
	global_store_dwordx2 v4, v[24:25], s[10:11]
	s_add_u32 s10, s10, 0x4000
	s_addc_u32 s11, s11, 0
	v_lshlrev_b32_e32 v12, 16, v92
	v_and_b32_e32 v13, 0xffff0000, v92
	v_lshlrev_b32_e32 v14, 16, v93
	v_and_b32_e32 v15, 0xffff0000, v93
	v_pk_fma_f32 v[8:9], v[94:95], v[8:9], v[12:13]
	v_pk_fma_f32 v[10:11], v[96:97], v[10:11], v[14:15]
	global_load_dwordx2 v[92:93], v4, s[8:9]
	global_load_dwordx4 v[94:97], v5, s[38:39]
	s_add_u32 s8, s8, 0x4000
	s_addc_u32 s9, s9, 0
	s_sub_u32 s38, s38, 0x800
	s_subb_u32 s39, s39, 0
	s_waitcnt vmcnt(48)
	v_pk_mul_f32 v[26:27], v[8:9], v[100:101]
	v_pk_mul_f32 v[28:29], v[10:11], v[102:103]
	v_cvt_pk_bf16_f32 v16, v26, v27
	v_cvt_pk_bf16_f32 v17, v28, v29
	global_store_dwordx2 v4, v[16:17], s[10:11]
	s_add_u32 s10, s10, 0x4000
	s_addc_u32 s11, s11, 0
	v_lshlrev_b32_e32 v12, 16, v98
	v_and_b32_e32 v13, 0xffff0000, v98
	v_lshlrev_b32_e32 v14, 16, v99
	v_and_b32_e32 v15, 0xffff0000, v99
	v_pk_fma_f32 v[8:9], v[100:101], v[8:9], v[12:13]
	v_pk_fma_f32 v[10:11], v[102:103], v[10:11], v[14:15]
	global_load_dwordx2 v[98:99], v4, s[8:9]
	global_load_dwordx4 v[100:103], v5, s[38:39]
	s_add_u32 s8, s8, 0x4000
	s_addc_u32 s9, s9, 0
	s_sub_u32 s38, s38, 0x800
	s_subb_u32 s39, s39, 0
	s_waitcnt vmcnt(48)
	v_pk_mul_f32 v[26:27], v[8:9], v[106:107]
	v_pk_mul_f32 v[28:29], v[10:11], v[108:109]
	v_cvt_pk_bf16_f32 v18, v26, v27
	v_cvt_pk_bf16_f32 v19, v28, v29
	global_store_dwordx2 v4, v[18:19], s[10:11]
	s_add_u32 s10, s10, 0x4000
	s_addc_u32 s11, s11, 0
	v_lshlrev_b32_e32 v12, 16, v104
	v_and_b32_e32 v13, 0xffff0000, v104
	v_lshlrev_b32_e32 v14, 16, v105
	v_and_b32_e32 v15, 0xffff0000, v105
	v_pk_fma_f32 v[8:9], v[106:107], v[8:9], v[12:13]
	v_pk_fma_f32 v[10:11], v[108:109], v[10:11], v[14:15]
	global_load_dwordx2 v[104:105], v4, s[8:9]
	global_load_dwordx4 v[106:109], v5, s[38:39]
	s_add_u32 s8, s8, 0x4000
	s_addc_u32 s9, s9, 0
	s_sub_u32 s38, s38, 0x800
	s_subb_u32 s39, s39, 0
	s_waitcnt vmcnt(48)
; __device__ __forceinline__ unsigned pk2(float lo, float hi) { return pg8::pkc(lo, hi); }
; __device__ __forceinline__ void ph_g2(Frame& F) {
;     ...
;         for (int s = 0; s < 68; ++s) {
;             const v2u uw = *(const v2u*)(UT + base + (size_t)s * 8192);
;             const int rc = chain_slot_rc(b, dir, s);
;             const f32x4 a = *(const f32x4*)(AL + (size_t)(dir * NRC + rc) * 512 + 64 * h + dk4);
;             v2u o; if (dir) { o.x = pk2(S0 * a.x, S1 * a.y); o.y = pk2(S2 * a.z, S3 * a.w); } else { o.x = pk2(S0, S1); o.y = pk2(S2, S3); }
;             *(v2u*)(ST + base + (size_t)s * 8192) = o;
;             S0 = fmaf(a.x, S0, bflo(uw.x)); S1 = fmaf(a.y, S1, bfhi(uw.x)); S2 = fmaf(a.z, S2, bflo(uw.y)); S3 = fmaf(a.w, S3, bfhi(uw.y));
	v_pk_mul_f32 v[26:27], v[8:9], v[112:113]
	v_pk_mul_f32 v[28:29], v[10:11], v[114:115]
	v_cvt_pk_bf16_f32 v20, v26, v27
	v_cvt_pk_bf16_f32 v21, v28, v29
	global_store_dwordx2 v4, v[20:21], s[10:11]
	s_add_u32 s10, s10, 0x4000
	s_addc_u32 s11, s11, 0
	v_lshlrev_b32_e32 v12, 16, v110
	v_and_b32_e32 v13, 0xffff0000, v110
	v_lshlrev_b32_e32 v14, 16, v111
	v_and_b32_e32 v15, 0xffff0000, v111
	v_pk_fma_f32 v[8:9], v[112:113], v[8:9], v[12:13]
	v_pk_fma_f32 v[10:11], v[114:115], v[10:11], v[14:15]
	global_load_dwordx2 v[110:111], v4, s[8:9]
	global_load_dwordx4 v[112:115], v5, s[38:39]
	s_add_u32 s8, s8, 0x4000
	s_addc_u32 s9, s9, 0
	s_sub_u32 s38, s38, 0x800
	s_subb_u32 s39, s39, 0
	s_waitcnt vmcnt(48)
	v_pk_mul_f32 v[26:27], v[8:9], v[118:119]
	v_pk_mul_f32 v[28:29], v[10:11], v[120:121]
	v_cvt_pk_bf16_f32 v24, v26, v27
	v_cvt_pk_bf16_f32 v25, v28, v29
	global_store_dwordx2 v4, v[24:25], s[10:11]
	s_add_u32 s10, s10, 0x4000
	s_addc_u32 s11, s11, 0
	v_lshlrev_b32_e32 v12, 16, v116
	v_and_b32_e32 v13, 0xffff0000, v116
	v_lshlrev_b32_e32 v14, 16, v117
	v_and_b32_e32 v15, 0xffff0000, v117
	v_pk_fma_f32 v[8:9], v[118:119], v[8:9], v[12:13]
	v_pk_fma_f32 v[10:11], v[120:121], v[10:11], v[14:15]
	global_load_dwordx2 v[116:117], v4, s[8:9]
	global_load_dwordx4 v[118:121], v5, s[38:39]
	s_add_u32 s8, s8, 0x4000
	s_addc_u32 s9, s9, 0
	s_sub_u32 s38, s38, 0x800
	s_subb_u32 s39, s39, 0
	s_waitcnt vmcnt(48)
	v_pk_mul_f32 v[26:27], v[8:9], v[124:125]
	v_pk_mul_f32 v[28:29], v[10:11], v[126:127]
	v_cvt_pk_bf16_f32 v16, v26, v27
	v_cvt_pk_bf16_f32 v17, v28, v29
	global_store_dwordx2 v4, v[16:17], s[10:11]
	s_add_u32 s10, s10, 0x4000
	s_addc_u32 s11, s11, 0
	v_lshlrev_b32_e32 v12, 16, v122
	v_and_b32_e32 v13, 0xffff0000, v122
	v_lshlrev_b32_e32 v14, 16, v123
	v_and_b32_e32 v15, 0xffff0000, v123
	v_pk_fma_f32 v[8:9], v[124:125], v[8:9], v[12:13]
	v_pk_fma_f32 v[10:11], v[126:127], v[10:11], v[14:15]
	global_load_dwordx2 v[122:123], v4, s[8:9]
	global_load_dwordx4 v[124:127], v5, s[38:39]
	s_add_u32 s8, s8, 0x4000
	s_addc_u32 s9, s9, 0
	s_sub_u32 s38, s38, 0x800
	s_subb_u32 s39, s39, 0
	s_waitcnt vmcnt(48)
	v_pk_mul_f32 v[26:27], v[8:9], v[130:131]
	v_pk_mul_f32 v[28:29], v[10:11], v[132:133]
	v_cvt_pk_bf16_f32 v18, v26, v27
	v_cvt_pk_bf16_f32 v19, v28, v29
	global_store_dwordx2 v4, v[18:19], s[10:11]
	s_add_u32 s10, s10, 0x4000
	s_addc_u32 s11, s11, 0
	v_lshlrev_b32_e32 v12, 16, v128
	v_and_b32_e32 v13, 0xffff0000, v128
	v_lshlrev_b32_e32 v14, 16, v129
	v_and_b32_e32 v15, 0xffff0000, v129
	v_pk_fma_f32 v[8:9], v[130:131], v[8:9], v[12:13]
	v_pk_fma_f32 v[10:11], v[132:133], v[10:11], v[14:15]
	global_load_dwordx2 v[128:129], v4, s[8:9]
	global_load_dwordx4 v[130:133], v5, s[38:39]
	s_add_u32 s8, s8, 0x4000
	s_addc_u32 s9, s9, 0
	s_sub_u32 s38, s38, 0x800
	s_subb_u32 s39, s39, 0
	s_waitcnt vmcnt(48)
	v_pk_mul_f32 v[26:27], v[8:9], v[34:35]
	v_pk_mul_f32 v[28:29], v[10:11], v[36:37]
	v_cvt_pk_bf16_f32 v20, v26, v27
	v_cvt_pk_bf16_f32 v21, v28, v29
	global_store_dwordx2 v4, v[20:21], s[10:11]
	s_add_u32 s10, s10, 0x4000
	s_addc_u32 s11, s11, 0
	v_lshlrev_b32_e32 v12, 16, v32
	v_and_b32_e32 v13, 0xffff0000, v32
	v_lshlrev_b32_e32 v14, 16, v33
	v_and_b32_e32 v15, 0xffff0000, v33
	v_pk_fma_f32 v[8:9], v[34:35], v[8:9], v[12:13]
	v_pk_fma_f32 v[10:11], v[36:37], v[10:11], v[14:15]
	global_load_dwordx2 v[32:33], v4, s[8:9]
	global_load_dwordx4 v[34:37], v5, s[38:39]
	s_add_u32 s8, s8, 0x4000
	s_addc_u32 s9, s9, 0
	s_sub_u32 s38, s38, 0x800
	s_subb_u32 s39, s39, 0
	s_waitcnt vmcnt(48)
	v_pk_mul_f32 v[26:27], v[8:9], v[40:41]
	v_pk_mul_f32 v[28:29], v[10:11], v[42:43]
	v_cvt_pk_bf16_f32 v24, v26, v27
	v_cvt_pk_bf16_f32 v25, v28, v29
	global_store_dwordx2 v4, v[24:25], s[10:11]
	s_add_u32 s10, s10, 0x4000
	s_addc_u32 s11, s11, 0
	v_lshlrev_b32_e32 v12, 16, v38
	v_and_b32_e32 v13, 0xffff0000, v38
	v_lshlrev_b32_e32 v14, 16, v39
	v_and_b32_e32 v15, 0xffff0000, v39
	v_pk_fma_f32 v[8:9], v[40:41], v[8:9], v[12:13]
	v_pk_fma_f32 v[10:11], v[42:43], v[10:11], v[14:15]
	global_load_dwordx2 v[38:39], v4, s[8:9]
	global_load_dwordx4 v[40:43], v5, s[38:39]
	s_add_u32 s8, s8, 0x4000
	s_addc_u32 s9, s9, 0
	s_sub_u32 s38, s38, 0x800
	s_subb_u32 s39, s39, 0
	s_waitcnt vmcnt(48)
	v_pk_mul_f32 v[26:27], v[8:9], v[46:47]
	v_pk_mul_f32 v[28:29], v[10:11], v[48:49]
	v_cvt_pk_bf16_f32 v16, v26, v27
	v_cvt_pk_bf16_f32 v17, v28, v29
	global_store_dwordx2 v4, v[16:17], s[10:11]
	s_add_u32 s10, s10, 0x4000
	s_addc_u32 s11, s11, 0
	v_lshlrev_b32_e32 v12, 16, v44
	v_and_b32_e32 v13, 0xffff0000, v44
	v_lshlrev_b32_e32 v14, 16, v45
	v_and_b32_e32 v15, 0xffff0000, v45
	v_pk_fma_f32 v[8:9], v[46:47], v[8:9], v[12:13]
	v_pk_fma_f32 v[10:11], v[48:49], v[10:11], v[14:15]
	global_load_dwordx2 v[44:45], v4, s[8:9]
	global_load_dwordx4 v[46:49], v5, s[38:39]
	s_add_u32 s8, s8, 0x4000
	s_addc_u32 s9, s9, 0
	s_sub_u32 s38, s38, 0x800
	s_subb_u32 s39, s39, 0
	s_waitcnt vmcnt(48)
	v_pk_mul_f32 v[26:27], v[8:9], v[52:53]
	v_pk_mul_f32 v[28:29], v[10:11], v[54:55]
	v_cvt_pk_bf16_f32 v18, v26, v27
	v_cvt_pk_bf16_f32 v19, v28, v29
	global_store_dwordx2 v4, v[18:19], s[10:11]
	s_add_u32 s10, s10, 0x4000
	s_addc_u32 s11, s11, 0
	v_lshlrev_b32_e32 v12, 16, v50
	v_and_b32_e32 v13, 0xffff0000, v50
	v_lshlrev_b32_e32 v14, 16, v51
	v_and_b32_e32 v15, 0xffff0000, v51
	v_pk_fma_f32 v[8:9], v[52:53], v[8:9], v[12:13]
	v_pk_fma_f32 v[10:11], v[54:55], v[10:11], v[14:15]
	global_load_dwordx2 v[50:51], v4, s[8:9]
	global_load_dwordx4 v[52:55], v5, s[38:39]
	s_add_u32 s8, s8, 0x4000
	s_addc_u32 s9, s9, 0
	s_sub_u32 s38, s38, 0x800
	s_subb_u32 s39, s39, 0
	s_waitcnt vmcnt(48)
; __device__ __forceinline__ unsigned pk2(float lo, float hi) { return pg8::pkc(lo, hi); }
; __device__ __forceinline__ void ph_g2(Frame& F) {
;     ...
;         for (int s = 0; s < 68; ++s) {
;             const v2u uw = *(const v2u*)(UT + base + (size_t)s * 8192);
;             const int rc = chain_slot_rc(b, dir, s);
;             const f32x4 a = *(const f32x4*)(AL + (size_t)(dir * NRC + rc) * 512 + 64 * h + dk4);
;             v2u o; if (dir) { o.x = pk2(S0 * a.x, S1 * a.y); o.y = pk2(S2 * a.z, S3 * a.w); } else { o.x = pk2(S0, S1); o.y = pk2(S2, S3); }
;             *(v2u*)(ST + base + (size_t)s * 8192) = o;
;             S0 = fmaf(a.x, S0, bflo(uw.x)); S1 = fmaf(a.y, S1, bfhi(uw.x)); S2 = fmaf(a.z, S2, bflo(uw.y)); S3 = fmaf(a.w, S3, bfhi(uw.y));
	v_pk_mul_f32 v[26:27], v[8:9], v[58:59]
	v_pk_mul_f32 v[28:29], v[10:11], v[60:61]
	v_cvt_pk_bf16_f32 v20, v26, v27
	v_cvt_pk_bf16_f32 v21, v28, v29
	global_store_dwordx2 v4, v[20:21], s[10:11]
	s_add_u32 s10, s10, 0x4000
	s_addc_u32 s11, s11, 0
	v_lshlrev_b32_e32 v12, 16, v56
	v_and_b32_e32 v13, 0xffff0000, v56
	v_lshlrev_b32_e32 v14, 16, v57
	v_and_b32_e32 v15, 0xffff0000, v57
	v_pk_fma_f32 v[8:9], v[58:59], v[8:9], v[12:13]
	v_pk_fma_f32 v[10:11], v[60:61], v[10:11], v[14:15]
	global_load_dwordx2 v[56:57], v4, s[8:9]
	global_load_dwordx4 v[58:61], v5, s[38:39]
	s_add_u32 s8, s8, 0x4000
	s_addc_u32 s9, s9, 0
	s_sub_u32 s38, s38, 0x800
	s_subb_u32 s39, s39, 0
	s_waitcnt vmcnt(48)
	v_pk_mul_f32 v[26:27], v[8:9], v[64:65]
	v_pk_mul_f32 v[28:29], v[10:11], v[66:67]
	v_cvt_pk_bf16_f32 v24, v26, v27
	v_cvt_pk_bf16_f32 v25, v28, v29
	global_store_dwordx2 v4, v[24:25], s[10:11]
	s_add_u32 s10, s10, 0x4000
	s_addc_u32 s11, s11, 0
	v_lshlrev_b32_e32 v12, 16, v62
	v_and_b32_e32 v13, 0xffff0000, v62
	v_lshlrev_b32_e32 v14, 16, v63
	v_and_b32_e32 v15, 0xffff0000, v63
	v_pk_fma_f32 v[8:9], v[64:65], v[8:9], v[12:13]
	v_pk_fma_f32 v[10:11], v[66:67], v[10:11], v[14:15]
	global_load_dwordx2 v[62:63], v4, s[8:9]
	global_load_dwordx4 v[64:67], v5, s[38:39]
	s_add_u32 s8, s8, 0x4000
	s_addc_u32 s9, s9, 0
	s_sub_u32 s38, s38, 0x800
	s_subb_u32 s39, s39, 0
	s_waitcnt vmcnt(48)
	v_pk_mul_f32 v[26:27], v[8:9], v[70:71]
	v_pk_mul_f32 v[28:29], v[10:11], v[72:73]
	v_cvt_pk_bf16_f32 v16, v26, v27
	v_cvt_pk_bf16_f32 v17, v28, v29
	global_store_dwordx2 v4, v[16:17], s[10:11]
	s_add_u32 s10, s10, 0x4000
	s_addc_u32 s11, s11, 0
	v_lshlrev_b32_e32 v12, 16, v68
	v_and_b32_e32 v13, 0xffff0000, v68
	v_lshlrev_b32_e32 v14, 16, v69
	v_and_b32_e32 v15, 0xffff0000, v69
	v_pk_fma_f32 v[8:9], v[70:71], v[8:9], v[12:13]
	v_pk_fma_f32 v[10:11], v[72:73], v[10:11], v[14:15]
	global_load_dwordx2 v[68:69], v4, s[8:9]
	global_load_dwordx4 v[70:73], v5, s[38:39]
	s_add_u32 s8, s8, 0x4000
	s_addc_u32 s9, s9, 0
	s_sub_u32 s38, s38, 0x800
	s_subb_u32 s39, s39, 0
	s_waitcnt vmcnt(48)
	v_pk_mul_f32 v[26:27], v[8:9], v[76:77]
	v_pk_mul_f32 v[28:29], v[10:11], v[78:79]
	v_cvt_pk_bf16_f32 v18, v26, v27
	v_cvt_pk_bf16_f32 v19, v28, v29
	global_store_dwordx2 v4, v[18:19], s[10:11]
	s_add_u32 s10, s10, 0x4000
	s_addc_u32 s11, s11, 0
	v_lshlrev_b32_e32 v12, 16, v74
	v_and_b32_e32 v13, 0xffff0000, v74
	v_lshlrev_b32_e32 v14, 16, v75
	v_and_b32_e32 v15, 0xffff0000, v75
	v_pk_fma_f32 v[8:9], v[76:77], v[8:9], v[12:13]
	v_pk_fma_f32 v[10:11], v[78:79], v[10:11], v[14:15]
	global_load_dwordx2 v[74:75], v4, s[8:9]
	global_load_dwordx4 v[76:79], v5, s[38:39]
	s_add_u32 s8, s8, 0x4000
	s_addc_u32 s9, s9, 0
	s_sub_u32 s38, s38, 0x800
	s_subb_u32 s39, s39, 0
	s_waitcnt vmcnt(48)
	v_pk_mul_f32 v[26:27], v[8:9], v[82:83]
	v_pk_mul_f32 v[28:29], v[10:11], v[84:85]
	v_cvt_pk_bf16_f32 v20, v26, v27
	v_cvt_pk_bf16_f32 v21, v28, v29
	global_store_dwordx2 v4, v[20:21], s[10:11]
	s_add_u32 s10, s10, 0x4000
	s_addc_u32 s11, s11, 0
	v_lshlrev_b32_e32 v12, 16, v80
	v_and_b32_e32 v13, 0xffff0000, v80
	v_lshlrev_b32_e32 v14, 16, v81
	v_and_b32_e32 v15, 0xffff0000, v81
	v_pk_fma_f32 v[8:9], v[82:83], v[8:9], v[12:13]
	v_pk_fma_f32 v[10:11], v[84:85], v[10:11], v[14:15]
	global_load_dwordx2 v[80:81], v4, s[8:9]
	global_load_dwordx4 v[82:85], v5, s[38:39]
	s_add_u32 s8, s8, 0x4000
	s_addc_u32 s9, s9, 0
	s_sub_u32 s38, s38, 0x800
	s_subb_u32 s39, s39, 0
	s_waitcnt vmcnt(48)
	v_pk_mul_f32 v[26:27], v[8:9], v[88:89]
	v_pk_mul_f32 v[28:29], v[10:11], v[90:91]
	v_cvt_pk_bf16_f32 v24, v26, v27
	v_cvt_pk_bf16_f32 v25, v28, v29
	global_store_dwordx2 v4, v[24:25], s[10:11]
	s_add_u32 s10, s10, 0x4000
	s_addc_u32 s11, s11, 0
	v_lshlrev_b32_e32 v12, 16, v86
	v_and_b32_e32 v13, 0xffff0000, v86
	v_lshlrev_b32_e32 v14, 16, v87
	v_and_b32_e32 v15, 0xffff0000, v87
	v_pk_fma_f32 v[8:9], v[88:89], v[8:9], v[12:13]
	v_pk_fma_f32 v[10:11], v[90:91], v[10:11], v[14:15]
	global_load_dwordx2 v[86:87], v4, s[8:9]
	global_load_dwordx4 v[88:91], v5, s[38:39]
	s_add_u32 s8, s8, 0x4000
	s_addc_u32 s9, s9, 0
	s_sub_u32 s38, s38, 0x800
	s_subb_u32 s39, s39, 0
	s_waitcnt vmcnt(48)
	v_pk_mul_f32 v[26:27], v[8:9], v[94:95]
	v_pk_mul_f32 v[28:29], v[10:11], v[96:97]
	v_cvt_pk_bf16_f32 v16, v26, v27
	v_cvt_pk_bf16_f32 v17, v28, v29
	global_store_dwordx2 v4, v[16:17], s[10:11]
	s_add_u32 s10, s10, 0x4000
	s_addc_u32 s11, s11, 0
	v_lshlrev_b32_e32 v12, 16, v92
	v_and_b32_e32 v13, 0xffff0000, v92
	v_lshlrev_b32_e32 v14, 16, v93
	v_and_b32_e32 v15, 0xffff0000, v93
	v_pk_fma_f32 v[8:9], v[94:95], v[8:9], v[12:13]
	v_pk_fma_f32 v[10:11], v[96:97], v[10:11], v[14:15]
	global_load_dwordx2 v[92:93], v4, s[8:9]
	global_load_dwordx4 v[94:97], v5, s[38:39]
	s_add_u32 s8, s8, 0x4000
	s_addc_u32 s9, s9, 0
	s_sub_u32 s38, s38, 0x800
	s_subb_u32 s39, s39, 0
	s_waitcnt vmcnt(48)
	v_pk_mul_f32 v[26:27], v[8:9], v[100:101]
	v_pk_mul_f32 v[28:29], v[10:11], v[102:103]
	v_cvt_pk_bf16_f32 v18, v26, v27
	v_cvt_pk_bf16_f32 v19, v28, v29
	global_store_dwordx2 v4, v[18:19], s[10:11]
	s_add_u32 s10, s10, 0x4000
	s_addc_u32 s11, s11, 0
	v_lshlrev_b32_e32 v12, 16, v98
	v_and_b32_e32 v13, 0xffff0000, v98
	v_lshlrev_b32_e32 v14, 16, v99
	v_and_b32_e32 v15, 0xffff0000, v99
	v_pk_fma_f32 v[8:9], v[100:101], v[8:9], v[12:13]
	v_pk_fma_f32 v[10:11], v[102:103], v[10:11], v[14:15]
	global_load_dwordx2 v[98:99], v4, s[8:9]
	global_load_dwordx4 v[100:103], v5, s[38:39]
	s_add_u32 s8, s8, 0x4000
	s_addc_u32 s9, s9, 0
	s_sub_u32 s38, s38, 0x800
	s_subb_u32 s39, s39, 0
	s_waitcnt vmcnt(48)
; __device__ __forceinline__ unsigned pk2(float lo, float hi) { return pg8::pkc(lo, hi); }
; __device__ __forceinline__ void ph_g2(Frame& F) {
;     ...
;         for (int s = 0; s < 68; ++s) {
;             const v2u uw = *(const v2u*)(UT + base + (size_t)s * 8192);
;             const int rc = chain_slot_rc(b, dir, s);
;             const f32x4 a = *(const f32x4*)(AL + (size_t)(dir * NRC + rc) * 512 + 64 * h + dk4);
;             v2u o; if (dir) { o.x = pk2(S0 * a.x, S1 * a.y); o.y = pk2(S2 * a.z, S3 * a.w); } else { o.x = pk2(S0, S1); o.y = pk2(S2, S3); }
;             *(v2u*)(ST + base + (size_t)s * 8192) = o;
;             S0 = fmaf(a.x, S0, bflo(uw.x)); S1 = fmaf(a.y, S1, bfhi(uw.x)); S2 = fmaf(a.z, S2, bflo(uw.y)); S3 = fmaf(a.w, S3, bfhi(uw.y));
	v_pk_mul_f32 v[26:27], v[8:9], v[106:107]
	v_pk_mul_f32 v[28:29], v[10:11], v[108:109]
	v_cvt_pk_bf16_f32 v20, v26, v27
	v_cvt_pk_bf16_f32 v21, v28, v29
	global_store_dwordx2 v4, v[20:21], s[10:11]
	s_add_u32 s10, s10, 0x4000
	s_addc_u32 s11, s11, 0
	v_lshlrev_b32_e32 v12, 16, v104
	v_and_b32_e32 v13, 0xffff0000, v104
	v_lshlrev_b32_e32 v14, 16, v105
	v_and_b32_e32 v15, 0xffff0000, v105
	v_pk_fma_f32 v[8:9], v[106:107], v[8:9], v[12:13]
	v_pk_fma_f32 v[10:11], v[108:109], v[10:11], v[14:15]
	global_load_dwordx2 v[104:105], v4, s[8:9]
	global_load_dwordx4 v[106:109], v5, s[38:39]
	s_add_u32 s8, s8, 0x4000
	s_addc_u32 s9, s9, 0
	s_sub_u32 s38, s38, 0x800
	s_subb_u32 s39, s39, 0
	s_waitcnt vmcnt(48)
	v_pk_mul_f32 v[26:27], v[8:9], v[112:113]
	v_pk_mul_f32 v[28:29], v[10:11], v[114:115]
	v_cvt_pk_bf16_f32 v24, v26, v27
	v_cvt_pk_bf16_f32 v25, v28, v29
	global_store_dwordx2 v4, v[24:25], s[10:11]
	s_add_u32 s10, s10, 0x4000
	s_addc_u32 s11, s11, 0
	v_lshlrev_b32_e32 v12, 16, v110
	v_and_b32_e32 v13, 0xffff0000, v110
	v_lshlrev_b32_e32 v14, 16, v111
	v_and_b32_e32 v15, 0xffff0000, v111
	v_pk_fma_f32 v[8:9], v[112:113], v[8:9], v[12:13]
	v_pk_fma_f32 v[10:11], v[114:115], v[10:11], v[14:15]
	global_load_dwordx2 v[110:111], v4, s[8:9]
	global_load_dwordx4 v[112:115], v5, s[38:39]
	s_add_u32 s8, s8, 0x4000
	s_addc_u32 s9, s9, 0
	s_sub_u32 s38, s38, 0x800
	s_subb_u32 s39, s39, 0
	s_waitcnt vmcnt(48)
	v_pk_mul_f32 v[26:27], v[8:9], v[118:119]
	v_pk_mul_f32 v[28:29], v[10:11], v[120:121]
	v_cvt_pk_bf16_f32 v16, v26, v27
	v_cvt_pk_bf16_f32 v17, v28, v29
	global_store_dwordx2 v4, v[16:17], s[10:11]
	s_add_u32 s10, s10, 0x4000
	s_addc_u32 s11, s11, 0
	v_lshlrev_b32_e32 v12, 16, v116
	v_and_b32_e32 v13, 0xffff0000, v116
	v_lshlrev_b32_e32 v14, 16, v117
	v_and_b32_e32 v15, 0xffff0000, v117
	v_pk_fma_f32 v[8:9], v[118:119], v[8:9], v[12:13]
	v_pk_fma_f32 v[10:11], v[120:121], v[10:11], v[14:15]
	global_load_dwordx2 v[116:117], v4, s[8:9]
	global_load_dwordx4 v[118:121], v5, s[38:39]
	s_add_u32 s8, s8, 0x4000
	s_addc_u32 s9, s9, 0
	s_sub_u32 s38, s38, 0x800
	s_subb_u32 s39, s39, 0
	s_waitcnt vmcnt(48)
	v_pk_mul_f32 v[26:27], v[8:9], v[124:125]
	v_pk_mul_f32 v[28:29], v[10:11], v[126:127]
	v_cvt_pk_bf16_f32 v18, v26, v27
	v_cvt_pk_bf16_f32 v19, v28, v29
	global_store_dwordx2 v4, v[18:19], s[10:11]
	s_add_u32 s10, s10, 0x4000
	s_addc_u32 s11, s11, 0
	v_lshlrev_b32_e32 v12, 16, v122
	v_and_b32_e32 v13, 0xffff0000, v122
	v_lshlrev_b32_e32 v14, 16, v123
	v_and_b32_e32 v15, 0xffff0000, v123
	v_pk_fma_f32 v[8:9], v[124:125], v[8:9], v[12:13]
	v_pk_fma_f32 v[10:11], v[126:127], v[10:11], v[14:15]
	global_load_dwordx2 v[122:123], v4, s[8:9]
	global_load_dwordx4 v[124:127], v5, s[38:39]
	s_add_u32 s8, s8, 0x4000
	s_addc_u32 s9, s9, 0
	s_sub_u32 s38, s38, 0x800
	s_subb_u32 s39, s39, 0
	s_waitcnt vmcnt(48)
	v_pk_mul_f32 v[26:27], v[8:9], v[130:131]
	v_pk_mul_f32 v[28:29], v[10:11], v[132:133]
	v_cvt_pk_bf16_f32 v20, v26, v27
	v_cvt_pk_bf16_f32 v21, v28, v29
	global_store_dwordx2 v4, v[20:21], s[10:11]
	s_add_u32 s10, s10, 0x4000
	s_addc_u32 s11, s11, 0
	v_lshlrev_b32_e32 v12, 16, v128
	v_and_b32_e32 v13, 0xffff0000, v128
	v_lshlrev_b32_e32 v14, 16, v129
	v_and_b32_e32 v15, 0xffff0000, v129
	v_pk_fma_f32 v[8:9], v[130:131], v[8:9], v[12:13]
	v_pk_fma_f32 v[10:11], v[132:133], v[10:11], v[14:15]
	global_load_dwordx2 v[128:129], v4, s[8:9]
	global_load_dwordx4 v[130:133], v5, s[38:39]
	s_add_u32 s8, s8, 0x4000
	s_addc_u32 s9, s9, 0
	s_sub_u32 s38, s38, 0x800
	s_subb_u32 s39, s39, 0
	s_waitcnt vmcnt(48)
	v_pk_mul_f32 v[26:27], v[8:9], v[34:35]
	v_pk_mul_f32 v[28:29], v[10:11], v[36:37]
	v_cvt_pk_bf16_f32 v24, v26, v27
	v_cvt_pk_bf16_f32 v25, v28, v29
	global_store_dwordx2 v4, v[24:25], s[10:11]
	s_add_u32 s10, s10, 0x4000
	s_addc_u32 s11, s11, 0
	v_lshlrev_b32_e32 v12, 16, v32
	v_and_b32_e32 v13, 0xffff0000, v32
	v_lshlrev_b32_e32 v14, 16, v33
	v_and_b32_e32 v15, 0xffff0000, v33
	v_pk_fma_f32 v[8:9], v[34:35], v[8:9], v[12:13]
	v_pk_fma_f32 v[10:11], v[36:37], v[10:11], v[14:15]
	s_waitcnt vmcnt(46)
	v_pk_mul_f32 v[26:27], v[8:9], v[40:41]
	v_pk_mul_f32 v[28:29], v[10:11], v[42:43]
	v_cvt_pk_bf16_f32 v16, v26, v27
	v_cvt_pk_bf16_f32 v17, v28, v29
	global_store_dwordx2 v4, v[16:17], s[10:11]
	s_add_u32 s10, s10, 0x4000
	s_addc_u32 s11, s11, 0
	v_lshlrev_b32_e32 v12, 16, v38
	v_and_b32_e32 v13, 0xffff0000, v38
	v_lshlrev_b32_e32 v14, 16, v39
	v_and_b32_e32 v15, 0xffff0000, v39
	v_pk_fma_f32 v[8:9], v[40:41], v[8:9], v[12:13]
	v_pk_fma_f32 v[10:11], v[42:43], v[10:11], v[14:15]
	s_waitcnt vmcnt(44)
	v_pk_mul_f32 v[26:27], v[8:9], v[46:47]
	v_pk_mul_f32 v[28:29], v[10:11], v[48:49]
	v_cvt_pk_bf16_f32 v18, v26, v27
	v_cvt_pk_bf16_f32 v19, v28, v29
	global_store_dwordx2 v4, v[18:19], s[10:11]
	s_add_u32 s10, s10, 0x4000
	s_addc_u32 s11, s11, 0
	v_lshlrev_b32_e32 v12, 16, v44
	v_and_b32_e32 v13, 0xffff0000, v44
	v_lshlrev_b32_e32 v14, 16, v45
	v_and_b32_e32 v15, 0xffff0000, v45
	v_pk_fma_f32 v[8:9], v[46:47], v[8:9], v[12:13]
	v_pk_fma_f32 v[10:11], v[48:49], v[10:11], v[14:15]
	s_waitcnt vmcnt(42)
	v_pk_mul_f32 v[26:27], v[8:9], v[52:53]
	v_pk_mul_f32 v[28:29], v[10:11], v[54:55]
	v_cvt_pk_bf16_f32 v20, v26, v27
	v_cvt_pk_bf16_f32 v21, v28, v29
	global_store_dwordx2 v4, v[20:21], s[10:11]
	s_add_u32 s10, s10, 0x4000
	s_addc_u32 s11, s11, 0
	v_lshlrev_b32_e32 v12, 16, v50
	v_and_b32_e32 v13, 0xffff0000, v50
	v_lshlrev_b32_e32 v14, 16, v51
	v_and_b32_e32 v15, 0xffff0000, v51
	v_pk_fma_f32 v[8:9], v[52:53], v[8:9], v[12:13]
	v_pk_fma_f32 v[10:11], v[54:55], v[10:11], v[14:15]
	s_waitcnt vmcnt(40)
; __device__ __forceinline__ unsigned pk2(float lo, float hi) { return pg8::pkc(lo, hi); }
; __device__ __forceinline__ void ph_g2(Frame& F) {
;     ...
;         for (int s = 0; s < 68; ++s) {
;             const v2u uw = *(const v2u*)(UT + base + (size_t)s * 8192);
;             const int rc = chain_slot_rc(b, dir, s);
;             const f32x4 a = *(const f32x4*)(AL + (size_t)(dir * NRC + rc) * 512 + 64 * h + dk4);
;             v2u o; if (dir) { o.x = pk2(S0 * a.x, S1 * a.y); o.y = pk2(S2 * a.z, S3 * a.w); } else { o.x = pk2(S0, S1); o.y = pk2(S2, S3); }
;             *(v2u*)(ST + base + (size_t)s * 8192) = o;
;             S0 = fmaf(a.x, S0, bflo(uw.x)); S1 = fmaf(a.y, S1, bfhi(uw.x)); S2 = fmaf(a.z, S2, bflo(uw.y)); S3 = fmaf(a.w, S3, bfhi(uw.y));
;         }
	v_pk_mul_f32 v[26:27], v[8:9], v[58:59]
	v_pk_mul_f32 v[28:29], v[10:11], v[60:61]
	v_cvt_pk_bf16_f32 v24, v26, v27
	v_cvt_pk_bf16_f32 v25, v28, v29
	global_store_dwordx2 v4, v[24:25], s[10:11]
	s_add_u32 s10, s10, 0x4000
	s_addc_u32 s11, s11, 0
	v_lshlrev_b32_e32 v12, 16, v56
	v_and_b32_e32 v13, 0xffff0000, v56
	v_lshlrev_b32_e32 v14, 16, v57
	v_and_b32_e32 v15, 0xffff0000, v57
	v_pk_fma_f32 v[8:9], v[58:59], v[8:9], v[12:13]
	v_pk_fma_f32 v[10:11], v[60:61], v[10:11], v[14:15]
	s_waitcnt vmcnt(38)
	v_pk_mul_f32 v[26:27], v[8:9], v[64:65]
	v_pk_mul_f32 v[28:29], v[10:11], v[66:67]
	v_cvt_pk_bf16_f32 v16, v26, v27
	v_cvt_pk_bf16_f32 v17, v28, v29
	global_store_dwordx2 v4, v[16:17], s[10:11]
	s_add_u32 s10, s10, 0x4000
	s_addc_u32 s11, s11, 0
	v_lshlrev_b32_e32 v12, 16, v62
	v_and_b32_e32 v13, 0xffff0000, v62
	v_lshlrev_b32_e32 v14, 16, v63
	v_and_b32_e32 v15, 0xffff0000, v63
	v_pk_fma_f32 v[8:9], v[64:65], v[8:9], v[12:13]
	v_pk_fma_f32 v[10:11], v[66:67], v[10:11], v[14:15]
	s_waitcnt vmcnt(36)
	v_pk_mul_f32 v[26:27], v[8:9], v[70:71]
	v_pk_mul_f32 v[28:29], v[10:11], v[72:73]
	v_cvt_pk_bf16_f32 v18, v26, v27
	v_cvt_pk_bf16_f32 v19, v28, v29
	global_store_dwordx2 v4, v[18:19], s[10:11]
	s_add_u32 s10, s10, 0x4000
	s_addc_u32 s11, s11, 0
	v_lshlrev_b32_e32 v12, 16, v68
	v_and_b32_e32 v13, 0xffff0000, v68
	v_lshlrev_b32_e32 v14, 16, v69
	v_and_b32_e32 v15, 0xffff0000, v69
	v_pk_fma_f32 v[8:9], v[70:71], v[8:9], v[12:13]
	v_pk_fma_f32 v[10:11], v[72:73], v[10:11], v[14:15]
	s_waitcnt vmcnt(34)
	v_pk_mul_f32 v[26:27], v[8:9], v[76:77]
	v_pk_mul_f32 v[28:29], v[10:11], v[78:79]
	v_cvt_pk_bf16_f32 v20, v26, v27
	v_cvt_pk_bf16_f32 v21, v28, v29
	global_store_dwordx2 v4, v[20:21], s[10:11]
	s_add_u32 s10, s10, 0x4000
	s_addc_u32 s11, s11, 0
	v_lshlrev_b32_e32 v12, 16, v74
	v_and_b32_e32 v13, 0xffff0000, v74
	v_lshlrev_b32_e32 v14, 16, v75
	v_and_b32_e32 v15, 0xffff0000, v75
	v_pk_fma_f32 v[8:9], v[76:77], v[8:9], v[12:13]
	v_pk_fma_f32 v[10:11], v[78:79], v[10:11], v[14:15]
	s_waitcnt vmcnt(32)
	v_pk_mul_f32 v[26:27], v[8:9], v[82:83]
	v_pk_mul_f32 v[28:29], v[10:11], v[84:85]
	v_cvt_pk_bf16_f32 v24, v26, v27
	v_cvt_pk_bf16_f32 v25, v28, v29
	global_store_dwordx2 v4, v[24:25], s[10:11]
	s_add_u32 s10, s10, 0x4000
	s_addc_u32 s11, s11, 0
	v_lshlrev_b32_e32 v12, 16, v80
	v_and_b32_e32 v13, 0xffff0000, v80
	v_lshlrev_b32_e32 v14, 16, v81
	v_and_b32_e32 v15, 0xffff0000, v81
	v_pk_fma_f32 v[8:9], v[82:83], v[8:9], v[12:13]
	v_pk_fma_f32 v[10:11], v[84:85], v[10:11], v[14:15]
	s_waitcnt vmcnt(30)
	v_pk_mul_f32 v[26:27], v[8:9], v[88:89]
	v_pk_mul_f32 v[28:29], v[10:11], v[90:91]
	v_cvt_pk_bf16_f32 v16, v26, v27
	v_cvt_pk_bf16_f32 v17, v28, v29
	global_store_dwordx2 v4, v[16:17], s[10:11]
	s_add_u32 s10, s10, 0x4000
	s_addc_u32 s11, s11, 0
	v_lshlrev_b32_e32 v12, 16, v86
	v_and_b32_e32 v13, 0xffff0000, v86
	v_lshlrev_b32_e32 v14, 16, v87
	v_and_b32_e32 v15, 0xffff0000, v87
	v_pk_fma_f32 v[8:9], v[88:89], v[8:9], v[12:13]
	v_pk_fma_f32 v[10:11], v[90:91], v[10:11], v[14:15]
	s_waitcnt vmcnt(28)
	v_pk_mul_f32 v[26:27], v[8:9], v[94:95]
	v_pk_mul_f32 v[28:29], v[10:11], v[96:97]
	v_cvt_pk_bf16_f32 v18, v26, v27
	v_cvt_pk_bf16_f32 v19, v28, v29
	global_store_dwordx2 v4, v[18:19], s[10:11]
	s_add_u32 s10, s10, 0x4000
	s_addc_u32 s11, s11, 0
	v_lshlrev_b32_e32 v12, 16, v92
	v_and_b32_e32 v13, 0xffff0000, v92
	v_lshlrev_b32_e32 v14, 16, v93
	v_and_b32_e32 v15, 0xffff0000, v93
	v_pk_fma_f32 v[8:9], v[94:95], v[8:9], v[12:13]
	v_pk_fma_f32 v[10:11], v[96:97], v[10:11], v[14:15]
	s_waitcnt vmcnt(26)
	v_pk_mul_f32 v[26:27], v[8:9], v[100:101]
	v_pk_mul_f32 v[28:29], v[10:11], v[102:103]
	v_cvt_pk_bf16_f32 v20, v26, v27
	v_cvt_pk_bf16_f32 v21, v28, v29
	global_store_dwordx2 v4, v[20:21], s[10:11]
	s_add_u32 s10, s10, 0x4000
	s_addc_u32 s11, s11, 0
	v_lshlrev_b32_e32 v12, 16, v98
	v_and_b32_e32 v13, 0xffff0000, v98
	v_lshlrev_b32_e32 v14, 16, v99
	v_and_b32_e32 v15, 0xffff0000, v99
	v_pk_fma_f32 v[8:9], v[100:101], v[8:9], v[12:13]
	v_pk_fma_f32 v[10:11], v[102:103], v[10:11], v[14:15]
	s_waitcnt vmcnt(24)
	v_pk_mul_f32 v[26:27], v[8:9], v[106:107]
	v_pk_mul_f32 v[28:29], v[10:11], v[108:109]
	v_cvt_pk_bf16_f32 v24, v26, v27
	v_cvt_pk_bf16_f32 v25, v28, v29
	global_store_dwordx2 v4, v[24:25], s[10:11]
	s_add_u32 s10, s10, 0x4000
	s_addc_u32 s11, s11, 0
	v_lshlrev_b32_e32 v12, 16, v104
	v_and_b32_e32 v13, 0xffff0000, v104
	v_lshlrev_b32_e32 v14, 16, v105
	v_and_b32_e32 v15, 0xffff0000, v105
	v_pk_fma_f32 v[8:9], v[106:107], v[8:9], v[12:13]
	v_pk_fma_f32 v[10:11], v[108:109], v[10:11], v[14:15]
	s_waitcnt vmcnt(22)
	v_pk_mul_f32 v[26:27], v[8:9], v[112:113]
	v_pk_mul_f32 v[28:29], v[10:11], v[114:115]
	v_cvt_pk_bf16_f32 v16, v26, v27
	v_cvt_pk_bf16_f32 v17, v28, v29
	global_store_dwordx2 v4, v[16:17], s[10:11]
	s_add_u32 s10, s10, 0x4000
	s_addc_u32 s11, s11, 0
	v_lshlrev_b32_e32 v12, 16, v110
	v_and_b32_e32 v13, 0xffff0000, v110
	v_lshlrev_b32_e32 v14, 16, v111
	v_and_b32_e32 v15, 0xffff0000, v111
	v_pk_fma_f32 v[8:9], v[112:113], v[8:9], v[12:13]
	v_pk_fma_f32 v[10:11], v[114:115], v[10:11], v[14:15]
	s_waitcnt vmcnt(20)
	v_pk_mul_f32 v[26:27], v[8:9], v[118:119]
	v_pk_mul_f32 v[28:29], v[10:11], v[120:121]
	v_cvt_pk_bf16_f32 v18, v26, v27
	v_cvt_pk_bf16_f32 v19, v28, v29
	global_store_dwordx2 v4, v[18:19], s[10:11]
	s_add_u32 s10, s10, 0x4000
	s_addc_u32 s11, s11, 0
	v_lshlrev_b32_e32 v12, 16, v116
	v_and_b32_e32 v13, 0xffff0000, v116
	v_lshlrev_b32_e32 v14, 16, v117
	v_and_b32_e32 v15, 0xffff0000, v117
	v_pk_fma_f32 v[8:9], v[118:119], v[8:9], v[12:13]
	v_pk_fma_f32 v[10:11], v[120:121], v[10:11], v[14:15]
	s_waitcnt vmcnt(18)
	v_pk_mul_f32 v[26:27], v[8:9], v[124:125]
	v_pk_mul_f32 v[28:29], v[10:11], v[126:127]
	v_cvt_pk_bf16_f32 v20, v26, v27
	v_cvt_pk_bf16_f32 v21, v28, v29
	global_store_dwordx2 v4, v[20:21], s[10:11]
	s_add_u32 s10, s10, 0x4000
	s_addc_u32 s11, s11, 0
	v_lshlrev_b32_e32 v12, 16, v122
	v_and_b32_e32 v13, 0xffff0000, v122
	v_lshlrev_b32_e32 v14, 16, v123
	v_and_b32_e32 v15, 0xffff0000, v123
	v_pk_fma_f32 v[8:9], v[124:125], v[8:9], v[12:13]
	v_pk_fma_f32 v[10:11], v[126:127], v[10:11], v[14:15]
	s_waitcnt vmcnt(16)
	v_pk_mul_f32 v[26:27], v[8:9], v[130:131]
	v_pk_mul_f32 v[28:29], v[10:11], v[132:133]
	v_cvt_pk_bf16_f32 v24, v26, v27
	v_cvt_pk_bf16_f32 v25, v28, v29
	global_store_dwordx2 v4, v[24:25], s[10:11]
	s_add_u32 s10, s10, 0x4000
	s_addc_u32 s11, s11, 0
	v_lshlrev_b32_e32 v12, 16, v128
	v_and_b32_e32 v13, 0xffff0000, v128
	v_lshlrev_b32_e32 v14, 16, v129
	v_and_b32_e32 v15, 0xffff0000, v129
	v_pk_fma_f32 v[8:9], v[130:131], v[8:9], v[12:13]
	v_pk_fma_f32 v[10:11], v[132:133], v[10:11], v[14:15]
	s_branch .LBB0_791

; #define PG8_STAGE(bufoff, gbase, voff) do { _Pragma("unroll") for (int _i = 0; _i < 2; ++_i) \
;         __builtin_amdgcn_global_load_lds((const unsigned*)((const char*)(gbase) + (voff)[_i]), (PG8_LAS unsigned*)(lds + (bufoff) + ldsw + _i * 8192), 16, 0, 0); } while (0)
; #define PG8_LDA(dst, b, h) do { _Pragma("unroll") for (int m = 0; m < 4; ++m) _Pragma("unroll") for (int k = 0; k < 2; ++k) dst[m][k] = *(const PG8_LAS bf16x8*)(lds + PG8_SA(b, h) + aoff + m * 2048 + k * 1024); } while (0)
; #define PG8_LDB(dst, b, h) do { _Pragma("unroll") for (int n = 0; n < 2; ++n) _Pragma("unroll") for (int k = 0; k < 2; ++k) dst[n][k] = *(const PG8_LAS bf16x8*)(lds + PG8_SB(b, h) + boff + n * 2048 + k * 1024); } while (0)
; #define PG8_MMA(ai, bj, At, Bt) do { __builtin_amdgcn_s_setprio(1); _Pragma("unroll") for (int m = 0; m < 4; ++m) _Pragma("unroll") for (int n = 0; n < 2; ++n) _Pragma("unroll") for (int k = 0; k < 2; ++k) \
;         acc[ai][bj][m][n] = __builtin_amdgcn_mfma_f32_16x16x32_bf16(Bt[n][k], At[m][k], acc[ai][bj][m][n], 0, 0, 0); __builtin_amdgcn_s_setprio(0); } while (0)
; #define PG8_WAIT_V(n) asm volatile("s_waitcnt vmcnt(" #n ")" ::: "memory")
; #define PG8_WAIT_L(n) asm volatile("s_waitcnt lgkmcnt(" #n ")" ::: "memory")
; template <class Epi, class Sched, bool ALIGN_EPI = true>
; __device__ __forceinline__ void gemm_phase(PG8_LAS unsigned char* lds, const Gemm g, const Sched& S, const Epi& E, const int tid) {
;     ...
;         for (int t = 0; t < nt; t += 2) {
;             const bool last = (t == nt - 2);
;             const char* a1 = cA + (size_t)(t + 1) * kstep;
;             const char* a2 = last ? nA : cA + (size_t)(t + 2) * kstep; const char* b2 = last ? nB : cB + (size_t)(t + 2) * kstep;
;             const char* a3 = a2 + kstep; const char* b3 = b2 + kstep;
;             if (last && has_next) S.a_ready(nxt);
;             PG8_LDB(B0, 0, 0); PG8_LDB(B1, 0, 1); PG8_SCHED; PG8_LDA(At, 0, 0); PG8_STAGE(PG8_SA(1, 1), a1 + hstepA, voffA);
;             PG8_WAIT_V(8); PG8_WAIT_L(0); PG8_BAR; PG8_MMA(0, 0, At, B0); PG8_MMA(0, 1, At, B1); PG8_BAR; PG8_SCHED;
;             PG8_LDA(At, 0, 1); PG8_STAGE(PG8_SB(0, 0), b2, voffB); PG8_STAGE(PG8_SB(0, 1), b2 + hstepB, voffB); PG8_STAGE(PG8_SA(0, 0), a2, voffA);
;             PG8_WAIT_V(8); PG8_WAIT_L(0); PG8_BAR; PG8_MMA(1, 0, At, B0); PG8_MMA(1, 1, At, B1); PG8_BAR; PG8_SCHED;
.LBB0_1087:
	s_add_i32 s45, s22, 2
	s_add_u32 s15, s12, 0xfff80080
	s_addc_u32 s16, s13, -1
	s_add_i32 s17, 0, 0x10000
	s_cmp_eq_u32 s1, s22
	s_cselect_b32 s55, s51, s16
	s_cselect_b32 s54, s50, s15
	s_cselect_b32 s23, s53, s21
	s_cselect_b32 s22, s52, s20
	s_add_i32 s15, 0, 0x14000
	v_add_u32_e32 v72, s17, v251
	v_add_u32_e32 v128, s15, v251
	ds_read_b128 v[56:59], v72
	ds_read_b128 v[64:67], v72 offset:1024
	ds_read_b128 v[68:71], v72 offset:2048
	ds_read_b128 v[72:75], v72 offset:3072
	ds_read_b128 v[92:95], v128
	ds_read_b128 v[104:107], v128 offset:1024
	ds_read_b128 v[116:119], v128 offset:2048
	ds_read_b128 v[128:131], v128 offset:3072
	v_lshl_add_u64 v[196:197], s[12:13], 0, v[216:217]
	s_add_i32 m0, s11, 0xc000
	ds_read_b128 v[140:143], v252
	ds_read_b128 v[152:155], v252 offset:1024
	ds_read_b128 v[156:159], v252 offset:2048
	ds_read_b128 v[160:163], v252 offset:3072
	ds_read_b128 v[172:175], v252 offset:4096
	ds_read_b128 v[184:187], v252 offset:5120
	ds_read_b128 v[188:191], v252 offset:6144
	ds_read_b128 v[192:195], v252 offset:7168
	global_load_lds_dwordx4 v[196:197], off
	v_lshl_add_u64 v[196:197], s[12:13], 0, v[218:219]
	s_add_i32 m0, s11, 0xe000
	s_nop 0
	global_load_lds_dwordx4 v[196:197], off
	s_waitcnt vmcnt(8)
	s_waitcnt lgkmcnt(0)
	s_barrier
	s_waitcnt lgkmcnt(0)
	v_mfma_f32_16x16x32_bf16 v[180:183], v[56:59], v[140:143], v[180:183]
	v_mfma_f32_16x16x32_bf16 v[176:179], v[68:71], v[140:143], v[176:179]
	v_mfma_f32_16x16x32_bf16 v[148:151], v[56:59], v[156:159], v[148:151]
	v_mfma_f32_16x16x32_bf16 v[144:147], v[68:71], v[156:159], v[144:147]
	v_mfma_f32_16x16x32_bf16 v[124:127], v[56:59], v[172:175], v[124:127]
	v_mfma_f32_16x16x32_bf16 v[120:123], v[68:71], v[172:175], v[120:123]
	v_mfma_f32_16x16x32_bf16 v[100:103], v[56:59], v[188:191], v[100:103]
	v_mfma_f32_16x16x32_bf16 v[96:99], v[68:71], v[188:191], v[96:99]
	v_mfma_f32_16x16x32_bf16 v[180:183], v[64:67], v[152:155], v[180:183]
	v_mfma_f32_16x16x32_bf16 v[176:179], v[72:75], v[152:155], v[176:179]
	v_mfma_f32_16x16x32_bf16 v[148:151], v[64:67], v[160:163], v[148:151]
	v_mfma_f32_16x16x32_bf16 v[144:147], v[72:75], v[160:163], v[144:147]
	v_mfma_f32_16x16x32_bf16 v[124:127], v[64:67], v[184:187], v[124:127]
	v_mfma_f32_16x16x32_bf16 v[120:123], v[72:75], v[184:187], v[120:123]
	v_mfma_f32_16x16x32_bf16 v[100:103], v[64:67], v[192:195], v[100:103]
	v_mfma_f32_16x16x32_bf16 v[96:99], v[72:75], v[192:195], v[96:99]
	v_mfma_f32_16x16x32_bf16 v[168:171], v[92:95], v[140:143], v[168:171]
	v_mfma_f32_16x16x32_bf16 v[136:139], v[92:95], v[156:159], v[136:139]
	v_mfma_f32_16x16x32_bf16 v[132:135], v[116:119], v[156:159], v[132:135]
	v_mfma_f32_16x16x32_bf16 v[112:115], v[92:95], v[172:175], v[112:115]
	v_mfma_f32_16x16x32_bf16 v[108:111], v[116:119], v[172:175], v[108:111]
	v_mfma_f32_16x16x32_bf16 v[88:91], v[92:95], v[188:191], v[88:91]
	v_mfma_f32_16x16x32_bf16 v[84:87], v[116:119], v[188:191], v[84:87]
	v_mfma_f32_16x16x32_bf16 v[168:171], v[104:107], v[152:155], v[168:171]
	v_mfma_f32_16x16x32_bf16 v[140:143], v[116:119], v[140:143], v[164:167]
	v_mfma_f32_16x16x32_bf16 v[136:139], v[104:107], v[160:163], v[136:139]
	v_mfma_f32_16x16x32_bf16 v[132:135], v[128:131], v[160:163], v[132:135]
	v_mfma_f32_16x16x32_bf16 v[112:115], v[104:107], v[184:187], v[112:115]
	v_mfma_f32_16x16x32_bf16 v[108:111], v[128:131], v[184:187], v[108:111]
	v_mfma_f32_16x16x32_bf16 v[88:91], v[104:107], v[192:195], v[88:91]
	v_mfma_f32_16x16x32_bf16 v[84:87], v[128:131], v[192:195], v[84:87]
	v_mfma_f32_16x16x32_bf16 v[140:143], v[128:131], v[152:155], v[140:143]
	s_barrier
	s_add_i32 s16, s17, s60
	v_lshl_add_u64 v[200:201], s[22:23], 0, v[2:3]
	s_mov_b32 m0, s16
	ds_read_b128 v[152:155], v252 offset:16384
	ds_read_b128 v[156:159], v252 offset:17408
	ds_read_b128 v[160:163], v252 offset:18432
	ds_read_b128 v[164:167], v252 offset:19456
	ds_read_b128 v[172:175], v252 offset:20480
	ds_read_b128 v[184:187], v252 offset:21504
	ds_read_b128 v[188:191], v252 offset:22528
	ds_read_b128 v[192:195], v252 offset:23552
	global_load_lds_dwordx4 v[200:201], off
	s_add_i32 m0, s16, 0x2000
	s_add_u32 s72, s22, 0x80000
	v_lshl_add_u64 v[202:203], s[22:23], 0, v[214:215]
	s_addc_u32 s73, s23, 0
	s_add_i32 s15, s15, s60
	global_load_lds_dwordx4 v[202:203], off
	v_lshl_add_u64 v[196:197], s[72:73], 0, v[2:3]
	s_mov_b32 m0, s15
	v_lshl_add_u64 v[204:205], s[54:55], 0, v[210:211]
	global_load_lds_dwordx4 v[196:197], off
	v_lshl_add_u64 v[196:197], s[72:73], 0, v[214:215]
	s_add_i32 m0, s15, 0x2000
	v_lshl_add_u64 v[206:207], s[54:55], 0, v[212:213]
	global_load_lds_dwordx4 v[196:197], off
	s_mov_b32 m0, s11
	s_nop 0
	global_load_lds_dwordx4 v[204:205], off
	s_mov_b32 m0, s61
	s_nop 0
	global_load_lds_dwordx4 v[206:207], off
	s_waitcnt vmcnt(8)
	s_waitcnt lgkmcnt(0)
	s_barrier
; #define PG8_STAGE(bufoff, gbase, voff) do { _Pragma("unroll") for (int _i = 0; _i < 2; ++_i) \
;         __builtin_amdgcn_global_load_lds((const unsigned*)((const char*)(gbase) + (voff)[_i]), (PG8_LAS unsigned*)(lds + (bufoff) + ldsw + _i * 8192), 16, 0, 0); } while (0)
; #define PG8_LDA(dst, b, h) do { _Pragma("unroll") for (int m = 0; m < 4; ++m) _Pragma("unroll") for (int k = 0; k < 2; ++k) dst[m][k] = *(const PG8_LAS bf16x8*)(lds + PG8_SA(b, h) + aoff + m * 2048 + k * 1024); } while (0)
; #define PG8_LDB(dst, b, h) do { _Pragma("unroll") for (int n = 0; n < 2; ++n) _Pragma("unroll") for (int k = 0; k < 2; ++k) dst[n][k] = *(const PG8_LAS bf16x8*)(lds + PG8_SB(b, h) + boff + n * 2048 + k * 1024); } while (0)
; #define PG8_MMA(ai, bj, At, Bt) do { __builtin_amdgcn_s_setprio(1); _Pragma("unroll") for (int m = 0; m < 4; ++m) _Pragma("unroll") for (int n = 0; n < 2; ++n) _Pragma("unroll") for (int k = 0; k < 2; ++k) \
;         acc[ai][bj][m][n] = __builtin_amdgcn_mfma_f32_16x16x32_bf16(Bt[n][k], At[m][k], acc[ai][bj][m][n], 0, 0, 0); __builtin_amdgcn_s_setprio(0); } while (0)
; #define PG8_WAIT_V(n) asm volatile("s_waitcnt vmcnt(" #n ")" ::: "memory")
; #define PG8_WAIT_L(n) asm volatile("s_waitcnt lgkmcnt(" #n ")" ::: "memory")
; #define PG8_BAR __builtin_amdgcn_s_barrier()
; #define PG8_SCHED __builtin_amdgcn_sched_barrier(0)
; template <class Epi, class Sched, bool ALIGN_EPI = true>
; __device__ __forceinline__ void gemm_phase(PG8_LAS unsigned char* lds, const Gemm g, const Sched& S, const Epi& E, const int tid) {
;     ...
;             PG8_WAIT_V(8); PG8_WAIT_L(0); PG8_BAR; PG8_MMA(1, 0, At, B0); PG8_MMA(1, 1, At, B1); PG8_BAR; PG8_SCHED;
;             PG8_LDB(B0, 1, 0); PG8_LDB(B1, 1, 1); PG8_SCHED; PG8_LDA(At, 1, 0); PG8_STAGE(PG8_SA(0, 1), a2 + hstepA, voffA);
;             PG8_WAIT_V(8); PG8_WAIT_L(0); PG8_BAR; PG8_MMA(0, 0, At, B0); PG8_MMA(0, 1, At, B1); PG8_BAR; PG8_SCHED;
	s_waitcnt lgkmcnt(0)
	v_mfma_f32_16x16x32_bf16 v[80:83], v[56:59], v[152:155], v[80:83]
	v_mfma_f32_16x16x32_bf16 v[76:79], v[68:71], v[152:155], v[76:79]
	v_mfma_f32_16x16x32_bf16 v[48:51], v[56:59], v[160:163], v[48:51]
	v_mfma_f32_16x16x32_bf16 v[44:47], v[68:71], v[160:163], v[44:47]
	v_mfma_f32_16x16x32_bf16 v[32:35], v[56:59], v[172:175], v[32:35]
	v_mfma_f32_16x16x32_bf16 v[28:31], v[68:71], v[172:175], v[28:31]
	v_mfma_f32_16x16x32_bf16 v[16:19], v[56:59], v[188:191], v[16:19]
	v_mfma_f32_16x16x32_bf16 v[12:15], v[68:71], v[188:191], v[12:15]
	v_mfma_f32_16x16x32_bf16 v[80:83], v[64:67], v[156:159], v[80:83]
	v_mfma_f32_16x16x32_bf16 v[76:79], v[72:75], v[156:159], v[76:79]
	v_mfma_f32_16x16x32_bf16 v[48:51], v[64:67], v[164:167], v[48:51]
	v_mfma_f32_16x16x32_bf16 v[44:47], v[72:75], v[164:167], v[44:47]
	v_mfma_f32_16x16x32_bf16 v[32:35], v[64:67], v[184:187], v[32:35]
	v_mfma_f32_16x16x32_bf16 v[28:31], v[72:75], v[184:187], v[28:31]
	v_mfma_f32_16x16x32_bf16 v[16:19], v[64:67], v[192:195], v[16:19]
	v_mfma_f32_16x16x32_bf16 v[12:15], v[72:75], v[192:195], v[12:15]
	v_mfma_f32_16x16x32_bf16 v[52:55], v[116:119], v[152:155], v[52:55]
	v_mfma_f32_16x16x32_bf16 v[40:43], v[92:95], v[160:163], v[40:43]
	v_mfma_f32_16x16x32_bf16 v[36:39], v[116:119], v[160:163], v[36:39]
	v_mfma_f32_16x16x32_bf16 v[24:27], v[92:95], v[172:175], v[24:27]
	v_mfma_f32_16x16x32_bf16 v[20:23], v[116:119], v[172:175], v[20:23]
	v_mfma_f32_16x16x32_bf16 v[8:11], v[92:95], v[188:191], v[8:11]
	v_mfma_f32_16x16x32_bf16 v[4:7], v[116:119], v[188:191], v[4:7]
	v_mfma_f32_16x16x32_bf16 v[56:59], v[92:95], v[152:155], v[60:63]
	v_mfma_f32_16x16x32_bf16 v[52:55], v[128:131], v[156:159], v[52:55]
	v_mfma_f32_16x16x32_bf16 v[40:43], v[104:107], v[164:167], v[40:43]
	v_mfma_f32_16x16x32_bf16 v[36:39], v[128:131], v[164:167], v[36:39]
	v_mfma_f32_16x16x32_bf16 v[24:27], v[104:107], v[184:187], v[24:27]
	v_mfma_f32_16x16x32_bf16 v[20:23], v[128:131], v[184:187], v[20:23]
	v_mfma_f32_16x16x32_bf16 v[8:11], v[104:107], v[192:195], v[8:11]
	v_mfma_f32_16x16x32_bf16 v[4:7], v[128:131], v[192:195], v[4:7]
	v_mfma_f32_16x16x32_bf16 v[56:59], v[104:107], v[156:159], v[56:59]
	s_barrier
	s_add_i32 s15, 0, 0x18000
	s_add_i32 s16, 0, 0x1c000
	v_add_u32_e32 v72, s15, v251
	v_add_u32_e32 v128, s16, v251
	ds_read_b128 v[60:63], v72
	ds_read_b128 v[64:67], v72 offset:1024
	ds_read_b128 v[68:71], v72 offset:2048
	ds_read_b128 v[72:75], v72 offset:3072
	ds_read_b128 v[92:95], v128
	ds_read_b128 v[104:107], v128 offset:1024
	ds_read_b128 v[116:119], v128 offset:2048
	ds_read_b128 v[128:131], v128 offset:3072
	s_add_u32 s54, s54, 0x80000
	s_addc_u32 s55, s55, 0
	s_mov_b32 m0, s62
	v_lshl_add_u64 v[164:165], s[54:55], 0, v[210:211]
	ds_read_b128 v[152:155], v252 offset:32768
	ds_read_b128 v[156:159], v252 offset:33792
	ds_read_b128 v[160:163], v252 offset:34816
	ds_read_b128 v[172:175], v252 offset:35840
	ds_read_b128 v[184:187], v252 offset:36864
	ds_read_b128 v[188:191], v252 offset:37888
	ds_read_b128 v[192:195], v252 offset:38912
	ds_read_b128 v[196:199], v252 offset:39936
	global_load_lds_dwordx4 v[164:165], off
	v_lshl_add_u64 v[164:165], s[54:55], 0, v[212:213]
	s_mov_b32 m0, s63
	s_nop 0
	global_load_lds_dwordx4 v[164:165], off
	s_waitcnt vmcnt(8)
	s_waitcnt lgkmcnt(0)
	s_barrier
	s_waitcnt lgkmcnt(0)
	v_mfma_f32_16x16x32_bf16 v[164:167], v[60:63], v[152:155], v[180:183]
	v_mfma_f32_16x16x32_bf16 v[180:183], v[64:67], v[156:159], v[164:167]
	v_mfma_f32_16x16x32_bf16 v[164:167], v[68:71], v[152:155], v[176:179]
	v_mfma_f32_16x16x32_bf16 v[148:151], v[60:63], v[160:163], v[148:151]
	v_mfma_f32_16x16x32_bf16 v[144:147], v[68:71], v[160:163], v[144:147]
	v_mfma_f32_16x16x32_bf16 v[124:127], v[60:63], v[184:187], v[124:127]
	v_mfma_f32_16x16x32_bf16 v[120:123], v[68:71], v[184:187], v[120:123]
	v_mfma_f32_16x16x32_bf16 v[100:103], v[60:63], v[192:195], v[100:103]
	v_mfma_f32_16x16x32_bf16 v[96:99], v[68:71], v[192:195], v[96:99]
	v_mfma_f32_16x16x32_bf16 v[176:179], v[72:75], v[156:159], v[164:167]
	v_mfma_f32_16x16x32_bf16 v[148:151], v[64:67], v[172:175], v[148:151]
	v_mfma_f32_16x16x32_bf16 v[144:147], v[72:75], v[172:175], v[144:147]
	v_mfma_f32_16x16x32_bf16 v[124:127], v[64:67], v[188:191], v[124:127]
	v_mfma_f32_16x16x32_bf16 v[120:123], v[72:75], v[188:191], v[120:123]
	v_mfma_f32_16x16x32_bf16 v[100:103], v[64:67], v[196:199], v[100:103]
	v_mfma_f32_16x16x32_bf16 v[96:99], v[72:75], v[196:199], v[96:99]
	v_mfma_f32_16x16x32_bf16 v[164:167], v[92:95], v[152:155], v[168:171]
	v_mfma_f32_16x16x32_bf16 v[140:143], v[116:119], v[152:155], v[140:143]
	v_mfma_f32_16x16x32_bf16 v[136:139], v[92:95], v[160:163], v[136:139]
	v_mfma_f32_16x16x32_bf16 v[132:135], v[116:119], v[160:163], v[132:135]
	v_mfma_f32_16x16x32_bf16 v[112:115], v[92:95], v[184:187], v[112:115]
	v_mfma_f32_16x16x32_bf16 v[108:111], v[116:119], v[184:187], v[108:111]
	v_mfma_f32_16x16x32_bf16 v[88:91], v[92:95], v[192:195], v[88:91]
	v_mfma_f32_16x16x32_bf16 v[84:87], v[116:119], v[192:195], v[84:87]
	v_mfma_f32_16x16x32_bf16 v[168:171], v[104:107], v[156:159], v[164:167]
	v_mfma_f32_16x16x32_bf16 v[164:167], v[128:131], v[156:159], v[140:143]
	v_mfma_f32_16x16x32_bf16 v[136:139], v[104:107], v[172:175], v[136:139]
	v_mfma_f32_16x16x32_bf16 v[132:135], v[128:131], v[172:175], v[132:135]
	v_mfma_f32_16x16x32_bf16 v[112:115], v[104:107], v[188:191], v[112:115]
	v_mfma_f32_16x16x32_bf16 v[108:111], v[128:131], v[188:191], v[108:111]
	v_mfma_f32_16x16x32_bf16 v[88:91], v[104:107], v[196:199], v[88:91]
	v_mfma_f32_16x16x32_bf16 v[84:87], v[128:131], v[196:199], v[84:87]
	s_barrier
; #define PG8_STAGE(bufoff, gbase, voff) do { _Pragma("unroll") for (int _i = 0; _i < 2; ++_i) \
;         __builtin_amdgcn_global_load_lds((const unsigned*)((const char*)(gbase) + (voff)[_i]), (PG8_LAS unsigned*)(lds + (bufoff) + ldsw + _i * 8192), 16, 0, 0); } while (0)
; #define PG8_LDA(dst, b, h) do { _Pragma("unroll") for (int m = 0; m < 4; ++m) _Pragma("unroll") for (int k = 0; k < 2; ++k) dst[m][k] = *(const PG8_LAS bf16x8*)(lds + PG8_SA(b, h) + aoff + m * 2048 + k * 1024); } while (0)
; #define PG8_MMA(ai, bj, At, Bt) do { __builtin_amdgcn_s_setprio(1); _Pragma("unroll") for (int m = 0; m < 4; ++m) _Pragma("unroll") for (int n = 0; n < 2; ++n) _Pragma("unroll") for (int k = 0; k < 2; ++k) \
;         acc[ai][bj][m][n] = __builtin_amdgcn_mfma_f32_16x16x32_bf16(Bt[n][k], At[m][k], acc[ai][bj][m][n], 0, 0, 0); __builtin_amdgcn_s_setprio(0); } while (0)
; #define PG8_WAIT_V(n) asm volatile("s_waitcnt vmcnt(" #n ")" ::: "memory")
; #define PG8_WAIT_L(n) asm volatile("s_waitcnt lgkmcnt(" #n ")" ::: "memory")
; #define PG8_BAR __builtin_amdgcn_s_barrier()
; #define PG8_SCHED __builtin_amdgcn_sched_barrier(0)
; template <class Epi, class Sched, bool ALIGN_EPI = true>
; __device__ __forceinline__ void gemm_phase(PG8_LAS unsigned char* lds, const Gemm g, const Sched& S, const Epi& E, const int tid) {
;     ...
;             PG8_LDA(At, 1, 1); PG8_STAGE(PG8_SB(1, 0), b3, voffB); PG8_STAGE(PG8_SB(1, 1), b3 + hstepB, voffB); PG8_STAGE(PG8_SA(1, 0), a3, voffA);
;             PG8_WAIT_V(8); PG8_WAIT_L(0); PG8_BAR; PG8_MMA(1, 0, At, B0); PG8_MMA(1, 1, At, B1); PG8_BAR; PG8_SCHED;
;         }
;         if constexpr (ALIGN_EPI) { if (wr == 0) PG8_BAR; }
	s_add_i32 s15, s15, s60
	v_lshl_add_u64 v[196:197], v[200:201], 0, s[36:37]
	s_mov_b32 m0, s15
	ds_read_b128 v[140:143], v252 offset:49152
	ds_read_b128 v[152:155], v252 offset:50176
	ds_read_b128 v[156:159], v252 offset:51200
	ds_read_b128 v[160:163], v252 offset:52224
	ds_read_b128 v[172:175], v252 offset:53248
	ds_read_b128 v[184:187], v252 offset:54272
	ds_read_b128 v[188:191], v252 offset:55296
	ds_read_b128 v[192:195], v252 offset:56320
	global_load_lds_dwordx4 v[196:197], off
	s_add_i32 m0, s15, 0x2000
	s_add_u32 s22, s22, 0x80080
	v_lshl_add_u64 v[196:197], v[202:203], 0, s[36:37]
	s_addc_u32 s23, s23, 0
	s_add_i32 s15, s16, s60
	global_load_lds_dwordx4 v[196:197], off
	v_lshl_add_u64 v[196:197], s[22:23], 0, v[2:3]
	s_mov_b32 m0, s15
	s_nop 0
	global_load_lds_dwordx4 v[196:197], off
	v_lshl_add_u64 v[196:197], s[22:23], 0, v[214:215]
	s_add_i32 m0, s15, 0x2000
	s_nop 0
	global_load_lds_dwordx4 v[196:197], off
	v_lshl_add_u64 v[196:197], v[204:205], 0, s[36:37]
	s_mov_b32 m0, s68
	s_nop 0
	global_load_lds_dwordx4 v[196:197], off
	v_lshl_add_u64 v[196:197], v[206:207], 0, s[36:37]
	s_mov_b32 m0, s69
	s_nop 0
	global_load_lds_dwordx4 v[196:197], off
	s_waitcnt vmcnt(8)
	s_waitcnt lgkmcnt(0)
	s_barrier
	s_waitcnt lgkmcnt(0)
	v_mfma_f32_16x16x32_bf16 v[80:83], v[60:63], v[140:143], v[80:83]
	v_mfma_f32_16x16x32_bf16 v[76:79], v[68:71], v[140:143], v[76:79]
	v_mfma_f32_16x16x32_bf16 v[48:51], v[60:63], v[156:159], v[48:51]
	v_mfma_f32_16x16x32_bf16 v[44:47], v[68:71], v[156:159], v[44:47]
	v_mfma_f32_16x16x32_bf16 v[32:35], v[60:63], v[172:175], v[32:35]
	v_mfma_f32_16x16x32_bf16 v[28:31], v[68:71], v[172:175], v[28:31]
	v_mfma_f32_16x16x32_bf16 v[16:19], v[60:63], v[188:191], v[16:19]
	v_mfma_f32_16x16x32_bf16 v[12:15], v[68:71], v[188:191], v[12:15]
	v_mfma_f32_16x16x32_bf16 v[80:83], v[64:67], v[152:155], v[80:83]
	v_mfma_f32_16x16x32_bf16 v[76:79], v[72:75], v[152:155], v[76:79]
	v_mfma_f32_16x16x32_bf16 v[48:51], v[64:67], v[160:163], v[48:51]
	v_mfma_f32_16x16x32_bf16 v[44:47], v[72:75], v[160:163], v[44:47]
	v_mfma_f32_16x16x32_bf16 v[32:35], v[64:67], v[184:187], v[32:35]
	v_mfma_f32_16x16x32_bf16 v[28:31], v[72:75], v[184:187], v[28:31]
	v_mfma_f32_16x16x32_bf16 v[16:19], v[64:67], v[192:195], v[16:19]
	v_mfma_f32_16x16x32_bf16 v[12:15], v[72:75], v[192:195], v[12:15]
	v_mfma_f32_16x16x32_bf16 v[56:59], v[92:95], v[140:143], v[56:59]
	v_mfma_f32_16x16x32_bf16 v[52:55], v[116:119], v[140:143], v[52:55]
	v_mfma_f32_16x16x32_bf16 v[40:43], v[92:95], v[156:159], v[40:43]
	v_mfma_f32_16x16x32_bf16 v[36:39], v[116:119], v[156:159], v[36:39]
	v_mfma_f32_16x16x32_bf16 v[24:27], v[92:95], v[172:175], v[24:27]
	v_mfma_f32_16x16x32_bf16 v[20:23], v[116:119], v[172:175], v[20:23]
	v_mfma_f32_16x16x32_bf16 v[8:11], v[92:95], v[188:191], v[8:11]
	v_mfma_f32_16x16x32_bf16 v[4:7], v[116:119], v[188:191], v[4:7]
	v_mfma_f32_16x16x32_bf16 v[60:63], v[104:107], v[152:155], v[56:59]
	v_mfma_f32_16x16x32_bf16 v[52:55], v[128:131], v[152:155], v[52:55]
	v_mfma_f32_16x16x32_bf16 v[40:43], v[104:107], v[160:163], v[40:43]
	v_mfma_f32_16x16x32_bf16 v[36:39], v[128:131], v[160:163], v[36:39]
	v_mfma_f32_16x16x32_bf16 v[24:27], v[104:107], v[184:187], v[24:27]
	v_mfma_f32_16x16x32_bf16 v[20:23], v[128:131], v[184:187], v[20:23]
	v_mfma_f32_16x16x32_bf16 v[8:11], v[104:107], v[192:195], v[8:11]
	v_mfma_f32_16x16x32_bf16 v[4:7], v[128:131], v[192:195], v[4:7]
	s_barrier
	s_add_u32 s12, s12, 0x100
	s_addc_u32 s13, s13, 0
	s_add_u32 s20, s20, 0x100
	s_addc_u32 s21, s21, 0
	s_cmp_ge_i32 s45, s9
	s_mov_b32 s22, s45
	s_cbranch_scc0 .LBB0_1087
	s_and_b64 vcc, exec, s[42:43]
	s_cbranch_vccz .LBB0_1090
	s_barrier

; #define PG8_STAGE(bufoff, gbase, voff) do { _Pragma("unroll") for (int _i = 0; _i < 2; ++_i) \
;         __builtin_amdgcn_global_load_lds((const unsigned*)((const char*)(gbase) + (voff)[_i]), (PG8_LAS unsigned*)(lds + (bufoff) + ldsw + _i * 8192), 16, 0, 0); } while (0)
; #define PG8_LDA(dst, b, h) do { _Pragma("unroll") for (int m = 0; m < 4; ++m) _Pragma("unroll") for (int k = 0; k < 2; ++k) dst[m][k] = *(const PG8_LAS bf16x8*)(lds + PG8_SA(b, h) + aoff + m * 2048 + k * 1024); } while (0)
; #define PG8_LDB(dst, b, h) do { _Pragma("unroll") for (int n = 0; n < 2; ++n) _Pragma("unroll") for (int k = 0; k < 2; ++k) dst[n][k] = *(const PG8_LAS bf16x8*)(lds + PG8_SB(b, h) + boff + n * 2048 + k * 1024); } while (0)
; #define PG8_MMA(ai, bj, At, Bt) do { __builtin_amdgcn_s_setprio(1); _Pragma("unroll") for (int m = 0; m < 4; ++m) _Pragma("unroll") for (int n = 0; n < 2; ++n) _Pragma("unroll") for (int k = 0; k < 2; ++k) \
;         acc[ai][bj][m][n] = __builtin_amdgcn_mfma_f32_16x16x32_bf16(Bt[n][k], At[m][k], acc[ai][bj][m][n], 0, 0, 0); __builtin_amdgcn_s_setprio(0); } while (0)
; #define PG8_WAIT_V(n) asm volatile("s_waitcnt vmcnt(" #n ")" ::: "memory")
; #define PG8_WAIT_L(n) asm volatile("s_waitcnt lgkmcnt(" #n ")" ::: "memory")
; template <class Epi, class Sched, bool ALIGN_EPI = true>
; __device__ __forceinline__ void gemm_phase(PG8_LAS unsigned char* lds, const Gemm g, const Sched& S, const Epi& E, const int tid) {
;     ...
;         for (int t = 0; t < nt; t += 2) {
;             const bool last = (t == nt - 2);
;             const char* a1 = cA + (size_t)(t + 1) * kstep;
;             const char* a2 = last ? nA : cA + (size_t)(t + 2) * kstep; const char* b2 = last ? nB : cB + (size_t)(t + 2) * kstep;
;             const char* a3 = a2 + kstep; const char* b3 = b2 + kstep;
;             if (last && has_next) S.a_ready(nxt);
;             PG8_LDB(B0, 0, 0); PG8_LDB(B1, 0, 1); PG8_SCHED; PG8_LDA(At, 0, 0); PG8_STAGE(PG8_SA(1, 1), a1 + hstepA, voffA);
;             PG8_WAIT_V(8); PG8_WAIT_L(0); PG8_BAR; PG8_MMA(0, 0, At, B0); PG8_MMA(0, 1, At, B1); PG8_BAR; PG8_SCHED;
;             PG8_LDA(At, 0, 1); PG8_STAGE(PG8_SB(0, 0), b2, voffB); PG8_STAGE(PG8_SB(0, 1), b2 + hstepB, voffB); PG8_STAGE(PG8_SA(0, 0), a2, voffA);
;             PG8_WAIT_V(8); PG8_WAIT_L(0); PG8_BAR; PG8_MMA(1, 0, At, B0); PG8_MMA(1, 1, At, B1); PG8_BAR; PG8_SCHED;
.LBB0_1238:
	s_add_u32 s15, s74, 0xfff80080
	s_addc_u32 s16, s75, -1
	s_add_i32 s17, 0, 0x10000
	s_cmp_eq_u32 s21, 28
	s_cselect_b32 s79, s8, s16
	s_cselect_b32 s78, s11, s15
	s_cselect_b32 s77, s13, s20
	s_cselect_b32 s76, s18, s19
	s_add_i32 s15, 0, 0x14000
	v_add_u32_e32 v88, s17, v193
	v_add_u32_e32 v104, s15, v193
	ds_read_b128 v[72:75], v88
	ds_read_b128 v[76:79], v88 offset:1024
	ds_read_b128 v[84:87], v88 offset:2048
	ds_read_b128 v[88:91], v88 offset:3072
	ds_read_b128 v[92:95], v104
	ds_read_b128 v[96:99], v104 offset:1024
	ds_read_b128 v[100:103], v104 offset:2048
	ds_read_b128 v[104:107], v104 offset:3072
	v_lshl_add_u64 v[190:191], s[74:75], 0, v[186:187]
	s_add_i32 m0, s86, 0xc000
	ds_read_b128 v[164:167], v200
	ds_read_b128 v[168:171], v200 offset:1024
	ds_read_b128 v[172:175], v200 offset:2048
	ds_read_b128 v[176:179], v200 offset:3072
	ds_read_b128 v[202:205], v200 offset:4096
	ds_read_b128 v[210:213], v200 offset:5120
	ds_read_b128 v[214:217], v200 offset:6144
	ds_read_b128 v[218:221], v200 offset:7168
	global_load_lds_dwordx4 v[190:191], off
	v_lshl_add_u64 v[190:191], s[74:75], 0, v[188:189]
	s_add_i32 m0, s86, 0xe000
	s_nop 0
	global_load_lds_dwordx4 v[190:191], off
	s_waitcnt vmcnt(8)
	s_waitcnt lgkmcnt(0)
	s_barrier
	s_waitcnt lgkmcnt(0)
	v_mfma_f32_16x16x32_bf16 v[160:163], v[72:75], v[164:167], v[160:163]
	v_mfma_f32_16x16x32_bf16 v[156:159], v[84:87], v[164:167], v[156:159]
	v_mfma_f32_16x16x32_bf16 v[144:147], v[72:75], v[172:175], v[144:147]
	v_mfma_f32_16x16x32_bf16 v[140:143], v[84:87], v[172:175], v[140:143]
	v_mfma_f32_16x16x32_bf16 v[128:131], v[72:75], v[202:205], v[128:131]
	v_mfma_f32_16x16x32_bf16 v[124:127], v[84:87], v[202:205], v[124:127]
	v_mfma_f32_16x16x32_bf16 v[80:83], v[72:75], v[214:217], v[80:83]
	v_mfma_f32_16x16x32_bf16 v[68:71], v[84:87], v[214:217], v[68:71]
	v_mfma_f32_16x16x32_bf16 v[160:163], v[76:79], v[168:171], v[160:163]
	v_mfma_f32_16x16x32_bf16 v[156:159], v[88:91], v[168:171], v[156:159]
	v_mfma_f32_16x16x32_bf16 v[144:147], v[76:79], v[176:179], v[144:147]
	v_mfma_f32_16x16x32_bf16 v[140:143], v[88:91], v[176:179], v[140:143]
	v_mfma_f32_16x16x32_bf16 v[128:131], v[76:79], v[210:213], v[128:131]
	v_mfma_f32_16x16x32_bf16 v[124:127], v[88:91], v[210:213], v[124:127]
	v_mfma_f32_16x16x32_bf16 v[80:83], v[76:79], v[218:221], v[80:83]
	v_mfma_f32_16x16x32_bf16 v[68:71], v[88:91], v[218:221], v[68:71]
	v_mfma_f32_16x16x32_bf16 v[152:155], v[92:95], v[164:167], v[152:155]
	v_mfma_f32_16x16x32_bf16 v[148:151], v[100:103], v[164:167], v[148:151]
	v_mfma_f32_16x16x32_bf16 v[136:139], v[92:95], v[172:175], v[136:139]
	v_mfma_f32_16x16x32_bf16 v[132:135], v[100:103], v[172:175], v[132:135]
	v_mfma_f32_16x16x32_bf16 v[120:123], v[92:95], v[202:205], v[120:123]
	v_mfma_f32_16x16x32_bf16 v[116:119], v[100:103], v[202:205], v[116:119]
	v_mfma_f32_16x16x32_bf16 v[112:115], v[92:95], v[214:217], v[112:115]
	v_mfma_f32_16x16x32_bf16 v[108:111], v[100:103], v[214:217], v[108:111]
	v_mfma_f32_16x16x32_bf16 v[152:155], v[96:99], v[168:171], v[152:155]
	v_mfma_f32_16x16x32_bf16 v[148:151], v[104:107], v[168:171], v[148:151]
	v_mfma_f32_16x16x32_bf16 v[136:139], v[96:99], v[176:179], v[136:139]
	v_mfma_f32_16x16x32_bf16 v[132:135], v[104:107], v[176:179], v[132:135]
	v_mfma_f32_16x16x32_bf16 v[120:123], v[96:99], v[210:213], v[120:123]
	v_mfma_f32_16x16x32_bf16 v[116:119], v[104:107], v[210:213], v[116:119]
	v_mfma_f32_16x16x32_bf16 v[112:115], v[96:99], v[218:221], v[112:115]
	v_mfma_f32_16x16x32_bf16 v[108:111], v[104:107], v[218:221], v[108:111]
	s_barrier
	s_add_i32 s16, s17, s85
	v_lshl_add_u64 v[190:191], s[76:77], 0, v[2:3]
	s_mov_b32 m0, s16
	ds_read_b128 v[164:167], v200 offset:16384
	ds_read_b128 v[168:171], v200 offset:17408
	ds_read_b128 v[172:175], v200 offset:18432
	ds_read_b128 v[176:179], v200 offset:19456
	ds_read_b128 v[202:205], v200 offset:20480
	ds_read_b128 v[210:213], v200 offset:21504
	ds_read_b128 v[214:217], v200 offset:22528
	ds_read_b128 v[218:221], v200 offset:23552
	global_load_lds_dwordx4 v[190:191], off
	s_add_i32 m0, s16, 0x2000
	s_add_u32 s96, s76, 0x80000
	v_lshl_add_u64 v[206:207], s[76:77], 0, v[184:185]
	s_addc_u32 s97, s77, 0
	s_add_i32 s15, s15, s85
	global_load_lds_dwordx4 v[206:207], off
	v_lshl_add_u64 v[208:209], s[96:97], 0, v[2:3]
	s_mov_b32 m0, s15
	v_lshl_add_u64 v[222:223], s[78:79], 0, v[182:183]
	global_load_lds_dwordx4 v[208:209], off
	v_lshl_add_u64 v[208:209], s[96:97], 0, v[184:185]
	s_add_i32 m0, s15, 0x2000
	s_nop 0
	global_load_lds_dwordx4 v[208:209], off
	v_lshl_add_u64 v[208:209], s[78:79], 0, v[180:181]
	s_mov_b32 m0, s86
	s_nop 0
	global_load_lds_dwordx4 v[208:209], off
	s_mov_b32 m0, s87
	s_nop 0
	global_load_lds_dwordx4 v[222:223], off
	s_waitcnt vmcnt(8)
	s_waitcnt lgkmcnt(0)
	s_barrier
; #define PG8_STAGE(bufoff, gbase, voff) do { _Pragma("unroll") for (int _i = 0; _i < 2; ++_i) \
;         __builtin_amdgcn_global_load_lds((const unsigned*)((const char*)(gbase) + (voff)[_i]), (PG8_LAS unsigned*)(lds + (bufoff) + ldsw + _i * 8192), 16, 0, 0); } while (0)
; #define PG8_LDA(dst, b, h) do { _Pragma("unroll") for (int m = 0; m < 4; ++m) _Pragma("unroll") for (int k = 0; k < 2; ++k) dst[m][k] = *(const PG8_LAS bf16x8*)(lds + PG8_SA(b, h) + aoff + m * 2048 + k * 1024); } while (0)
; #define PG8_LDB(dst, b, h) do { _Pragma("unroll") for (int n = 0; n < 2; ++n) _Pragma("unroll") for (int k = 0; k < 2; ++k) dst[n][k] = *(const PG8_LAS bf16x8*)(lds + PG8_SB(b, h) + boff + n * 2048 + k * 1024); } while (0)
; #define PG8_MMA(ai, bj, At, Bt) do { __builtin_amdgcn_s_setprio(1); _Pragma("unroll") for (int m = 0; m < 4; ++m) _Pragma("unroll") for (int n = 0; n < 2; ++n) _Pragma("unroll") for (int k = 0; k < 2; ++k) \
;         acc[ai][bj][m][n] = __builtin_amdgcn_mfma_f32_16x16x32_bf16(Bt[n][k], At[m][k], acc[ai][bj][m][n], 0, 0, 0); __builtin_amdgcn_s_setprio(0); } while (0)
; #define PG8_WAIT_V(n) asm volatile("s_waitcnt vmcnt(" #n ")" ::: "memory")
; #define PG8_WAIT_L(n) asm volatile("s_waitcnt lgkmcnt(" #n ")" ::: "memory")
; #define PG8_BAR __builtin_amdgcn_s_barrier()
; #define PG8_SCHED __builtin_amdgcn_sched_barrier(0)
; template <class Epi, class Sched, bool ALIGN_EPI = true>
; __device__ __forceinline__ void gemm_phase(PG8_LAS unsigned char* lds, const Gemm g, const Sched& S, const Epi& E, const int tid) {
;     ...
;             PG8_WAIT_V(8); PG8_WAIT_L(0); PG8_BAR; PG8_MMA(1, 0, At, B0); PG8_MMA(1, 1, At, B1); PG8_BAR; PG8_SCHED;
;             PG8_LDB(B0, 1, 0); PG8_LDB(B1, 1, 1); PG8_SCHED; PG8_LDA(At, 1, 0); PG8_STAGE(PG8_SA(0, 1), a2 + hstepA, voffA);
;             PG8_WAIT_V(8); PG8_WAIT_L(0); PG8_BAR; PG8_MMA(0, 0, At, B0); PG8_MMA(0, 1, At, B1); PG8_BAR; PG8_SCHED;
	s_waitcnt lgkmcnt(0)
	v_mfma_f32_16x16x32_bf16 v[64:67], v[72:75], v[164:167], v[64:67]
	v_mfma_f32_16x16x32_bf16 v[60:63], v[84:87], v[164:167], v[60:63]
	v_mfma_f32_16x16x32_bf16 v[48:51], v[72:75], v[172:175], v[48:51]
	v_mfma_f32_16x16x32_bf16 v[44:47], v[84:87], v[172:175], v[44:47]
	v_mfma_f32_16x16x32_bf16 v[32:35], v[72:75], v[202:205], v[32:35]
	v_mfma_f32_16x16x32_bf16 v[28:31], v[84:87], v[202:205], v[28:31]
	v_mfma_f32_16x16x32_bf16 v[8:11], v[72:75], v[214:217], v[8:11]
	v_mfma_f32_16x16x32_bf16 v[4:7], v[84:87], v[214:217], v[4:7]
	v_mfma_f32_16x16x32_bf16 v[64:67], v[76:79], v[168:171], v[64:67]
	v_mfma_f32_16x16x32_bf16 v[60:63], v[88:91], v[168:171], v[60:63]
	v_mfma_f32_16x16x32_bf16 v[48:51], v[76:79], v[176:179], v[48:51]
	v_mfma_f32_16x16x32_bf16 v[44:47], v[88:91], v[176:179], v[44:47]
	v_mfma_f32_16x16x32_bf16 v[32:35], v[76:79], v[210:213], v[32:35]
	v_mfma_f32_16x16x32_bf16 v[28:31], v[88:91], v[210:213], v[28:31]
	v_mfma_f32_16x16x32_bf16 v[8:11], v[76:79], v[218:221], v[8:11]
	v_mfma_f32_16x16x32_bf16 v[4:7], v[88:91], v[218:221], v[4:7]
	v_mfma_f32_16x16x32_bf16 v[56:59], v[92:95], v[164:167], v[56:59]
	v_mfma_f32_16x16x32_bf16 v[52:55], v[100:103], v[164:167], v[52:55]
	v_mfma_f32_16x16x32_bf16 v[40:43], v[92:95], v[172:175], v[40:43]
	v_mfma_f32_16x16x32_bf16 v[36:39], v[100:103], v[172:175], v[36:39]
	v_mfma_f32_16x16x32_bf16 v[24:27], v[92:95], v[202:205], v[24:27]
	v_mfma_f32_16x16x32_bf16 v[20:23], v[100:103], v[202:205], v[20:23]
	v_mfma_f32_16x16x32_bf16 v[16:19], v[92:95], v[214:217], v[16:19]
	v_mfma_f32_16x16x32_bf16 v[12:15], v[100:103], v[214:217], v[12:15]
	v_mfma_f32_16x16x32_bf16 v[56:59], v[96:99], v[168:171], v[56:59]
	v_mfma_f32_16x16x32_bf16 v[52:55], v[104:107], v[168:171], v[52:55]
	v_mfma_f32_16x16x32_bf16 v[40:43], v[96:99], v[176:179], v[40:43]
	v_mfma_f32_16x16x32_bf16 v[36:39], v[104:107], v[176:179], v[36:39]
	v_mfma_f32_16x16x32_bf16 v[24:27], v[96:99], v[210:213], v[24:27]
	v_mfma_f32_16x16x32_bf16 v[20:23], v[104:107], v[210:213], v[20:23]
	v_mfma_f32_16x16x32_bf16 v[16:19], v[96:99], v[218:221], v[16:19]
	v_mfma_f32_16x16x32_bf16 v[12:15], v[104:107], v[218:221], v[12:15]
	s_barrier
	s_add_i32 s15, 0, 0x18000
	s_add_i32 s16, 0, 0x1c000
	v_add_u32_e32 v88, s15, v193
	v_add_u32_e32 v104, s16, v193
	ds_read_b128 v[72:75], v88
	ds_read_b128 v[76:79], v88 offset:1024
	ds_read_b128 v[84:87], v88 offset:2048
	ds_read_b128 v[88:91], v88 offset:3072
	ds_read_b128 v[92:95], v104
	ds_read_b128 v[96:99], v104 offset:1024
	ds_read_b128 v[100:103], v104 offset:2048
	ds_read_b128 v[104:107], v104 offset:3072
	s_add_u32 s78, s78, 0x80000
	s_addc_u32 s79, s79, 0
	s_mov_b32 m0, s88
	v_lshl_add_u64 v[224:225], s[78:79], 0, v[180:181]
	ds_read_b128 v[164:167], v200 offset:32768
	ds_read_b128 v[168:171], v200 offset:33792
	ds_read_b128 v[172:175], v200 offset:34816
	ds_read_b128 v[176:179], v200 offset:35840
	ds_read_b128 v[202:205], v200 offset:36864
	ds_read_b128 v[210:213], v200 offset:37888
	ds_read_b128 v[214:217], v200 offset:38912
	ds_read_b128 v[218:221], v200 offset:39936
	global_load_lds_dwordx4 v[224:225], off
	v_lshl_add_u64 v[224:225], s[78:79], 0, v[182:183]
	s_mov_b32 m0, s89
	s_nop 0
	global_load_lds_dwordx4 v[224:225], off
	s_waitcnt vmcnt(8)
	s_waitcnt lgkmcnt(0)
	s_barrier
	s_waitcnt lgkmcnt(0)
	v_mfma_f32_16x16x32_bf16 v[160:163], v[72:75], v[164:167], v[160:163]
	v_mfma_f32_16x16x32_bf16 v[156:159], v[84:87], v[164:167], v[156:159]
	v_mfma_f32_16x16x32_bf16 v[144:147], v[72:75], v[172:175], v[144:147]
	v_mfma_f32_16x16x32_bf16 v[140:143], v[84:87], v[172:175], v[140:143]
	v_mfma_f32_16x16x32_bf16 v[128:131], v[72:75], v[202:205], v[128:131]
	v_mfma_f32_16x16x32_bf16 v[124:127], v[84:87], v[202:205], v[124:127]
	v_mfma_f32_16x16x32_bf16 v[80:83], v[72:75], v[214:217], v[80:83]
	v_mfma_f32_16x16x32_bf16 v[68:71], v[84:87], v[214:217], v[68:71]
	v_mfma_f32_16x16x32_bf16 v[160:163], v[76:79], v[168:171], v[160:163]
	v_mfma_f32_16x16x32_bf16 v[156:159], v[88:91], v[168:171], v[156:159]
	v_mfma_f32_16x16x32_bf16 v[144:147], v[76:79], v[176:179], v[144:147]
	v_mfma_f32_16x16x32_bf16 v[140:143], v[88:91], v[176:179], v[140:143]
	v_mfma_f32_16x16x32_bf16 v[128:131], v[76:79], v[210:213], v[128:131]
	v_mfma_f32_16x16x32_bf16 v[124:127], v[88:91], v[210:213], v[124:127]
	v_mfma_f32_16x16x32_bf16 v[80:83], v[76:79], v[218:221], v[80:83]
	v_mfma_f32_16x16x32_bf16 v[68:71], v[88:91], v[218:221], v[68:71]
	v_mfma_f32_16x16x32_bf16 v[152:155], v[92:95], v[164:167], v[152:155]
	v_mfma_f32_16x16x32_bf16 v[148:151], v[100:103], v[164:167], v[148:151]
	v_mfma_f32_16x16x32_bf16 v[136:139], v[92:95], v[172:175], v[136:139]
	v_mfma_f32_16x16x32_bf16 v[132:135], v[100:103], v[172:175], v[132:135]
	v_mfma_f32_16x16x32_bf16 v[120:123], v[92:95], v[202:205], v[120:123]
	v_mfma_f32_16x16x32_bf16 v[116:119], v[100:103], v[202:205], v[116:119]
	v_mfma_f32_16x16x32_bf16 v[112:115], v[92:95], v[214:217], v[112:115]
	v_mfma_f32_16x16x32_bf16 v[108:111], v[100:103], v[214:217], v[108:111]
	v_mfma_f32_16x16x32_bf16 v[152:155], v[96:99], v[168:171], v[152:155]
	v_mfma_f32_16x16x32_bf16 v[148:151], v[104:107], v[168:171], v[148:151]
	v_mfma_f32_16x16x32_bf16 v[136:139], v[96:99], v[176:179], v[136:139]
	v_mfma_f32_16x16x32_bf16 v[132:135], v[104:107], v[176:179], v[132:135]
	v_mfma_f32_16x16x32_bf16 v[120:123], v[96:99], v[210:213], v[120:123]
	v_mfma_f32_16x16x32_bf16 v[116:119], v[104:107], v[210:213], v[116:119]
	v_mfma_f32_16x16x32_bf16 v[112:115], v[96:99], v[218:221], v[112:115]
	v_mfma_f32_16x16x32_bf16 v[108:111], v[104:107], v[218:221], v[108:111]
	s_barrier
; #define PG8_LAS __attribute__((address_space(3)))
; #define PG8_STAGE(bufoff, gbase, voff) do { _Pragma("unroll") for (int _i = 0; _i < 2; ++_i) \
;         __builtin_amdgcn_global_load_lds((const unsigned*)((const char*)(gbase) + (voff)[_i]), (PG8_LAS unsigned*)(lds + (bufoff) + ldsw + _i * 8192), 16, 0, 0); } while (0)
; #define PG8_LDA(dst, b, h) do { _Pragma("unroll") for (int m = 0; m < 4; ++m) _Pragma("unroll") for (int k = 0; k < 2; ++k) dst[m][k] = *(const PG8_LAS bf16x8*)(lds + PG8_SA(b, h) + aoff + m * 2048 + k * 1024); } while (0)
; #define PG8_MMA(ai, bj, At, Bt) do { __builtin_amdgcn_s_setprio(1); _Pragma("unroll") for (int m = 0; m < 4; ++m) _Pragma("unroll") for (int n = 0; n < 2; ++n) _Pragma("unroll") for (int k = 0; k < 2; ++k) \
;         acc[ai][bj][m][n] = __builtin_amdgcn_mfma_f32_16x16x32_bf16(Bt[n][k], At[m][k], acc[ai][bj][m][n], 0, 0, 0); __builtin_amdgcn_s_setprio(0); } while (0)
; #define PG8_WAIT_V(n) asm volatile("s_waitcnt vmcnt(" #n ")" ::: "memory")
; #define PG8_WAIT_L(n) asm volatile("s_waitcnt lgkmcnt(" #n ")" ::: "memory")
; #define PG8_BAR __builtin_amdgcn_s_barrier()
; #define PG8_SCHED __builtin_amdgcn_sched_barrier(0)
;     __device__ __forceinline__ void operator()(const f32x4 (&acc)[2][2][4][2], const Unit& u, int wr, int wc, int fr, int fq) const {
;     ...
;             if (fr == 0)  { *(PG8_LAS f32x4*)(xme + (ai * 2 + 0) * 32) = acc[ai][1][0][0]; *(PG8_LAS f32x4*)(xme + (ai * 2 + 0) * 32 + 4) = acc[ai][1][0][1]; }
; template <class Epi, class Sched, bool ALIGN_EPI = true>
; __device__ __forceinline__ void gemm_phase(PG8_LAS unsigned char* lds, const Gemm g, const Sched& S, const Epi& E, const int tid) {
;     ...
;             PG8_LDA(At, 1, 1); PG8_STAGE(PG8_SB(1, 0), b3, voffB); PG8_STAGE(PG8_SB(1, 1), b3 + hstepB, voffB); PG8_STAGE(PG8_SA(1, 0), a3, voffA);
;             PG8_WAIT_V(8); PG8_WAIT_L(0); PG8_BAR; PG8_MMA(1, 0, At, B0); PG8_MMA(1, 1, At, B1); PG8_BAR; PG8_SCHED;
;         }
;         if constexpr (ALIGN_EPI) { if (wr == 0) PG8_BAR; }
	s_add_i32 s15, s15, s85
	v_lshl_add_u64 v[190:191], v[190:191], 0, s[36:37]
	s_mov_b32 m0, s15
	ds_read_b128 v[164:167], v200 offset:49152
	ds_read_b128 v[168:171], v200 offset:50176
	ds_read_b128 v[172:175], v200 offset:51200
	ds_read_b128 v[176:179], v200 offset:52224
	ds_read_b128 v[202:205], v200 offset:53248
	ds_read_b128 v[210:213], v200 offset:54272
	ds_read_b128 v[214:217], v200 offset:55296
	ds_read_b128 v[218:221], v200 offset:56320
	global_load_lds_dwordx4 v[190:191], off
	s_add_i32 m0, s15, 0x2000
	s_add_u32 s76, s76, 0x80080
	v_lshl_add_u64 v[190:191], v[206:207], 0, s[36:37]
	s_addc_u32 s77, s77, 0
	s_add_i32 s15, s16, s85
	global_load_lds_dwordx4 v[190:191], off
	v_lshl_add_u64 v[190:191], s[76:77], 0, v[2:3]
	s_mov_b32 m0, s15
	s_nop 0
	global_load_lds_dwordx4 v[190:191], off
	v_lshl_add_u64 v[190:191], s[76:77], 0, v[184:185]
	s_add_i32 m0, s15, 0x2000
	s_nop 0
	global_load_lds_dwordx4 v[190:191], off
	v_lshl_add_u64 v[190:191], v[208:209], 0, s[36:37]
	s_mov_b32 m0, s92
	s_nop 0
	global_load_lds_dwordx4 v[190:191], off
	v_lshl_add_u64 v[190:191], v[222:223], 0, s[36:37]
	s_mov_b32 m0, s93
	s_nop 0
	global_load_lds_dwordx4 v[190:191], off
	s_waitcnt vmcnt(8)
	s_waitcnt lgkmcnt(0)
	s_barrier
	s_waitcnt lgkmcnt(0)
	v_mfma_f32_16x16x32_bf16 v[64:67], v[72:75], v[164:167], v[64:67]
	v_mfma_f32_16x16x32_bf16 v[60:63], v[84:87], v[164:167], v[60:63]
	v_mfma_f32_16x16x32_bf16 v[48:51], v[72:75], v[172:175], v[48:51]
	v_mfma_f32_16x16x32_bf16 v[44:47], v[84:87], v[172:175], v[44:47]
	v_mfma_f32_16x16x32_bf16 v[32:35], v[72:75], v[202:205], v[32:35]
	v_mfma_f32_16x16x32_bf16 v[28:31], v[84:87], v[202:205], v[28:31]
	v_mfma_f32_16x16x32_bf16 v[8:11], v[72:75], v[214:217], v[8:11]
	v_mfma_f32_16x16x32_bf16 v[4:7], v[84:87], v[214:217], v[4:7]
	v_mfma_f32_16x16x32_bf16 v[64:67], v[76:79], v[168:171], v[64:67]
	v_mfma_f32_16x16x32_bf16 v[60:63], v[88:91], v[168:171], v[60:63]
	v_mfma_f32_16x16x32_bf16 v[48:51], v[76:79], v[176:179], v[48:51]
	v_mfma_f32_16x16x32_bf16 v[44:47], v[88:91], v[176:179], v[44:47]
	v_mfma_f32_16x16x32_bf16 v[32:35], v[76:79], v[210:213], v[32:35]
	v_mfma_f32_16x16x32_bf16 v[28:31], v[88:91], v[210:213], v[28:31]
	v_mfma_f32_16x16x32_bf16 v[8:11], v[76:79], v[218:221], v[8:11]
	v_mfma_f32_16x16x32_bf16 v[4:7], v[88:91], v[218:221], v[4:7]
	v_mfma_f32_16x16x32_bf16 v[56:59], v[92:95], v[164:167], v[56:59]
	v_mfma_f32_16x16x32_bf16 v[52:55], v[100:103], v[164:167], v[52:55]
	v_mfma_f32_16x16x32_bf16 v[40:43], v[92:95], v[172:175], v[40:43]
	v_mfma_f32_16x16x32_bf16 v[36:39], v[100:103], v[172:175], v[36:39]
	v_mfma_f32_16x16x32_bf16 v[24:27], v[92:95], v[202:205], v[24:27]
	v_mfma_f32_16x16x32_bf16 v[20:23], v[100:103], v[202:205], v[20:23]
	v_mfma_f32_16x16x32_bf16 v[16:19], v[92:95], v[214:217], v[16:19]
	v_mfma_f32_16x16x32_bf16 v[12:15], v[100:103], v[214:217], v[12:15]
	v_mfma_f32_16x16x32_bf16 v[56:59], v[96:99], v[168:171], v[56:59]
	v_mfma_f32_16x16x32_bf16 v[52:55], v[104:107], v[168:171], v[52:55]
	v_mfma_f32_16x16x32_bf16 v[40:43], v[96:99], v[176:179], v[40:43]
	v_mfma_f32_16x16x32_bf16 v[36:39], v[104:107], v[176:179], v[36:39]
	v_mfma_f32_16x16x32_bf16 v[24:27], v[96:99], v[210:213], v[24:27]
	v_mfma_f32_16x16x32_bf16 v[20:23], v[104:107], v[210:213], v[20:23]
	v_mfma_f32_16x16x32_bf16 v[16:19], v[96:99], v[218:221], v[16:19]
	v_mfma_f32_16x16x32_bf16 v[12:15], v[104:107], v[218:221], v[12:15]
	s_barrier
	s_add_i32 s21, s21, 2
	s_add_u32 s74, s74, 0x100
	s_addc_u32 s75, s75, 0
	s_add_u32 s19, s19, 0x100
	s_addc_u32 s20, s20, 0
	s_cmp_gt_u32 s21, 29
	s_cbranch_scc0 .LBB0_1238
	s_and_b64 vcc, exec, s[56:57]
	s_cbranch_vccnz .LBB0_1264
	s_and_saveexec_b64 s[18:19], s[38:39]
	s_cbranch_execnz .LBB0_1265

; #define PG8_STAGE(bufoff, gbase, voff) do { _Pragma("unroll") for (int _i = 0; _i < 2; ++_i) \
;         __builtin_amdgcn_global_load_lds((const unsigned*)((const char*)(gbase) + (voff)[_i]), (PG8_LAS unsigned*)(lds + (bufoff) + ldsw + _i * 8192), 16, 0, 0); } while (0)
; #define PG8_LDA(dst, b, h) do { _Pragma("unroll") for (int m = 0; m < 4; ++m) _Pragma("unroll") for (int k = 0; k < 2; ++k) dst[m][k] = *(const PG8_LAS bf16x8*)(lds + PG8_SA(b, h) + aoff + m * 2048 + k * 1024); } while (0)
; #define PG8_LDB(dst, b, h) do { _Pragma("unroll") for (int n = 0; n < 2; ++n) _Pragma("unroll") for (int k = 0; k < 2; ++k) dst[n][k] = *(const PG8_LAS bf16x8*)(lds + PG8_SB(b, h) + boff + n * 2048 + k * 1024); } while (0)
; #define PG8_MMA(ai, bj, At, Bt) do { __builtin_amdgcn_s_setprio(1); _Pragma("unroll") for (int m = 0; m < 4; ++m) _Pragma("unroll") for (int n = 0; n < 2; ++n) _Pragma("unroll") for (int k = 0; k < 2; ++k) \
;         acc[ai][bj][m][n] = __builtin_amdgcn_mfma_f32_16x16x32_bf16(Bt[n][k], At[m][k], acc[ai][bj][m][n], 0, 0, 0); __builtin_amdgcn_s_setprio(0); } while (0)
; #define PG8_WAIT_V(n) asm volatile("s_waitcnt vmcnt(" #n ")" ::: "memory")
; #define PG8_WAIT_L(n) asm volatile("s_waitcnt lgkmcnt(" #n ")" ::: "memory")
; template <class Epi, class Sched, bool ALIGN_EPI = true>
; __device__ __forceinline__ void gemm_phase(PG8_LAS unsigned char* lds, const Gemm g, const Sched& S, const Epi& E, const int tid) {
;     ...
;         for (int t = 0; t < nt; t += 2) {
;             const bool last = (t == nt - 2);
;             const char* a1 = cA + (size_t)(t + 1) * kstep;
;             const char* a2 = last ? nA : cA + (size_t)(t + 2) * kstep; const char* b2 = last ? nB : cB + (size_t)(t + 2) * kstep;
;             const char* a3 = a2 + kstep; const char* b3 = b2 + kstep;
;             if (last && has_next) S.a_ready(nxt);
;             PG8_LDB(B0, 0, 0); PG8_LDB(B1, 0, 1); PG8_SCHED; PG8_LDA(At, 0, 0); PG8_STAGE(PG8_SA(1, 1), a1 + hstepA, voffA);
;             PG8_WAIT_V(8); PG8_WAIT_L(0); PG8_BAR; PG8_MMA(0, 0, At, B0); PG8_MMA(0, 1, At, B1); PG8_BAR; PG8_SCHED;
;             PG8_LDA(At, 0, 1); PG8_STAGE(PG8_SB(0, 0), b2, voffB); PG8_STAGE(PG8_SB(0, 1), b2 + hstepB, voffB); PG8_STAGE(PG8_SA(0, 0), a2, voffA);
;             PG8_WAIT_V(8); PG8_WAIT_L(0); PG8_BAR; PG8_MMA(1, 0, At, B0); PG8_MMA(1, 1, At, B1); PG8_BAR; PG8_SCHED;
.LBB0_1414:
	s_add_i32 s70, s12, 2
	s_add_u32 s10, s0, 0x100
	s_addc_u32 s11, s1, 0
	s_add_i32 s15, 0, 0x10000
	s_cmp_eq_u32 s45, s12
	s_cselect_b32 s23, s47, s11
	s_cselect_b32 s22, s46, s10
	s_cselect_b32 s13, s49, s69
	s_cselect_b32 s12, s48, s68
	s_add_i32 s16, 0, 0x14000
	v_add_u32_e32 v72, s15, v251
	v_add_u32_e32 v128, s16, v251
	ds_read_b128 v[56:59], v72
	ds_read_b128 v[60:63], v72 offset:1024
	ds_read_b128 v[68:71], v72 offset:2048
	ds_read_b128 v[72:75], v72 offset:3072
	ds_read_b128 v[92:95], v128
	ds_read_b128 v[104:107], v128 offset:1024
	ds_read_b128 v[116:119], v128 offset:2048
	ds_read_b128 v[128:131], v128 offset:3072
	v_lshl_add_u64 v[196:197], s[0:1], 0, v[216:217]
	s_add_i32 m0, s52, 0xc000
	ds_read_b128 v[140:143], v252
	ds_read_b128 v[152:155], v252 offset:1024
	ds_read_b128 v[156:159], v252 offset:2048
	ds_read_b128 v[160:163], v252 offset:3072
	ds_read_b128 v[172:175], v252 offset:4096
	ds_read_b128 v[184:187], v252 offset:5120
	ds_read_b128 v[188:191], v252 offset:6144
	ds_read_b128 v[192:195], v252 offset:7168
	global_load_lds_dwordx4 v[196:197], off
	v_lshl_add_u64 v[196:197], s[0:1], 0, v[218:219]
	s_add_i32 m0, s52, 0xe000
	s_nop 0
	global_load_lds_dwordx4 v[196:197], off
	s_waitcnt vmcnt(8)
	s_waitcnt lgkmcnt(0)
	s_barrier
	s_waitcnt lgkmcnt(0)
	v_mfma_f32_16x16x32_bf16 v[180:183], v[56:59], v[140:143], v[180:183]
	v_mfma_f32_16x16x32_bf16 v[176:179], v[68:71], v[140:143], v[176:179]
	v_mfma_f32_16x16x32_bf16 v[148:151], v[56:59], v[156:159], v[148:151]
	v_mfma_f32_16x16x32_bf16 v[144:147], v[68:71], v[156:159], v[144:147]
	v_mfma_f32_16x16x32_bf16 v[124:127], v[56:59], v[172:175], v[124:127]
	v_mfma_f32_16x16x32_bf16 v[120:123], v[68:71], v[172:175], v[120:123]
	v_mfma_f32_16x16x32_bf16 v[100:103], v[56:59], v[188:191], v[100:103]
	v_mfma_f32_16x16x32_bf16 v[96:99], v[68:71], v[188:191], v[96:99]
	v_mfma_f32_16x16x32_bf16 v[180:183], v[60:63], v[152:155], v[180:183]
	v_mfma_f32_16x16x32_bf16 v[176:179], v[72:75], v[152:155], v[176:179]
	v_mfma_f32_16x16x32_bf16 v[148:151], v[60:63], v[160:163], v[148:151]
	v_mfma_f32_16x16x32_bf16 v[144:147], v[72:75], v[160:163], v[144:147]
	v_mfma_f32_16x16x32_bf16 v[124:127], v[60:63], v[184:187], v[124:127]
	v_mfma_f32_16x16x32_bf16 v[120:123], v[72:75], v[184:187], v[120:123]
	v_mfma_f32_16x16x32_bf16 v[100:103], v[60:63], v[192:195], v[100:103]
	v_mfma_f32_16x16x32_bf16 v[96:99], v[72:75], v[192:195], v[96:99]
	v_mfma_f32_16x16x32_bf16 v[168:171], v[92:95], v[140:143], v[168:171]
	v_mfma_f32_16x16x32_bf16 v[136:139], v[92:95], v[156:159], v[136:139]
	v_mfma_f32_16x16x32_bf16 v[132:135], v[116:119], v[156:159], v[132:135]
	v_mfma_f32_16x16x32_bf16 v[112:115], v[92:95], v[172:175], v[112:115]
	v_mfma_f32_16x16x32_bf16 v[108:111], v[116:119], v[172:175], v[108:111]
	v_mfma_f32_16x16x32_bf16 v[88:91], v[92:95], v[188:191], v[88:91]
	v_mfma_f32_16x16x32_bf16 v[84:87], v[116:119], v[188:191], v[84:87]
	v_mfma_f32_16x16x32_bf16 v[168:171], v[104:107], v[152:155], v[168:171]
	v_mfma_f32_16x16x32_bf16 v[140:143], v[116:119], v[140:143], v[164:167]
	v_mfma_f32_16x16x32_bf16 v[136:139], v[104:107], v[160:163], v[136:139]
	v_mfma_f32_16x16x32_bf16 v[132:135], v[128:131], v[160:163], v[132:135]
	v_mfma_f32_16x16x32_bf16 v[112:115], v[104:107], v[184:187], v[112:115]
	v_mfma_f32_16x16x32_bf16 v[108:111], v[128:131], v[184:187], v[108:111]
	v_mfma_f32_16x16x32_bf16 v[88:91], v[104:107], v[192:195], v[88:91]
	v_mfma_f32_16x16x32_bf16 v[84:87], v[128:131], v[192:195], v[84:87]
	v_mfma_f32_16x16x32_bf16 v[140:143], v[128:131], v[152:155], v[140:143]
	s_barrier
	s_add_i32 s0, s15, s51
	v_lshl_add_u64 v[200:201], s[12:13], 0, v[2:3]
	s_mov_b32 m0, s0
	ds_read_b128 v[152:155], v252 offset:16384
	ds_read_b128 v[156:159], v252 offset:17408
	ds_read_b128 v[160:163], v252 offset:18432
	ds_read_b128 v[164:167], v252 offset:19456
	ds_read_b128 v[172:175], v252 offset:20480
	ds_read_b128 v[184:187], v252 offset:21504
	ds_read_b128 v[188:191], v252 offset:22528
	ds_read_b128 v[192:195], v252 offset:23552
	global_load_lds_dwordx4 v[200:201], off
	s_add_i32 m0, s0, 0x2000
	s_add_u32 s0, s12, 0x168000
	v_lshl_add_u64 v[202:203], s[12:13], 0, v[214:215]
	s_addc_u32 s1, s13, 0
	s_add_i32 s15, s16, s51
	global_load_lds_dwordx4 v[202:203], off
	v_lshl_add_u64 v[196:197], s[0:1], 0, v[2:3]
	s_mov_b32 m0, s15
	v_lshl_add_u64 v[204:205], s[22:23], 0, v[210:211]
	global_load_lds_dwordx4 v[196:197], off
	v_lshl_add_u64 v[196:197], s[0:1], 0, v[214:215]
	s_add_i32 m0, s15, 0x2000
	v_lshl_add_u64 v[206:207], s[22:23], 0, v[212:213]
	global_load_lds_dwordx4 v[196:197], off
	s_mov_b32 m0, s52
	s_nop 0
	global_load_lds_dwordx4 v[204:205], off
	s_mov_b32 m0, s53
	s_nop 0
	global_load_lds_dwordx4 v[206:207], off
	s_waitcnt vmcnt(8)
	s_waitcnt lgkmcnt(0)
	s_barrier
; #define PG8_STAGE(bufoff, gbase, voff) do { _Pragma("unroll") for (int _i = 0; _i < 2; ++_i) \
;         __builtin_amdgcn_global_load_lds((const unsigned*)((const char*)(gbase) + (voff)[_i]), (PG8_LAS unsigned*)(lds + (bufoff) + ldsw + _i * 8192), 16, 0, 0); } while (0)
; #define PG8_LDA(dst, b, h) do { _Pragma("unroll") for (int m = 0; m < 4; ++m) _Pragma("unroll") for (int k = 0; k < 2; ++k) dst[m][k] = *(const PG8_LAS bf16x8*)(lds + PG8_SA(b, h) + aoff + m * 2048 + k * 1024); } while (0)
; #define PG8_LDB(dst, b, h) do { _Pragma("unroll") for (int n = 0; n < 2; ++n) _Pragma("unroll") for (int k = 0; k < 2; ++k) dst[n][k] = *(const PG8_LAS bf16x8*)(lds + PG8_SB(b, h) + boff + n * 2048 + k * 1024); } while (0)
; #define PG8_MMA(ai, bj, At, Bt) do { __builtin_amdgcn_s_setprio(1); _Pragma("unroll") for (int m = 0; m < 4; ++m) _Pragma("unroll") for (int n = 0; n < 2; ++n) _Pragma("unroll") for (int k = 0; k < 2; ++k) \
;         acc[ai][bj][m][n] = __builtin_amdgcn_mfma_f32_16x16x32_bf16(Bt[n][k], At[m][k], acc[ai][bj][m][n], 0, 0, 0); __builtin_amdgcn_s_setprio(0); } while (0)
; #define PG8_WAIT_V(n) asm volatile("s_waitcnt vmcnt(" #n ")" ::: "memory")
; #define PG8_WAIT_L(n) asm volatile("s_waitcnt lgkmcnt(" #n ")" ::: "memory")
; #define PG8_BAR __builtin_amdgcn_s_barrier()
; #define PG8_SCHED __builtin_amdgcn_sched_barrier(0)
; template <class Epi, class Sched, bool ALIGN_EPI = true>
; __device__ __forceinline__ void gemm_phase(PG8_LAS unsigned char* lds, const Gemm g, const Sched& S, const Epi& E, const int tid) {
;     ...
;             PG8_WAIT_V(8); PG8_WAIT_L(0); PG8_BAR; PG8_MMA(1, 0, At, B0); PG8_MMA(1, 1, At, B1); PG8_BAR; PG8_SCHED;
;             PG8_LDB(B0, 1, 0); PG8_LDB(B1, 1, 1); PG8_SCHED; PG8_LDA(At, 1, 0); PG8_STAGE(PG8_SA(0, 1), a2 + hstepA, voffA);
;             PG8_WAIT_V(8); PG8_WAIT_L(0); PG8_BAR; PG8_MMA(0, 0, At, B0); PG8_MMA(0, 1, At, B1); PG8_BAR; PG8_SCHED;
	s_waitcnt lgkmcnt(0)
	v_mfma_f32_16x16x32_bf16 v[80:83], v[56:59], v[152:155], v[80:83]
	v_mfma_f32_16x16x32_bf16 v[76:79], v[68:71], v[152:155], v[76:79]
	v_mfma_f32_16x16x32_bf16 v[48:51], v[56:59], v[160:163], v[48:51]
	v_mfma_f32_16x16x32_bf16 v[44:47], v[68:71], v[160:163], v[44:47]
	v_mfma_f32_16x16x32_bf16 v[32:35], v[56:59], v[172:175], v[32:35]
	v_mfma_f32_16x16x32_bf16 v[28:31], v[68:71], v[172:175], v[28:31]
	v_mfma_f32_16x16x32_bf16 v[16:19], v[56:59], v[188:191], v[16:19]
	v_mfma_f32_16x16x32_bf16 v[12:15], v[68:71], v[188:191], v[12:15]
	v_mfma_f32_16x16x32_bf16 v[80:83], v[60:63], v[156:159], v[80:83]
	v_mfma_f32_16x16x32_bf16 v[76:79], v[72:75], v[156:159], v[76:79]
	v_mfma_f32_16x16x32_bf16 v[48:51], v[60:63], v[164:167], v[48:51]
	v_mfma_f32_16x16x32_bf16 v[44:47], v[72:75], v[164:167], v[44:47]
	v_mfma_f32_16x16x32_bf16 v[32:35], v[60:63], v[184:187], v[32:35]
	v_mfma_f32_16x16x32_bf16 v[28:31], v[72:75], v[184:187], v[28:31]
	v_mfma_f32_16x16x32_bf16 v[16:19], v[60:63], v[192:195], v[16:19]
	v_mfma_f32_16x16x32_bf16 v[12:15], v[72:75], v[192:195], v[12:15]
	v_mfma_f32_16x16x32_bf16 v[52:55], v[116:119], v[152:155], v[52:55]
	v_mfma_f32_16x16x32_bf16 v[40:43], v[92:95], v[160:163], v[40:43]
	v_mfma_f32_16x16x32_bf16 v[36:39], v[116:119], v[160:163], v[36:39]
	v_mfma_f32_16x16x32_bf16 v[24:27], v[92:95], v[172:175], v[24:27]
	v_mfma_f32_16x16x32_bf16 v[20:23], v[116:119], v[172:175], v[20:23]
	v_mfma_f32_16x16x32_bf16 v[8:11], v[92:95], v[188:191], v[8:11]
	v_mfma_f32_16x16x32_bf16 v[4:7], v[116:119], v[188:191], v[4:7]
	v_mfma_f32_16x16x32_bf16 v[56:59], v[92:95], v[152:155], v[64:67]
	v_mfma_f32_16x16x32_bf16 v[52:55], v[128:131], v[156:159], v[52:55]
	v_mfma_f32_16x16x32_bf16 v[40:43], v[104:107], v[164:167], v[40:43]
	v_mfma_f32_16x16x32_bf16 v[36:39], v[128:131], v[164:167], v[36:39]
	v_mfma_f32_16x16x32_bf16 v[24:27], v[104:107], v[184:187], v[24:27]
	v_mfma_f32_16x16x32_bf16 v[20:23], v[128:131], v[184:187], v[20:23]
	v_mfma_f32_16x16x32_bf16 v[8:11], v[104:107], v[192:195], v[8:11]
	v_mfma_f32_16x16x32_bf16 v[4:7], v[128:131], v[192:195], v[4:7]
	v_mfma_f32_16x16x32_bf16 v[56:59], v[104:107], v[156:159], v[56:59]
	s_barrier
	s_add_i32 s15, 0, 0x18000
	s_add_i32 s16, 0, 0x1c000
	v_add_u32_e32 v72, s15, v251
	v_add_u32_e32 v128, s16, v251
	ds_read_b128 v[60:63], v72
	ds_read_b128 v[64:67], v72 offset:1024
	ds_read_b128 v[68:71], v72 offset:2048
	ds_read_b128 v[72:75], v72 offset:3072
	ds_read_b128 v[92:95], v128
	ds_read_b128 v[104:107], v128 offset:1024
	ds_read_b128 v[116:119], v128 offset:2048
	ds_read_b128 v[128:131], v128 offset:3072
	s_add_u32 s0, s22, 0x168000
	s_addc_u32 s1, s23, 0
	s_mov_b32 m0, s54
	v_lshl_add_u64 v[164:165], s[0:1], 0, v[210:211]
	ds_read_b128 v[152:155], v252 offset:32768
	ds_read_b128 v[156:159], v252 offset:33792
	ds_read_b128 v[160:163], v252 offset:34816
	ds_read_b128 v[172:175], v252 offset:35840
	ds_read_b128 v[184:187], v252 offset:36864
	ds_read_b128 v[188:191], v252 offset:37888
	ds_read_b128 v[192:195], v252 offset:38912
	ds_read_b128 v[196:199], v252 offset:39936
	global_load_lds_dwordx4 v[164:165], off
	v_lshl_add_u64 v[164:165], s[0:1], 0, v[212:213]
	s_mov_b32 m0, s55
	s_nop 0
	global_load_lds_dwordx4 v[164:165], off
	s_waitcnt vmcnt(8)
	s_waitcnt lgkmcnt(0)
	s_barrier
	s_waitcnt lgkmcnt(0)
	v_mfma_f32_16x16x32_bf16 v[164:167], v[60:63], v[152:155], v[180:183]
	v_mfma_f32_16x16x32_bf16 v[180:183], v[64:67], v[156:159], v[164:167]
	v_mfma_f32_16x16x32_bf16 v[164:167], v[68:71], v[152:155], v[176:179]
	v_mfma_f32_16x16x32_bf16 v[148:151], v[60:63], v[160:163], v[148:151]
	v_mfma_f32_16x16x32_bf16 v[144:147], v[68:71], v[160:163], v[144:147]
	v_mfma_f32_16x16x32_bf16 v[124:127], v[60:63], v[184:187], v[124:127]
	v_mfma_f32_16x16x32_bf16 v[120:123], v[68:71], v[184:187], v[120:123]
	v_mfma_f32_16x16x32_bf16 v[100:103], v[60:63], v[192:195], v[100:103]
	v_mfma_f32_16x16x32_bf16 v[96:99], v[68:71], v[192:195], v[96:99]
	v_mfma_f32_16x16x32_bf16 v[176:179], v[72:75], v[156:159], v[164:167]
	v_mfma_f32_16x16x32_bf16 v[148:151], v[64:67], v[172:175], v[148:151]
	v_mfma_f32_16x16x32_bf16 v[144:147], v[72:75], v[172:175], v[144:147]
	v_mfma_f32_16x16x32_bf16 v[124:127], v[64:67], v[188:191], v[124:127]
	v_mfma_f32_16x16x32_bf16 v[120:123], v[72:75], v[188:191], v[120:123]
	v_mfma_f32_16x16x32_bf16 v[100:103], v[64:67], v[196:199], v[100:103]
	v_mfma_f32_16x16x32_bf16 v[96:99], v[72:75], v[196:199], v[96:99]
	v_mfma_f32_16x16x32_bf16 v[164:167], v[92:95], v[152:155], v[168:171]
	v_mfma_f32_16x16x32_bf16 v[140:143], v[116:119], v[152:155], v[140:143]
	v_mfma_f32_16x16x32_bf16 v[136:139], v[92:95], v[160:163], v[136:139]
	v_mfma_f32_16x16x32_bf16 v[132:135], v[116:119], v[160:163], v[132:135]
	v_mfma_f32_16x16x32_bf16 v[112:115], v[92:95], v[184:187], v[112:115]
	v_mfma_f32_16x16x32_bf16 v[108:111], v[116:119], v[184:187], v[108:111]
	v_mfma_f32_16x16x32_bf16 v[88:91], v[92:95], v[192:195], v[88:91]
	v_mfma_f32_16x16x32_bf16 v[84:87], v[116:119], v[192:195], v[84:87]
	v_mfma_f32_16x16x32_bf16 v[168:171], v[104:107], v[156:159], v[164:167]
	v_mfma_f32_16x16x32_bf16 v[164:167], v[128:131], v[156:159], v[140:143]
	v_mfma_f32_16x16x32_bf16 v[136:139], v[104:107], v[172:175], v[136:139]
	v_mfma_f32_16x16x32_bf16 v[132:135], v[128:131], v[172:175], v[132:135]
	v_mfma_f32_16x16x32_bf16 v[112:115], v[104:107], v[188:191], v[112:115]
	v_mfma_f32_16x16x32_bf16 v[108:111], v[128:131], v[188:191], v[108:111]
	v_mfma_f32_16x16x32_bf16 v[88:91], v[104:107], v[196:199], v[88:91]
	v_mfma_f32_16x16x32_bf16 v[84:87], v[128:131], v[196:199], v[84:87]
	s_barrier
; #define PG8_STAGE(bufoff, gbase, voff) do { _Pragma("unroll") for (int _i = 0; _i < 2; ++_i) \
;         __builtin_amdgcn_global_load_lds((const unsigned*)((const char*)(gbase) + (voff)[_i]), (PG8_LAS unsigned*)(lds + (bufoff) + ldsw + _i * 8192), 16, 0, 0); } while (0)
; #define PG8_LDA(dst, b, h) do { _Pragma("unroll") for (int m = 0; m < 4; ++m) _Pragma("unroll") for (int k = 0; k < 2; ++k) dst[m][k] = *(const PG8_LAS bf16x8*)(lds + PG8_SA(b, h) + aoff + m * 2048 + k * 1024); } while (0)
; #define PG8_MMA(ai, bj, At, Bt) do { __builtin_amdgcn_s_setprio(1); _Pragma("unroll") for (int m = 0; m < 4; ++m) _Pragma("unroll") for (int n = 0; n < 2; ++n) _Pragma("unroll") for (int k = 0; k < 2; ++k) \
;         acc[ai][bj][m][n] = __builtin_amdgcn_mfma_f32_16x16x32_bf16(Bt[n][k], At[m][k], acc[ai][bj][m][n], 0, 0, 0); __builtin_amdgcn_s_setprio(0); } while (0)
; #define PG8_WAIT_V(n) asm volatile("s_waitcnt vmcnt(" #n ")" ::: "memory")
; #define PG8_WAIT_L(n) asm volatile("s_waitcnt lgkmcnt(" #n ")" ::: "memory")
; #define PG8_BAR __builtin_amdgcn_s_barrier()
; #define PG8_SCHED __builtin_amdgcn_sched_barrier(0)
; template <class Epi, class Sched, bool ALIGN_EPI = true>
; __device__ __forceinline__ void gemm_phase(PG8_LAS unsigned char* lds, const Gemm g, const Sched& S, const Epi& E, const int tid) {
;     ...
;             PG8_LDA(At, 1, 1); PG8_STAGE(PG8_SB(1, 0), b3, voffB); PG8_STAGE(PG8_SB(1, 1), b3 + hstepB, voffB); PG8_STAGE(PG8_SA(1, 0), a3, voffA);
;             PG8_WAIT_V(8); PG8_WAIT_L(0); PG8_BAR; PG8_MMA(1, 0, At, B0); PG8_MMA(1, 1, At, B1); PG8_BAR; PG8_SCHED;
;         }
;         if constexpr (ALIGN_EPI) { if (wr == 0) PG8_BAR; }
	s_add_i32 s0, s15, s51
	v_lshl_add_u64 v[196:197], v[200:201], 0, s[36:37]
	s_mov_b32 m0, s0
	ds_read_b128 v[140:143], v252 offset:49152
	ds_read_b128 v[152:155], v252 offset:50176
	ds_read_b128 v[156:159], v252 offset:51200
	ds_read_b128 v[160:163], v252 offset:52224
	ds_read_b128 v[172:175], v252 offset:53248
	ds_read_b128 v[184:187], v252 offset:54272
	ds_read_b128 v[188:191], v252 offset:55296
	ds_read_b128 v[192:195], v252 offset:56320
	global_load_lds_dwordx4 v[196:197], off
	s_add_i32 m0, s0, 0x2000
	s_add_u32 s0, s12, 0x168080
	v_lshl_add_u64 v[196:197], v[202:203], 0, s[36:37]
	s_addc_u32 s1, s13, 0
	s_add_i32 s12, s16, s51
	global_load_lds_dwordx4 v[196:197], off
	v_lshl_add_u64 v[196:197], s[0:1], 0, v[2:3]
	s_mov_b32 m0, s12
	s_nop 0
	global_load_lds_dwordx4 v[196:197], off
	v_lshl_add_u64 v[196:197], s[0:1], 0, v[214:215]
	s_add_i32 m0, s12, 0x2000
	s_nop 0
	global_load_lds_dwordx4 v[196:197], off
	v_lshl_add_u64 v[196:197], v[204:205], 0, s[36:37]
	s_mov_b32 m0, s58
	s_nop 0
	global_load_lds_dwordx4 v[196:197], off
	v_lshl_add_u64 v[196:197], v[206:207], 0, s[36:37]
	s_mov_b32 m0, s59
	s_nop 0
	global_load_lds_dwordx4 v[196:197], off
	s_waitcnt vmcnt(8)
	s_waitcnt lgkmcnt(0)
	s_barrier
	s_waitcnt lgkmcnt(0)
	v_mfma_f32_16x16x32_bf16 v[80:83], v[60:63], v[140:143], v[80:83]
	v_mfma_f32_16x16x32_bf16 v[76:79], v[68:71], v[140:143], v[76:79]
	v_mfma_f32_16x16x32_bf16 v[48:51], v[60:63], v[156:159], v[48:51]
	v_mfma_f32_16x16x32_bf16 v[44:47], v[68:71], v[156:159], v[44:47]
	v_mfma_f32_16x16x32_bf16 v[32:35], v[60:63], v[172:175], v[32:35]
	v_mfma_f32_16x16x32_bf16 v[28:31], v[68:71], v[172:175], v[28:31]
	v_mfma_f32_16x16x32_bf16 v[16:19], v[60:63], v[188:191], v[16:19]
	v_mfma_f32_16x16x32_bf16 v[12:15], v[68:71], v[188:191], v[12:15]
	v_mfma_f32_16x16x32_bf16 v[80:83], v[64:67], v[152:155], v[80:83]
	v_mfma_f32_16x16x32_bf16 v[76:79], v[72:75], v[152:155], v[76:79]
	v_mfma_f32_16x16x32_bf16 v[48:51], v[64:67], v[160:163], v[48:51]
	v_mfma_f32_16x16x32_bf16 v[44:47], v[72:75], v[160:163], v[44:47]
	v_mfma_f32_16x16x32_bf16 v[32:35], v[64:67], v[184:187], v[32:35]
	v_mfma_f32_16x16x32_bf16 v[28:31], v[72:75], v[184:187], v[28:31]
	v_mfma_f32_16x16x32_bf16 v[16:19], v[64:67], v[192:195], v[16:19]
	v_mfma_f32_16x16x32_bf16 v[12:15], v[72:75], v[192:195], v[12:15]
	v_mfma_f32_16x16x32_bf16 v[56:59], v[92:95], v[140:143], v[56:59]
	v_mfma_f32_16x16x32_bf16 v[52:55], v[116:119], v[140:143], v[52:55]
	v_mfma_f32_16x16x32_bf16 v[40:43], v[92:95], v[156:159], v[40:43]
	v_mfma_f32_16x16x32_bf16 v[36:39], v[116:119], v[156:159], v[36:39]
	v_mfma_f32_16x16x32_bf16 v[24:27], v[92:95], v[172:175], v[24:27]
	v_mfma_f32_16x16x32_bf16 v[20:23], v[116:119], v[172:175], v[20:23]
	v_mfma_f32_16x16x32_bf16 v[8:11], v[92:95], v[188:191], v[8:11]
	v_mfma_f32_16x16x32_bf16 v[4:7], v[116:119], v[188:191], v[4:7]
	v_mfma_f32_16x16x32_bf16 v[64:67], v[104:107], v[152:155], v[56:59]
	v_mfma_f32_16x16x32_bf16 v[52:55], v[128:131], v[152:155], v[52:55]
	v_mfma_f32_16x16x32_bf16 v[40:43], v[104:107], v[160:163], v[40:43]
	v_mfma_f32_16x16x32_bf16 v[36:39], v[128:131], v[160:163], v[36:39]
	v_mfma_f32_16x16x32_bf16 v[24:27], v[104:107], v[184:187], v[24:27]
	v_mfma_f32_16x16x32_bf16 v[20:23], v[128:131], v[184:187], v[20:23]
	v_mfma_f32_16x16x32_bf16 v[8:11], v[104:107], v[192:195], v[8:11]
	v_mfma_f32_16x16x32_bf16 v[4:7], v[128:131], v[192:195], v[4:7]
	s_barrier
	s_add_u32 s68, s68, 0x100
	s_addc_u32 s69, s69, 0
	s_cmp_ge_i32 s70, s67
	s_mov_b64 s[0:1], s[10:11]
	s_mov_b32 s12, s70
	s_cbranch_scc0 .LBB0_1414
	s_and_b64 vcc, exec, s[42:43]
	s_cbranch_vccz .LBB0_1417
	s_barrier
